# GEMM epilogues at wave priority 2 (K loops: 3 reads / 1 MFMA / 0 barrier)
# speedup vs baseline: 1.0192x; 1.0039x over previous
.Lfin3_loop:
	s_setprio 3
	v_add_u32_e32 v234, s22, v232
	v_add_u32_e32 v236, s28, v232
	v_add_u32_e32 v235, s22, v233
	v_add_u32_e32 v237, s28, v233
	ds_read_b128 v[136:139], v234
	ds_read_b128 v[188:191], v236
	ds_read_b128 v[196:199], v236 offset:2048
	ds_read_b128 v[200:203], v236 offset:4096
	ds_read_b128 v[204:207], v236 offset:6144
	ds_read_b128 v[140:143], v234 offset:2048
	ds_read_b128 v[144:147], v234 offset:4096
	ds_read_b128 v[148:151], v234 offset:6144
	ds_read_b128 v[172:175], v235
	ds_read_b128 v[212:215], v237
	ds_read_b128 v[216:219], v237 offset:2048
	ds_read_b128 v[220:223], v237 offset:4096
	ds_read_b128 v[224:227], v237 offset:6144
	ds_read_b128 v[176:179], v235 offset:2048
	ds_read_b128 v[180:183], v235 offset:4096
	ds_read_b128 v[184:187], v235 offset:6144
	s_add_i32 m0, s51, 0xc000
	s_nop 0
	global_load_lds_dwordx4 v228, s[44:45]
	s_add_i32 m0, s51, 0xc400
	s_nop 0
	global_load_lds_dwordx4 v230, s[44:45]
	s_add_i32 m0, s51, 0xe000
	s_nop 0
	global_load_lds_dwordx4 v229, s[44:45]
	s_add_i32 m0, s51, 0xe400
	s_nop 0
	global_load_lds_dwordx4 v231, s[44:45]
	s_add_i32 m0, s51, 0x10000
	s_nop 0
	global_load_lds_dwordx4 v228, s[46:47]
	s_add_i32 m0, s51, 0x10400
	s_nop 0
	global_load_lds_dwordx4 v230, s[46:47]
	s_waitcnt lgkmcnt(11)
	s_setprio 1
	v_mfma_f32_16x16x32_bf16 v[2:5], v[136:139], v[188:191], v[2:5]
	v_mfma_f32_16x16x32_bf16 v[6:9], v[136:139], v[196:199], v[6:9]
	v_mfma_f32_16x16x32_bf16 v[10:13], v[136:139], v[200:203], v[10:13]
	v_mfma_f32_16x16x32_bf16 v[14:17], v[136:139], v[204:207], v[14:17]
	s_waitcnt lgkmcnt(10)
	v_mfma_f32_16x16x32_bf16 v[18:21], v[140:143], v[188:191], v[18:21]
	v_mfma_f32_16x16x32_bf16 v[22:25], v[140:143], v[196:199], v[22:25]
	v_mfma_f32_16x16x32_bf16 v[26:29], v[140:143], v[200:203], v[26:29]
	v_mfma_f32_16x16x32_bf16 v[30:33], v[140:143], v[204:207], v[30:33]
	s_waitcnt lgkmcnt(9)
	v_mfma_f32_16x16x32_bf16 v[34:37], v[144:147], v[188:191], v[34:37]
	v_mfma_f32_16x16x32_bf16 v[38:41], v[144:147], v[196:199], v[38:41]
	v_mfma_f32_16x16x32_bf16 v[42:45], v[144:147], v[200:203], v[42:45]
	v_mfma_f32_16x16x32_bf16 v[46:49], v[144:147], v[204:207], v[46:49]
	s_waitcnt lgkmcnt(8)
	v_mfma_f32_16x16x32_bf16 v[50:53], v[148:151], v[188:191], v[50:53]
	v_mfma_f32_16x16x32_bf16 v[54:57], v[148:151], v[196:199], v[54:57]
	v_mfma_f32_16x16x32_bf16 v[58:61], v[148:151], v[200:203], v[58:61]
	v_mfma_f32_16x16x32_bf16 v[62:65], v[148:151], v[204:207], v[62:65]
	s_waitcnt lgkmcnt(3)
	v_mfma_f32_16x16x32_bf16 v[2:5], v[172:175], v[212:215], v[2:5]
	v_mfma_f32_16x16x32_bf16 v[6:9], v[172:175], v[216:219], v[6:9]
	v_mfma_f32_16x16x32_bf16 v[10:13], v[172:175], v[220:223], v[10:13]
	v_mfma_f32_16x16x32_bf16 v[14:17], v[172:175], v[224:227], v[14:17]
	s_waitcnt lgkmcnt(2)
	v_mfma_f32_16x16x32_bf16 v[18:21], v[176:179], v[212:215], v[18:21]
	v_mfma_f32_16x16x32_bf16 v[22:25], v[176:179], v[216:219], v[22:25]
	v_mfma_f32_16x16x32_bf16 v[26:29], v[176:179], v[220:223], v[26:29]
	v_mfma_f32_16x16x32_bf16 v[30:33], v[176:179], v[224:227], v[30:33]
	s_waitcnt lgkmcnt(1)
	v_mfma_f32_16x16x32_bf16 v[34:37], v[180:183], v[212:215], v[34:37]
	v_mfma_f32_16x16x32_bf16 v[38:41], v[180:183], v[216:219], v[38:41]
	v_mfma_f32_16x16x32_bf16 v[42:45], v[180:183], v[220:223], v[42:45]
	v_mfma_f32_16x16x32_bf16 v[46:49], v[180:183], v[224:227], v[46:49]
	s_waitcnt lgkmcnt(0)
	v_mfma_f32_16x16x32_bf16 v[50:53], v[184:187], v[212:215], v[50:53]
	v_mfma_f32_16x16x32_bf16 v[54:57], v[184:187], v[216:219], v[54:57]
	v_mfma_f32_16x16x32_bf16 v[58:61], v[184:187], v[220:223], v[58:61]
	v_mfma_f32_16x16x32_bf16 v[62:65], v[184:187], v[224:227], v[62:65]
	s_setprio 0
	s_waitcnt vmcnt(6)
	s_barrier
	s_setprio 3
	v_add_u32_e32 v236, s40, v232
	v_add_u32_e32 v237, s40, v233
	ds_read_b128 v[188:191], v236
	ds_read_b128 v[196:199], v236 offset:2048
	ds_read_b128 v[200:203], v236 offset:4096
	ds_read_b128 v[204:207], v236 offset:6144
	ds_read_b128 v[212:215], v237
	ds_read_b128 v[216:219], v237 offset:2048
	ds_read_b128 v[220:223], v237 offset:4096
	ds_read_b128 v[224:227], v237 offset:6144
	s_mov_b32 m0, s51
	s_nop 0
	global_load_lds_dwordx4 v229, s[46:47]
	s_add_i32 m0, s51, 0x400
	s_nop 0
	global_load_lds_dwordx4 v231, s[46:47]
	s_add_i32 m0, s51, 0x2000
	s_nop 0
	global_load_lds_dwordx4 v228, s[48:49]
	s_add_i32 m0, s51, 0x2400
	s_nop 0
	global_load_lds_dwordx4 v230, s[48:49]
	s_add_i32 m0, s51, 0x4000
	s_nop 0
	global_load_lds_dwordx4 v229, s[48:49]
	s_add_i32 m0, s51, 0x4400
	s_nop 0
	global_load_lds_dwordx4 v231, s[48:49]
	s_waitcnt lgkmcnt(7)
	s_setprio 1
	v_mfma_f32_16x16x32_bf16 v[66:69], v[136:139], v[188:191], v[66:69]
	v_mfma_f32_16x16x32_bf16 v[82:85], v[140:143], v[188:191], v[82:85]
	v_mfma_f32_16x16x32_bf16 v[98:101], v[144:147], v[188:191], v[98:101]
	v_mfma_f32_16x16x32_bf16 v[114:117], v[148:151], v[188:191], v[114:117]
	s_waitcnt lgkmcnt(6)
	v_mfma_f32_16x16x32_bf16 v[70:73], v[136:139], v[196:199], v[70:73]
	v_mfma_f32_16x16x32_bf16 v[86:89], v[140:143], v[196:199], v[86:89]
	v_mfma_f32_16x16x32_bf16 v[102:105], v[144:147], v[196:199], v[102:105]
	v_mfma_f32_16x16x32_bf16 v[118:121], v[148:151], v[196:199], v[118:121]
	s_waitcnt lgkmcnt(5)
	v_mfma_f32_16x16x32_bf16 v[74:77], v[136:139], v[200:203], v[74:77]
	v_mfma_f32_16x16x32_bf16 v[90:93], v[140:143], v[200:203], v[90:93]
	v_mfma_f32_16x16x32_bf16 v[106:109], v[144:147], v[200:203], v[106:109]
	v_mfma_f32_16x16x32_bf16 v[122:125], v[148:151], v[200:203], v[122:125]
	s_waitcnt lgkmcnt(4)
	v_mfma_f32_16x16x32_bf16 v[78:81], v[136:139], v[204:207], v[78:81]
	v_mfma_f32_16x16x32_bf16 v[94:97], v[140:143], v[204:207], v[94:97]
	v_mfma_f32_16x16x32_bf16 v[110:113], v[144:147], v[204:207], v[110:113]
	v_mfma_f32_16x16x32_bf16 v[126:129], v[148:151], v[204:207], v[126:129]
	s_waitcnt lgkmcnt(3)
	v_mfma_f32_16x16x32_bf16 v[66:69], v[172:175], v[212:215], v[66:69]
	v_mfma_f32_16x16x32_bf16 v[82:85], v[176:179], v[212:215], v[82:85]
	v_mfma_f32_16x16x32_bf16 v[98:101], v[180:183], v[212:215], v[98:101]
	v_mfma_f32_16x16x32_bf16 v[114:117], v[184:187], v[212:215], v[114:117]
	s_waitcnt lgkmcnt(2)
	v_mfma_f32_16x16x32_bf16 v[70:73], v[172:175], v[216:219], v[70:73]
	v_mfma_f32_16x16x32_bf16 v[86:89], v[176:179], v[216:219], v[86:89]
	v_mfma_f32_16x16x32_bf16 v[102:105], v[180:183], v[216:219], v[102:105]
	v_mfma_f32_16x16x32_bf16 v[118:121], v[184:187], v[216:219], v[118:121]
	s_waitcnt lgkmcnt(1)
	v_mfma_f32_16x16x32_bf16 v[74:77], v[172:175], v[220:223], v[74:77]
	v_mfma_f32_16x16x32_bf16 v[90:93], v[176:179], v[220:223], v[90:93]
	v_mfma_f32_16x16x32_bf16 v[106:109], v[180:183], v[220:223], v[106:109]
	v_mfma_f32_16x16x32_bf16 v[122:125], v[184:187], v[220:223], v[122:125]
	s_waitcnt lgkmcnt(0)
	v_mfma_f32_16x16x32_bf16 v[78:81], v[172:175], v[224:227], v[78:81]
	v_mfma_f32_16x16x32_bf16 v[94:97], v[176:179], v[224:227], v[94:97]
	v_mfma_f32_16x16x32_bf16 v[110:113], v[180:183], v[224:227], v[110:113]
	v_mfma_f32_16x16x32_bf16 v[126:129], v[184:187], v[224:227], v[126:129]
	s_setprio 0
	v_add_u32_e32 v228, 0x80, v228
	v_add_u32_e32 v229, 0x80, v229
	v_add_u32_e32 v230, 0x80, v230
	v_add_u32_e32 v231, 0x80, v231
	s_waitcnt vmcnt(4)
	s_barrier
	s_setprio 3
	v_add_u32_e32 v234, s23, v232
	v_add_u32_e32 v236, s29, v232
	v_add_u32_e32 v235, s23, v233
	v_add_u32_e32 v237, s29, v233
	ds_read_b128 v[136:139], v234
	ds_read_b128 v[188:191], v236
	ds_read_b128 v[196:199], v236 offset:2048
	ds_read_b128 v[200:203], v236 offset:4096
	ds_read_b128 v[204:207], v236 offset:6144
	ds_read_b128 v[140:143], v234 offset:2048
	ds_read_b128 v[144:147], v234 offset:4096
	ds_read_b128 v[148:151], v234 offset:6144
	ds_read_b128 v[172:175], v235
	ds_read_b128 v[212:215], v237
	ds_read_b128 v[216:219], v237 offset:2048
	ds_read_b128 v[220:223], v237 offset:4096
	ds_read_b128 v[224:227], v237 offset:6144
	ds_read_b128 v[176:179], v235 offset:2048
	ds_read_b128 v[180:183], v235 offset:4096
	ds_read_b128 v[184:187], v235 offset:6144
	s_add_i32 m0, s51, 0x6000
	s_nop 0
	global_load_lds_dwordx4 v228, s[44:45]
	s_add_i32 m0, s51, 0x6400
	s_nop 0
	global_load_lds_dwordx4 v230, s[44:45]
	s_add_i32 m0, s51, 0x8000
	s_nop 0
	global_load_lds_dwordx4 v229, s[44:45]
	s_add_i32 m0, s51, 0x8400
	s_nop 0
	global_load_lds_dwordx4 v231, s[44:45]
	s_add_i32 m0, s51, 0xa000
	s_nop 0
	global_load_lds_dwordx4 v228, s[46:47]
	s_add_i32 m0, s51, 0xa400
	s_nop 0
	global_load_lds_dwordx4 v230, s[46:47]
	s_waitcnt lgkmcnt(11)
	s_setprio 1
	v_mfma_f32_16x16x32_bf16 v[2:5], v[136:139], v[188:191], v[2:5]
	v_mfma_f32_16x16x32_bf16 v[6:9], v[136:139], v[196:199], v[6:9]
	v_mfma_f32_16x16x32_bf16 v[10:13], v[136:139], v[200:203], v[10:13]
	v_mfma_f32_16x16x32_bf16 v[14:17], v[136:139], v[204:207], v[14:17]
	s_waitcnt lgkmcnt(10)
	v_mfma_f32_16x16x32_bf16 v[18:21], v[140:143], v[188:191], v[18:21]
	v_mfma_f32_16x16x32_bf16 v[22:25], v[140:143], v[196:199], v[22:25]
	v_mfma_f32_16x16x32_bf16 v[26:29], v[140:143], v[200:203], v[26:29]
	v_mfma_f32_16x16x32_bf16 v[30:33], v[140:143], v[204:207], v[30:33]
	s_waitcnt lgkmcnt(9)
	v_mfma_f32_16x16x32_bf16 v[34:37], v[144:147], v[188:191], v[34:37]
	v_mfma_f32_16x16x32_bf16 v[38:41], v[144:147], v[196:199], v[38:41]
	v_mfma_f32_16x16x32_bf16 v[42:45], v[144:147], v[200:203], v[42:45]
	v_mfma_f32_16x16x32_bf16 v[46:49], v[144:147], v[204:207], v[46:49]
	s_waitcnt lgkmcnt(8)
	v_mfma_f32_16x16x32_bf16 v[50:53], v[148:151], v[188:191], v[50:53]
	v_mfma_f32_16x16x32_bf16 v[54:57], v[148:151], v[196:199], v[54:57]
	v_mfma_f32_16x16x32_bf16 v[58:61], v[148:151], v[200:203], v[58:61]
	v_mfma_f32_16x16x32_bf16 v[62:65], v[148:151], v[204:207], v[62:65]
	s_waitcnt lgkmcnt(3)
	v_mfma_f32_16x16x32_bf16 v[2:5], v[172:175], v[212:215], v[2:5]
	v_mfma_f32_16x16x32_bf16 v[6:9], v[172:175], v[216:219], v[6:9]
	v_mfma_f32_16x16x32_bf16 v[10:13], v[172:175], v[220:223], v[10:13]
	v_mfma_f32_16x16x32_bf16 v[14:17], v[172:175], v[224:227], v[14:17]
	s_waitcnt lgkmcnt(2)
	v_mfma_f32_16x16x32_bf16 v[18:21], v[176:179], v[212:215], v[18:21]
	v_mfma_f32_16x16x32_bf16 v[22:25], v[176:179], v[216:219], v[22:25]
	v_mfma_f32_16x16x32_bf16 v[26:29], v[176:179], v[220:223], v[26:29]
	v_mfma_f32_16x16x32_bf16 v[30:33], v[176:179], v[224:227], v[30:33]
	s_waitcnt lgkmcnt(1)
	v_mfma_f32_16x16x32_bf16 v[34:37], v[180:183], v[212:215], v[34:37]
	v_mfma_f32_16x16x32_bf16 v[38:41], v[180:183], v[216:219], v[38:41]
	v_mfma_f32_16x16x32_bf16 v[42:45], v[180:183], v[220:223], v[42:45]
	v_mfma_f32_16x16x32_bf16 v[46:49], v[180:183], v[224:227], v[46:49]
	s_waitcnt lgkmcnt(0)
	v_mfma_f32_16x16x32_bf16 v[50:53], v[184:187], v[212:215], v[50:53]
	v_mfma_f32_16x16x32_bf16 v[54:57], v[184:187], v[216:219], v[54:57]
	v_mfma_f32_16x16x32_bf16 v[58:61], v[184:187], v[220:223], v[58:61]
	v_mfma_f32_16x16x32_bf16 v[62:65], v[184:187], v[224:227], v[62:65]
	s_setprio 0
	s_waitcnt vmcnt(6)
	s_barrier
	s_setprio 3
	v_add_u32_e32 v236, s41, v232
	v_add_u32_e32 v237, s41, v233
	ds_read_b128 v[188:191], v236
	ds_read_b128 v[196:199], v236 offset:2048
	ds_read_b128 v[200:203], v236 offset:4096
	ds_read_b128 v[204:207], v236 offset:6144
	ds_read_b128 v[212:215], v237
	ds_read_b128 v[216:219], v237 offset:2048
	ds_read_b128 v[220:223], v237 offset:4096
	ds_read_b128 v[224:227], v237 offset:6144
	s_add_i32 m0, s51, 0xc000
	s_nop 0
	global_load_lds_dwordx4 v229, s[46:47]
	s_add_i32 m0, s51, 0xc400
	s_nop 0
	global_load_lds_dwordx4 v231, s[46:47]
	s_add_i32 m0, s51, 0xe000
	s_nop 0
	global_load_lds_dwordx4 v228, s[48:49]
	s_add_i32 m0, s51, 0xe400
	s_nop 0
	global_load_lds_dwordx4 v230, s[48:49]
	s_add_i32 m0, s51, 0x10000
	s_nop 0
	global_load_lds_dwordx4 v229, s[48:49]
	s_add_i32 m0, s51, 0x10400
	s_nop 0
	global_load_lds_dwordx4 v231, s[48:49]
	s_waitcnt lgkmcnt(7)
	s_setprio 1
	v_mfma_f32_16x16x32_bf16 v[66:69], v[136:139], v[188:191], v[66:69]
	v_mfma_f32_16x16x32_bf16 v[82:85], v[140:143], v[188:191], v[82:85]
	v_mfma_f32_16x16x32_bf16 v[98:101], v[144:147], v[188:191], v[98:101]
	v_mfma_f32_16x16x32_bf16 v[114:117], v[148:151], v[188:191], v[114:117]
	s_waitcnt lgkmcnt(6)
	v_mfma_f32_16x16x32_bf16 v[70:73], v[136:139], v[196:199], v[70:73]
	v_mfma_f32_16x16x32_bf16 v[86:89], v[140:143], v[196:199], v[86:89]
	v_mfma_f32_16x16x32_bf16 v[102:105], v[144:147], v[196:199], v[102:105]
	v_mfma_f32_16x16x32_bf16 v[118:121], v[148:151], v[196:199], v[118:121]
	s_waitcnt lgkmcnt(5)
	v_mfma_f32_16x16x32_bf16 v[74:77], v[136:139], v[200:203], v[74:77]
	v_mfma_f32_16x16x32_bf16 v[90:93], v[140:143], v[200:203], v[90:93]
	v_mfma_f32_16x16x32_bf16 v[106:109], v[144:147], v[200:203], v[106:109]
	v_mfma_f32_16x16x32_bf16 v[122:125], v[148:151], v[200:203], v[122:125]
	s_waitcnt lgkmcnt(4)
	v_mfma_f32_16x16x32_bf16 v[78:81], v[136:139], v[204:207], v[78:81]
	v_mfma_f32_16x16x32_bf16 v[94:97], v[140:143], v[204:207], v[94:97]
	v_mfma_f32_16x16x32_bf16 v[110:113], v[144:147], v[204:207], v[110:113]
	v_mfma_f32_16x16x32_bf16 v[126:129], v[148:151], v[204:207], v[126:129]
	s_waitcnt lgkmcnt(3)
	v_mfma_f32_16x16x32_bf16 v[66:69], v[172:175], v[212:215], v[66:69]
	v_mfma_f32_16x16x32_bf16 v[82:85], v[176:179], v[212:215], v[82:85]
	v_mfma_f32_16x16x32_bf16 v[98:101], v[180:183], v[212:215], v[98:101]
	v_mfma_f32_16x16x32_bf16 v[114:117], v[184:187], v[212:215], v[114:117]
	s_waitcnt lgkmcnt(2)
	v_mfma_f32_16x16x32_bf16 v[70:73], v[172:175], v[216:219], v[70:73]
	v_mfma_f32_16x16x32_bf16 v[86:89], v[176:179], v[216:219], v[86:89]
	v_mfma_f32_16x16x32_bf16 v[102:105], v[180:183], v[216:219], v[102:105]
	v_mfma_f32_16x16x32_bf16 v[118:121], v[184:187], v[216:219], v[118:121]
	s_waitcnt lgkmcnt(1)
	v_mfma_f32_16x16x32_bf16 v[74:77], v[172:175], v[220:223], v[74:77]
	v_mfma_f32_16x16x32_bf16 v[90:93], v[176:179], v[220:223], v[90:93]
	v_mfma_f32_16x16x32_bf16 v[106:109], v[180:183], v[220:223], v[106:109]
	v_mfma_f32_16x16x32_bf16 v[122:125], v[184:187], v[220:223], v[122:125]
	s_waitcnt lgkmcnt(0)
	v_mfma_f32_16x16x32_bf16 v[78:81], v[172:175], v[224:227], v[78:81]
	v_mfma_f32_16x16x32_bf16 v[94:97], v[176:179], v[224:227], v[94:97]
	v_mfma_f32_16x16x32_bf16 v[110:113], v[180:183], v[224:227], v[110:113]
	v_mfma_f32_16x16x32_bf16 v[126:129], v[184:187], v[224:227], v[126:129]
	s_setprio 0
	v_add_u32_e32 v228, 0x80, v228
	v_add_u32_e32 v229, 0x80, v229
	v_add_u32_e32 v230, 0x80, v230
	v_add_u32_e32 v231, 0x80, v231
	s_waitcnt vmcnt(4)
	s_barrier
	s_setprio 3
	v_add_u32_e32 v234, s24, v232
	v_add_u32_e32 v236, s30, v232
	v_add_u32_e32 v235, s24, v233
	v_add_u32_e32 v237, s30, v233
	ds_read_b128 v[136:139], v234
	ds_read_b128 v[188:191], v236
	ds_read_b128 v[196:199], v236 offset:2048
	ds_read_b128 v[200:203], v236 offset:4096
	ds_read_b128 v[204:207], v236 offset:6144
	ds_read_b128 v[140:143], v234 offset:2048
	ds_read_b128 v[144:147], v234 offset:4096
	ds_read_b128 v[148:151], v234 offset:6144
	ds_read_b128 v[172:175], v235
	ds_read_b128 v[212:215], v237
	ds_read_b128 v[216:219], v237 offset:2048
	ds_read_b128 v[220:223], v237 offset:4096
	ds_read_b128 v[224:227], v237 offset:6144
	ds_read_b128 v[176:179], v235 offset:2048
	ds_read_b128 v[180:183], v235 offset:4096
	ds_read_b128 v[184:187], v235 offset:6144
	s_mov_b32 m0, s51
	s_nop 0
	global_load_lds_dwordx4 v228, s[44:45]
	s_add_i32 m0, s51, 0x400
	s_nop 0
	global_load_lds_dwordx4 v230, s[44:45]
	s_add_i32 m0, s51, 0x2000
	s_nop 0
	global_load_lds_dwordx4 v229, s[44:45]
	s_add_i32 m0, s51, 0x2400
	s_nop 0
	global_load_lds_dwordx4 v231, s[44:45]
	s_add_i32 m0, s51, 0x4000
	s_nop 0
	global_load_lds_dwordx4 v228, s[46:47]
	s_add_i32 m0, s51, 0x4400
	s_nop 0
	global_load_lds_dwordx4 v230, s[46:47]
	s_waitcnt lgkmcnt(11)
	s_setprio 1
	v_mfma_f32_16x16x32_bf16 v[2:5], v[136:139], v[188:191], v[2:5]
	v_mfma_f32_16x16x32_bf16 v[6:9], v[136:139], v[196:199], v[6:9]
	v_mfma_f32_16x16x32_bf16 v[10:13], v[136:139], v[200:203], v[10:13]
	v_mfma_f32_16x16x32_bf16 v[14:17], v[136:139], v[204:207], v[14:17]
	s_waitcnt lgkmcnt(10)
	v_mfma_f32_16x16x32_bf16 v[18:21], v[140:143], v[188:191], v[18:21]
	v_mfma_f32_16x16x32_bf16 v[22:25], v[140:143], v[196:199], v[22:25]
	v_mfma_f32_16x16x32_bf16 v[26:29], v[140:143], v[200:203], v[26:29]
	v_mfma_f32_16x16x32_bf16 v[30:33], v[140:143], v[204:207], v[30:33]
	s_waitcnt lgkmcnt(9)
	v_mfma_f32_16x16x32_bf16 v[34:37], v[144:147], v[188:191], v[34:37]
	v_mfma_f32_16x16x32_bf16 v[38:41], v[144:147], v[196:199], v[38:41]
	v_mfma_f32_16x16x32_bf16 v[42:45], v[144:147], v[200:203], v[42:45]
	v_mfma_f32_16x16x32_bf16 v[46:49], v[144:147], v[204:207], v[46:49]
	s_waitcnt lgkmcnt(8)
	v_mfma_f32_16x16x32_bf16 v[50:53], v[148:151], v[188:191], v[50:53]
	v_mfma_f32_16x16x32_bf16 v[54:57], v[148:151], v[196:199], v[54:57]
	v_mfma_f32_16x16x32_bf16 v[58:61], v[148:151], v[200:203], v[58:61]
	v_mfma_f32_16x16x32_bf16 v[62:65], v[148:151], v[204:207], v[62:65]
	s_waitcnt lgkmcnt(3)
	v_mfma_f32_16x16x32_bf16 v[2:5], v[172:175], v[212:215], v[2:5]
	v_mfma_f32_16x16x32_bf16 v[6:9], v[172:175], v[216:219], v[6:9]
	v_mfma_f32_16x16x32_bf16 v[10:13], v[172:175], v[220:223], v[10:13]
	v_mfma_f32_16x16x32_bf16 v[14:17], v[172:175], v[224:227], v[14:17]
	s_waitcnt lgkmcnt(2)
	v_mfma_f32_16x16x32_bf16 v[18:21], v[176:179], v[212:215], v[18:21]
	v_mfma_f32_16x16x32_bf16 v[22:25], v[176:179], v[216:219], v[22:25]
	v_mfma_f32_16x16x32_bf16 v[26:29], v[176:179], v[220:223], v[26:29]
	v_mfma_f32_16x16x32_bf16 v[30:33], v[176:179], v[224:227], v[30:33]
	s_waitcnt lgkmcnt(1)
	v_mfma_f32_16x16x32_bf16 v[34:37], v[180:183], v[212:215], v[34:37]
	v_mfma_f32_16x16x32_bf16 v[38:41], v[180:183], v[216:219], v[38:41]
	v_mfma_f32_16x16x32_bf16 v[42:45], v[180:183], v[220:223], v[42:45]
	v_mfma_f32_16x16x32_bf16 v[46:49], v[180:183], v[224:227], v[46:49]
	s_waitcnt lgkmcnt(0)
	v_mfma_f32_16x16x32_bf16 v[50:53], v[184:187], v[212:215], v[50:53]
	v_mfma_f32_16x16x32_bf16 v[54:57], v[184:187], v[216:219], v[54:57]
	v_mfma_f32_16x16x32_bf16 v[58:61], v[184:187], v[220:223], v[58:61]
	v_mfma_f32_16x16x32_bf16 v[62:65], v[184:187], v[224:227], v[62:65]
	s_setprio 0
	s_waitcnt vmcnt(6)
	s_barrier
	s_setprio 3
	v_add_u32_e32 v236, s42, v232
	v_add_u32_e32 v237, s42, v233
	ds_read_b128 v[188:191], v236
	ds_read_b128 v[196:199], v236 offset:2048
	ds_read_b128 v[200:203], v236 offset:4096
	ds_read_b128 v[204:207], v236 offset:6144
	ds_read_b128 v[212:215], v237
	ds_read_b128 v[216:219], v237 offset:2048
	ds_read_b128 v[220:223], v237 offset:4096
	ds_read_b128 v[224:227], v237 offset:6144
	s_add_i32 m0, s51, 0x6000
	s_nop 0
	global_load_lds_dwordx4 v229, s[46:47]
	s_add_i32 m0, s51, 0x6400
	s_nop 0
	global_load_lds_dwordx4 v231, s[46:47]
	s_add_i32 m0, s51, 0x8000
	s_nop 0
	global_load_lds_dwordx4 v228, s[48:49]
	s_add_i32 m0, s51, 0x8400
	s_nop 0
	global_load_lds_dwordx4 v230, s[48:49]
	s_add_i32 m0, s51, 0xa000
	s_nop 0
	global_load_lds_dwordx4 v229, s[48:49]
	s_add_i32 m0, s51, 0xa400
	s_nop 0
	global_load_lds_dwordx4 v231, s[48:49]
	s_waitcnt lgkmcnt(7)
	s_setprio 1
	v_mfma_f32_16x16x32_bf16 v[66:69], v[136:139], v[188:191], v[66:69]
	v_mfma_f32_16x16x32_bf16 v[82:85], v[140:143], v[188:191], v[82:85]
	v_mfma_f32_16x16x32_bf16 v[98:101], v[144:147], v[188:191], v[98:101]
	v_mfma_f32_16x16x32_bf16 v[114:117], v[148:151], v[188:191], v[114:117]
	s_waitcnt lgkmcnt(6)
	v_mfma_f32_16x16x32_bf16 v[70:73], v[136:139], v[196:199], v[70:73]
	v_mfma_f32_16x16x32_bf16 v[86:89], v[140:143], v[196:199], v[86:89]
	v_mfma_f32_16x16x32_bf16 v[102:105], v[144:147], v[196:199], v[102:105]
	v_mfma_f32_16x16x32_bf16 v[118:121], v[148:151], v[196:199], v[118:121]
	s_waitcnt lgkmcnt(5)
	v_mfma_f32_16x16x32_bf16 v[74:77], v[136:139], v[200:203], v[74:77]
	v_mfma_f32_16x16x32_bf16 v[90:93], v[140:143], v[200:203], v[90:93]
	v_mfma_f32_16x16x32_bf16 v[106:109], v[144:147], v[200:203], v[106:109]
	v_mfma_f32_16x16x32_bf16 v[122:125], v[148:151], v[200:203], v[122:125]
	s_waitcnt lgkmcnt(4)
	v_mfma_f32_16x16x32_bf16 v[78:81], v[136:139], v[204:207], v[78:81]
	v_mfma_f32_16x16x32_bf16 v[94:97], v[140:143], v[204:207], v[94:97]
	v_mfma_f32_16x16x32_bf16 v[110:113], v[144:147], v[204:207], v[110:113]
	v_mfma_f32_16x16x32_bf16 v[126:129], v[148:151], v[204:207], v[126:129]
	s_waitcnt lgkmcnt(3)
	v_mfma_f32_16x16x32_bf16 v[66:69], v[172:175], v[212:215], v[66:69]
	v_mfma_f32_16x16x32_bf16 v[82:85], v[176:179], v[212:215], v[82:85]
	v_mfma_f32_16x16x32_bf16 v[98:101], v[180:183], v[212:215], v[98:101]
	v_mfma_f32_16x16x32_bf16 v[114:117], v[184:187], v[212:215], v[114:117]
	s_waitcnt lgkmcnt(2)
	v_mfma_f32_16x16x32_bf16 v[70:73], v[172:175], v[216:219], v[70:73]
	v_mfma_f32_16x16x32_bf16 v[86:89], v[176:179], v[216:219], v[86:89]
	v_mfma_f32_16x16x32_bf16 v[102:105], v[180:183], v[216:219], v[102:105]
	v_mfma_f32_16x16x32_bf16 v[118:121], v[184:187], v[216:219], v[118:121]
	s_waitcnt lgkmcnt(1)
	v_mfma_f32_16x16x32_bf16 v[74:77], v[172:175], v[220:223], v[74:77]
	v_mfma_f32_16x16x32_bf16 v[90:93], v[176:179], v[220:223], v[90:93]
	v_mfma_f32_16x16x32_bf16 v[106:109], v[180:183], v[220:223], v[106:109]
	v_mfma_f32_16x16x32_bf16 v[122:125], v[184:187], v[220:223], v[122:125]
	s_waitcnt lgkmcnt(0)
	v_mfma_f32_16x16x32_bf16 v[78:81], v[172:175], v[224:227], v[78:81]
	v_mfma_f32_16x16x32_bf16 v[94:97], v[176:179], v[224:227], v[94:97]
	v_mfma_f32_16x16x32_bf16 v[110:113], v[180:183], v[224:227], v[110:113]
	v_mfma_f32_16x16x32_bf16 v[126:129], v[184:187], v[224:227], v[126:129]
	s_setprio 0
	v_add_u32_e32 v228, 0x80, v228
	v_add_u32_e32 v229, 0x80, v229
	v_add_u32_e32 v230, 0x80, v230
	v_add_u32_e32 v231, 0x80, v231
	s_waitcnt vmcnt(4)
	s_barrier
	s_add_i32 s52, s52, 1
	s_cmp_lt_u32 s52, 29
	s_cbranch_scc1 .Lfin3_loop
	s_setprio 3
	v_add_u32_e32 v234, s22, v232
	v_add_u32_e32 v236, s28, v232
	v_add_u32_e32 v235, s22, v233
	v_add_u32_e32 v237, s28, v233
	ds_read_b128 v[136:139], v234
	ds_read_b128 v[188:191], v236
	ds_read_b128 v[196:199], v236 offset:2048
	ds_read_b128 v[200:203], v236 offset:4096
	ds_read_b128 v[204:207], v236 offset:6144
	ds_read_b128 v[140:143], v234 offset:2048
	ds_read_b128 v[144:147], v234 offset:4096
	ds_read_b128 v[148:151], v234 offset:6144
	ds_read_b128 v[172:175], v235
	ds_read_b128 v[212:215], v237
	ds_read_b128 v[216:219], v237 offset:2048
	ds_read_b128 v[220:223], v237 offset:4096
	ds_read_b128 v[224:227], v237 offset:6144
	ds_read_b128 v[176:179], v235 offset:2048
	ds_read_b128 v[180:183], v235 offset:4096
	ds_read_b128 v[184:187], v235 offset:6144
	s_waitcnt lgkmcnt(11)
	s_setprio 1
	v_mfma_f32_16x16x32_bf16 v[2:5], v[136:139], v[188:191], v[2:5]
	v_mfma_f32_16x16x32_bf16 v[6:9], v[136:139], v[196:199], v[6:9]
	v_mfma_f32_16x16x32_bf16 v[10:13], v[136:139], v[200:203], v[10:13]
	v_mfma_f32_16x16x32_bf16 v[14:17], v[136:139], v[204:207], v[14:17]
	s_waitcnt lgkmcnt(10)
	v_mfma_f32_16x16x32_bf16 v[18:21], v[140:143], v[188:191], v[18:21]
	v_mfma_f32_16x16x32_bf16 v[22:25], v[140:143], v[196:199], v[22:25]
	v_mfma_f32_16x16x32_bf16 v[26:29], v[140:143], v[200:203], v[26:29]
	v_mfma_f32_16x16x32_bf16 v[30:33], v[140:143], v[204:207], v[30:33]
	s_waitcnt lgkmcnt(9)
	v_mfma_f32_16x16x32_bf16 v[34:37], v[144:147], v[188:191], v[34:37]
	v_mfma_f32_16x16x32_bf16 v[38:41], v[144:147], v[196:199], v[38:41]
	v_mfma_f32_16x16x32_bf16 v[42:45], v[144:147], v[200:203], v[42:45]
	v_mfma_f32_16x16x32_bf16 v[46:49], v[144:147], v[204:207], v[46:49]
	s_waitcnt lgkmcnt(8)
	v_mfma_f32_16x16x32_bf16 v[50:53], v[148:151], v[188:191], v[50:53]
	v_mfma_f32_16x16x32_bf16 v[54:57], v[148:151], v[196:199], v[54:57]
	v_mfma_f32_16x16x32_bf16 v[58:61], v[148:151], v[200:203], v[58:61]
	v_mfma_f32_16x16x32_bf16 v[62:65], v[148:151], v[204:207], v[62:65]
	s_waitcnt lgkmcnt(3)
	v_mfma_f32_16x16x32_bf16 v[2:5], v[172:175], v[212:215], v[2:5]
	v_mfma_f32_16x16x32_bf16 v[6:9], v[172:175], v[216:219], v[6:9]
	v_mfma_f32_16x16x32_bf16 v[10:13], v[172:175], v[220:223], v[10:13]
	v_mfma_f32_16x16x32_bf16 v[14:17], v[172:175], v[224:227], v[14:17]
	s_waitcnt lgkmcnt(2)
	v_mfma_f32_16x16x32_bf16 v[18:21], v[176:179], v[212:215], v[18:21]
	v_mfma_f32_16x16x32_bf16 v[22:25], v[176:179], v[216:219], v[22:25]
	v_mfma_f32_16x16x32_bf16 v[26:29], v[176:179], v[220:223], v[26:29]
	v_mfma_f32_16x16x32_bf16 v[30:33], v[176:179], v[224:227], v[30:33]
	s_waitcnt lgkmcnt(1)
	v_mfma_f32_16x16x32_bf16 v[34:37], v[180:183], v[212:215], v[34:37]
	v_mfma_f32_16x16x32_bf16 v[38:41], v[180:183], v[216:219], v[38:41]
	v_mfma_f32_16x16x32_bf16 v[42:45], v[180:183], v[220:223], v[42:45]
	v_mfma_f32_16x16x32_bf16 v[46:49], v[180:183], v[224:227], v[46:49]
	s_waitcnt lgkmcnt(0)
	v_mfma_f32_16x16x32_bf16 v[50:53], v[184:187], v[212:215], v[50:53]
	v_mfma_f32_16x16x32_bf16 v[54:57], v[184:187], v[216:219], v[54:57]
	v_mfma_f32_16x16x32_bf16 v[58:61], v[184:187], v[220:223], v[58:61]
	v_mfma_f32_16x16x32_bf16 v[62:65], v[184:187], v[224:227], v[62:65]
	s_setprio 0
	s_waitcnt vmcnt(0)
	s_barrier
	s_setprio 3
	v_add_u32_e32 v236, s40, v232
	v_add_u32_e32 v237, s40, v233
	ds_read_b128 v[188:191], v236
	ds_read_b128 v[196:199], v236 offset:2048
	ds_read_b128 v[200:203], v236 offset:4096
	ds_read_b128 v[204:207], v236 offset:6144
	ds_read_b128 v[212:215], v237
	ds_read_b128 v[216:219], v237 offset:2048
	ds_read_b128 v[220:223], v237 offset:4096
	ds_read_b128 v[224:227], v237 offset:6144
	s_waitcnt lgkmcnt(7)
	s_setprio 1
	v_mfma_f32_16x16x32_bf16 v[66:69], v[136:139], v[188:191], v[66:69]
	v_mfma_f32_16x16x32_bf16 v[82:85], v[140:143], v[188:191], v[82:85]
	v_mfma_f32_16x16x32_bf16 v[98:101], v[144:147], v[188:191], v[98:101]
	v_mfma_f32_16x16x32_bf16 v[114:117], v[148:151], v[188:191], v[114:117]
	s_waitcnt lgkmcnt(6)
	v_mfma_f32_16x16x32_bf16 v[70:73], v[136:139], v[196:199], v[70:73]
	v_mfma_f32_16x16x32_bf16 v[86:89], v[140:143], v[196:199], v[86:89]
	v_mfma_f32_16x16x32_bf16 v[102:105], v[144:147], v[196:199], v[102:105]
	v_mfma_f32_16x16x32_bf16 v[118:121], v[148:151], v[196:199], v[118:121]
	s_waitcnt lgkmcnt(5)
	v_mfma_f32_16x16x32_bf16 v[74:77], v[136:139], v[200:203], v[74:77]
	v_mfma_f32_16x16x32_bf16 v[90:93], v[140:143], v[200:203], v[90:93]
	v_mfma_f32_16x16x32_bf16 v[106:109], v[144:147], v[200:203], v[106:109]
	v_mfma_f32_16x16x32_bf16 v[122:125], v[148:151], v[200:203], v[122:125]
	s_waitcnt lgkmcnt(4)
	v_mfma_f32_16x16x32_bf16 v[78:81], v[136:139], v[204:207], v[78:81]
	v_mfma_f32_16x16x32_bf16 v[94:97], v[140:143], v[204:207], v[94:97]
	v_mfma_f32_16x16x32_bf16 v[110:113], v[144:147], v[204:207], v[110:113]
	v_mfma_f32_16x16x32_bf16 v[126:129], v[148:151], v[204:207], v[126:129]
	s_waitcnt lgkmcnt(3)
	v_mfma_f32_16x16x32_bf16 v[66:69], v[172:175], v[212:215], v[66:69]
	v_mfma_f32_16x16x32_bf16 v[82:85], v[176:179], v[212:215], v[82:85]
	v_mfma_f32_16x16x32_bf16 v[98:101], v[180:183], v[212:215], v[98:101]
	v_mfma_f32_16x16x32_bf16 v[114:117], v[184:187], v[212:215], v[114:117]
	s_waitcnt lgkmcnt(2)
	v_mfma_f32_16x16x32_bf16 v[70:73], v[172:175], v[216:219], v[70:73]
	v_mfma_f32_16x16x32_bf16 v[86:89], v[176:179], v[216:219], v[86:89]
	v_mfma_f32_16x16x32_bf16 v[102:105], v[180:183], v[216:219], v[102:105]
	v_mfma_f32_16x16x32_bf16 v[118:121], v[184:187], v[216:219], v[118:121]
	s_waitcnt lgkmcnt(1)
	v_mfma_f32_16x16x32_bf16 v[74:77], v[172:175], v[220:223], v[74:77]
	v_mfma_f32_16x16x32_bf16 v[90:93], v[176:179], v[220:223], v[90:93]
	v_mfma_f32_16x16x32_bf16 v[106:109], v[180:183], v[220:223], v[106:109]
	v_mfma_f32_16x16x32_bf16 v[122:125], v[184:187], v[220:223], v[122:125]
	s_waitcnt lgkmcnt(0)
	v_mfma_f32_16x16x32_bf16 v[78:81], v[172:175], v[224:227], v[78:81]
	v_mfma_f32_16x16x32_bf16 v[94:97], v[176:179], v[224:227], v[94:97]
	v_mfma_f32_16x16x32_bf16 v[110:113], v[180:183], v[224:227], v[110:113]
	v_mfma_f32_16x16x32_bf16 v[126:129], v[184:187], v[224:227], v[126:129]
	s_setprio 0
	s_nop 7
	s_barrier
	s_setprio 2
	s_load_dwordx2 s[58:59], s[12:13], 0x100
	v_lshrrev_b32_e32 v241, 5, v131
	v_and_b32_e32 v242, 31, v131
	v_lshlrev_b32_e32 v243, 4, v242
	s_movk_i32 s56, 0x210
	v_mad_u32_u24 v239, v241, s56, v243
	v_add_u32_e32 v239, 16, v239
	v_lshlrev_b32_e32 v240, 13, v241
	v_or_b32_e32 v240, v240, v243
	s_lshl_b32 s56, s53, 13
	s_lshl_b32 s57, s54, 2
	s_add_i32 s56, s56, s57
	s_waitcnt lgkmcnt(0)
	s_add_u32 s58, s58, s56
	s_addc_u32 s59, s59, 0
	ds_write_b32 v238, v2
	ds_write_b32 v238, v3 offset:528
	ds_write_b32 v238, v4 offset:1056
	ds_write_b32 v238, v5 offset:1584
	ds_write_b32 v238, v6 offset:64
	ds_write_b32 v238, v7 offset:592
	ds_write_b32 v238, v8 offset:1120
	ds_write_b32 v238, v9 offset:1648
	ds_write_b32 v238, v10 offset:128
	ds_write_b32 v238, v11 offset:656
	ds_write_b32 v238, v12 offset:1184
	ds_write_b32 v238, v13 offset:1712
	ds_write_b32 v238, v14 offset:192
	ds_write_b32 v238, v15 offset:720
	ds_write_b32 v238, v16 offset:1248
	ds_write_b32 v238, v17 offset:1776
	ds_write_b32 v238, v18 offset:8448
	ds_write_b32 v238, v19 offset:8976
	ds_write_b32 v238, v20 offset:9504
	ds_write_b32 v238, v21 offset:10032
	ds_write_b32 v238, v22 offset:8512
	ds_write_b32 v238, v23 offset:9040
	ds_write_b32 v238, v24 offset:9568
	ds_write_b32 v238, v25 offset:10096
	ds_write_b32 v238, v26 offset:8576
	ds_write_b32 v238, v27 offset:9104
	ds_write_b32 v238, v28 offset:9632
	ds_write_b32 v238, v29 offset:10160
	ds_write_b32 v238, v30 offset:8640
	ds_write_b32 v238, v31 offset:9168
	ds_write_b32 v238, v32 offset:9696
	ds_write_b32 v238, v33 offset:10224
	ds_write_b32 v238, v34 offset:16896
	ds_write_b32 v238, v35 offset:17424
	ds_write_b32 v238, v36 offset:17952
	ds_write_b32 v238, v37 offset:18480
	ds_write_b32 v238, v38 offset:16960
	ds_write_b32 v238, v39 offset:17488
	ds_write_b32 v238, v40 offset:18016
	ds_write_b32 v238, v41 offset:18544
	ds_write_b32 v238, v42 offset:17024
	ds_write_b32 v238, v43 offset:17552
	ds_write_b32 v238, v44 offset:18080
	ds_write_b32 v238, v45 offset:18608
	ds_write_b32 v238, v46 offset:17088
	ds_write_b32 v238, v47 offset:17616
	ds_write_b32 v238, v48 offset:18144
	ds_write_b32 v238, v49 offset:18672
	ds_write_b32 v238, v50 offset:25344
	ds_write_b32 v238, v51 offset:25872
	ds_write_b32 v238, v52 offset:26400
	ds_write_b32 v238, v53 offset:26928
	ds_write_b32 v238, v54 offset:25408
	ds_write_b32 v238, v55 offset:25936
	ds_write_b32 v238, v56 offset:26464
	ds_write_b32 v238, v57 offset:26992
	ds_write_b32 v238, v58 offset:25472
	ds_write_b32 v238, v59 offset:26000
	ds_write_b32 v238, v60 offset:26528
	ds_write_b32 v238, v61 offset:27056
	ds_write_b32 v238, v62 offset:25536
	ds_write_b32 v238, v63 offset:26064
	ds_write_b32 v238, v64 offset:26592
	ds_write_b32 v238, v65 offset:27120
	s_mov_b32 s0, s58
	s_mov_b32 s1, s59
	global_load_dwordx4 v[136:139], v240, s[0:1]
	s_add_u32 s0, s0, 0x10000
	s_addc_u32 s1, s1, 0
	global_load_dwordx4 v[140:143], v240, s[0:1]
	s_add_u32 s0, s0, 0x10000
	s_addc_u32 s1, s1, 0
	global_load_dwordx4 v[144:147], v240, s[0:1]
	s_add_u32 s0, s0, 0x10000
	s_addc_u32 s1, s1, 0
	global_load_dwordx4 v[148:151], v240, s[0:1]
	s_add_u32 s0, s0, 0x10000
	s_addc_u32 s1, s1, 0
	global_load_dwordx4 v[172:175], v240, s[0:1]
	s_add_u32 s0, s0, 0x10000
	s_addc_u32 s1, s1, 0
	global_load_dwordx4 v[176:179], v240, s[0:1]
	s_add_u32 s0, s0, 0x10000
	s_addc_u32 s1, s1, 0
	global_load_dwordx4 v[180:183], v240, s[0:1]
	s_add_u32 s0, s0, 0x10000
	s_addc_u32 s1, s1, 0
	global_load_dwordx4 v[184:187], v240, s[0:1]
	s_add_u32 s0, s0, 0x10000
	s_addc_u32 s1, s1, 0
	global_load_dwordx4 v[188:191], v240, s[0:1]
	s_add_u32 s0, s0, 0x10000
	s_addc_u32 s1, s1, 0
	global_load_dwordx4 v[196:199], v240, s[0:1]
	s_add_u32 s0, s0, 0x10000
	s_addc_u32 s1, s1, 0
	global_load_dwordx4 v[200:203], v240, s[0:1]
	s_add_u32 s0, s0, 0x10000
	s_addc_u32 s1, s1, 0
	global_load_dwordx4 v[204:207], v240, s[0:1]
	s_add_u32 s0, s0, 0x10000
	s_addc_u32 s1, s1, 0
	global_load_dwordx4 v[212:215], v240, s[0:1]
	s_add_u32 s0, s0, 0x10000
	s_addc_u32 s1, s1, 0
	global_load_dwordx4 v[216:219], v240, s[0:1]
	s_add_u32 s0, s0, 0x10000
	s_addc_u32 s1, s1, 0
	global_load_dwordx4 v[220:223], v240, s[0:1]
	s_add_u32 s0, s0, 0x10000
	s_addc_u32 s1, s1, 0
	global_load_dwordx4 v[224:227], v240, s[0:1]
	s_waitcnt lgkmcnt(0)
	s_barrier
	ds_read_b128 v[2:5], v239
	ds_read_b128 v[6:9], v239 offset:4224
	ds_read_b128 v[10:13], v239 offset:8448
	ds_read_b128 v[14:17], v239 offset:12672
	ds_read_b128 v[18:21], v239 offset:16896
	ds_read_b128 v[22:25], v239 offset:21120
	ds_read_b128 v[26:29], v239 offset:25344
	ds_read_b128 v[30:33], v239 offset:29568
	ds_read_b128 v[34:37], v239 offset:33792
	ds_read_b128 v[38:41], v239 offset:38016
	ds_read_b128 v[42:45], v239 offset:42240
	ds_read_b128 v[46:49], v239 offset:46464
	ds_read_b128 v[50:53], v239 offset:50688
	ds_read_b128 v[54:57], v239 offset:54912
	ds_read_b128 v[58:61], v239 offset:59136
	ds_read_b128 v[62:65], v239 offset:63360
	s_mov_b32 s0, s58
	s_mov_b32 s1, s59
	s_waitcnt vmcnt(15) lgkmcnt(15)
	v_pk_add_f32 v[2:3], v[2:3], v[136:137]
	v_pk_add_f32 v[4:5], v[4:5], v[138:139]
	s_waitcnt vmcnt(14) lgkmcnt(14)
	v_pk_add_f32 v[6:7], v[6:7], v[140:141]
	v_pk_add_f32 v[8:9], v[8:9], v[142:143]
	s_waitcnt vmcnt(13) lgkmcnt(13)
	v_pk_add_f32 v[10:11], v[10:11], v[144:145]
	v_pk_add_f32 v[12:13], v[12:13], v[146:147]
	s_waitcnt vmcnt(12) lgkmcnt(12)
	v_pk_add_f32 v[14:15], v[14:15], v[148:149]
	v_pk_add_f32 v[16:17], v[16:17], v[150:151]
	s_waitcnt vmcnt(11) lgkmcnt(11)
	v_pk_add_f32 v[18:19], v[18:19], v[172:173]
	v_pk_add_f32 v[20:21], v[20:21], v[174:175]
	s_waitcnt vmcnt(10) lgkmcnt(10)
	v_pk_add_f32 v[22:23], v[22:23], v[176:177]
	v_pk_add_f32 v[24:25], v[24:25], v[178:179]
	s_waitcnt vmcnt(9) lgkmcnt(9)
	v_pk_add_f32 v[26:27], v[26:27], v[180:181]
	v_pk_add_f32 v[28:29], v[28:29], v[182:183]
	s_waitcnt vmcnt(8) lgkmcnt(8)
	v_pk_add_f32 v[30:31], v[30:31], v[184:185]
	v_pk_add_f32 v[32:33], v[32:33], v[186:187]
	s_waitcnt vmcnt(7) lgkmcnt(7)
	v_pk_add_f32 v[34:35], v[34:35], v[188:189]
	v_pk_add_f32 v[36:37], v[36:37], v[190:191]
	s_waitcnt vmcnt(6) lgkmcnt(6)
	v_pk_add_f32 v[38:39], v[38:39], v[196:197]
	v_pk_add_f32 v[40:41], v[40:41], v[198:199]
	s_waitcnt vmcnt(5) lgkmcnt(5)
	v_pk_add_f32 v[42:43], v[42:43], v[200:201]
	v_pk_add_f32 v[44:45], v[44:45], v[202:203]
	s_waitcnt vmcnt(4) lgkmcnt(4)
	v_pk_add_f32 v[46:47], v[46:47], v[204:205]
	v_pk_add_f32 v[48:49], v[48:49], v[206:207]
	s_waitcnt vmcnt(3) lgkmcnt(3)
	v_pk_add_f32 v[50:51], v[50:51], v[212:213]
	v_pk_add_f32 v[52:53], v[52:53], v[214:215]
	s_waitcnt vmcnt(2) lgkmcnt(2)
	v_pk_add_f32 v[54:55], v[54:55], v[216:217]
	v_pk_add_f32 v[56:57], v[56:57], v[218:219]
	s_waitcnt vmcnt(1) lgkmcnt(1)
	v_pk_add_f32 v[58:59], v[58:59], v[220:221]
	v_pk_add_f32 v[60:61], v[60:61], v[222:223]
	s_waitcnt vmcnt(0) lgkmcnt(0)
	v_pk_add_f32 v[62:63], v[62:63], v[224:225]
	v_pk_add_f32 v[64:65], v[64:65], v[226:227]
	global_store_dwordx4 v240, v[2:5], s[0:1]
	s_add_u32 s0, s0, 0x10000
	s_addc_u32 s1, s1, 0
	global_store_dwordx4 v240, v[6:9], s[0:1]
	s_add_u32 s0, s0, 0x10000
	s_addc_u32 s1, s1, 0
	global_store_dwordx4 v240, v[10:13], s[0:1]
	s_add_u32 s0, s0, 0x10000
	s_addc_u32 s1, s1, 0
	global_store_dwordx4 v240, v[14:17], s[0:1]
	s_add_u32 s0, s0, 0x10000
	s_addc_u32 s1, s1, 0
	global_store_dwordx4 v240, v[18:21], s[0:1]
	s_add_u32 s0, s0, 0x10000
	s_addc_u32 s1, s1, 0
	global_store_dwordx4 v240, v[22:25], s[0:1]
	s_add_u32 s0, s0, 0x10000
	s_addc_u32 s1, s1, 0
	global_store_dwordx4 v240, v[26:29], s[0:1]
	s_add_u32 s0, s0, 0x10000
	s_addc_u32 s1, s1, 0
	global_store_dwordx4 v240, v[30:33], s[0:1]
	s_add_u32 s0, s0, 0x10000
	s_addc_u32 s1, s1, 0
	global_store_dwordx4 v240, v[34:37], s[0:1]
	s_add_u32 s0, s0, 0x10000
	s_addc_u32 s1, s1, 0
	global_store_dwordx4 v240, v[38:41], s[0:1]
	s_add_u32 s0, s0, 0x10000
	s_addc_u32 s1, s1, 0
	global_store_dwordx4 v240, v[42:45], s[0:1]
	s_add_u32 s0, s0, 0x10000
	s_addc_u32 s1, s1, 0
	global_store_dwordx4 v240, v[46:49], s[0:1]
	s_add_u32 s0, s0, 0x10000
	s_addc_u32 s1, s1, 0
	global_store_dwordx4 v240, v[50:53], s[0:1]
	s_add_u32 s0, s0, 0x10000
	s_addc_u32 s1, s1, 0
	global_store_dwordx4 v240, v[54:57], s[0:1]
	s_add_u32 s0, s0, 0x10000
	s_addc_u32 s1, s1, 0
	global_store_dwordx4 v240, v[58:61], s[0:1]
	s_add_u32 s0, s0, 0x10000
	s_addc_u32 s1, s1, 0
	global_store_dwordx4 v240, v[62:65], s[0:1]
	s_add_u32 s58, s58, 0x1000
	s_addc_u32 s59, s59, 0
	s_waitcnt lgkmcnt(0)
	s_barrier
	ds_write_b32 v238, v66
	ds_write_b32 v238, v67 offset:528
	ds_write_b32 v238, v68 offset:1056
	ds_write_b32 v238, v69 offset:1584
	ds_write_b32 v238, v70 offset:64
	ds_write_b32 v238, v71 offset:592
	ds_write_b32 v238, v72 offset:1120
	ds_write_b32 v238, v73 offset:1648
	ds_write_b32 v238, v74 offset:128
	ds_write_b32 v238, v75 offset:656
	ds_write_b32 v238, v76 offset:1184
	ds_write_b32 v238, v77 offset:1712
	ds_write_b32 v238, v78 offset:192
	ds_write_b32 v238, v79 offset:720
	ds_write_b32 v238, v80 offset:1248
	ds_write_b32 v238, v81 offset:1776
	ds_write_b32 v238, v82 offset:8448
	ds_write_b32 v238, v83 offset:8976
	ds_write_b32 v238, v84 offset:9504
	ds_write_b32 v238, v85 offset:10032
	ds_write_b32 v238, v86 offset:8512
	ds_write_b32 v238, v87 offset:9040
	ds_write_b32 v238, v88 offset:9568
	ds_write_b32 v238, v89 offset:10096
	ds_write_b32 v238, v90 offset:8576
	ds_write_b32 v238, v91 offset:9104
	ds_write_b32 v238, v92 offset:9632
	ds_write_b32 v238, v93 offset:10160
	ds_write_b32 v238, v94 offset:8640
	ds_write_b32 v238, v95 offset:9168
	ds_write_b32 v238, v96 offset:9696
	ds_write_b32 v238, v97 offset:10224
	ds_write_b32 v238, v98 offset:16896
	ds_write_b32 v238, v99 offset:17424
	ds_write_b32 v238, v100 offset:17952
	ds_write_b32 v238, v101 offset:18480
	ds_write_b32 v238, v102 offset:16960
	ds_write_b32 v238, v103 offset:17488
	ds_write_b32 v238, v104 offset:18016
	ds_write_b32 v238, v105 offset:18544
	ds_write_b32 v238, v106 offset:17024
	ds_write_b32 v238, v107 offset:17552
	ds_write_b32 v238, v108 offset:18080
	ds_write_b32 v238, v109 offset:18608
	ds_write_b32 v238, v110 offset:17088
	ds_write_b32 v238, v111 offset:17616
	ds_write_b32 v238, v112 offset:18144
	ds_write_b32 v238, v113 offset:18672
	ds_write_b32 v238, v114 offset:25344
	ds_write_b32 v238, v115 offset:25872
	ds_write_b32 v238, v116 offset:26400
	ds_write_b32 v238, v117 offset:26928
	ds_write_b32 v238, v118 offset:25408
	ds_write_b32 v238, v119 offset:25936
	ds_write_b32 v238, v120 offset:26464
	ds_write_b32 v238, v121 offset:26992
	ds_write_b32 v238, v122 offset:25472
	ds_write_b32 v238, v123 offset:26000
	ds_write_b32 v238, v124 offset:26528
	ds_write_b32 v238, v125 offset:27056
	ds_write_b32 v238, v126 offset:25536
	ds_write_b32 v238, v127 offset:26064
	ds_write_b32 v238, v128 offset:26592
	ds_write_b32 v238, v129 offset:27120
	s_mov_b32 s0, s58
	s_mov_b32 s1, s59
	global_load_dwordx4 v[136:139], v240, s[0:1]
	s_add_u32 s0, s0, 0x10000
	s_addc_u32 s1, s1, 0
	global_load_dwordx4 v[140:143], v240, s[0:1]
	s_add_u32 s0, s0, 0x10000
	s_addc_u32 s1, s1, 0
	global_load_dwordx4 v[144:147], v240, s[0:1]
	s_add_u32 s0, s0, 0x10000
	s_addc_u32 s1, s1, 0
	global_load_dwordx4 v[148:151], v240, s[0:1]
	s_add_u32 s0, s0, 0x10000
	s_addc_u32 s1, s1, 0
	global_load_dwordx4 v[172:175], v240, s[0:1]
	s_add_u32 s0, s0, 0x10000
	s_addc_u32 s1, s1, 0
	global_load_dwordx4 v[176:179], v240, s[0:1]
	s_add_u32 s0, s0, 0x10000
	s_addc_u32 s1, s1, 0
	global_load_dwordx4 v[180:183], v240, s[0:1]
	s_add_u32 s0, s0, 0x10000
	s_addc_u32 s1, s1, 0
	global_load_dwordx4 v[184:187], v240, s[0:1]
	s_add_u32 s0, s0, 0x10000
	s_addc_u32 s1, s1, 0
	global_load_dwordx4 v[188:191], v240, s[0:1]
	s_add_u32 s0, s0, 0x10000
	s_addc_u32 s1, s1, 0
	global_load_dwordx4 v[196:199], v240, s[0:1]
	s_add_u32 s0, s0, 0x10000
	s_addc_u32 s1, s1, 0
	global_load_dwordx4 v[200:203], v240, s[0:1]
	s_add_u32 s0, s0, 0x10000
	s_addc_u32 s1, s1, 0
	global_load_dwordx4 v[204:207], v240, s[0:1]
	s_add_u32 s0, s0, 0x10000
	s_addc_u32 s1, s1, 0
	global_load_dwordx4 v[212:215], v240, s[0:1]
	s_add_u32 s0, s0, 0x10000
	s_addc_u32 s1, s1, 0
	global_load_dwordx4 v[216:219], v240, s[0:1]
	s_add_u32 s0, s0, 0x10000
	s_addc_u32 s1, s1, 0
	global_load_dwordx4 v[220:223], v240, s[0:1]
	s_add_u32 s0, s0, 0x10000
	s_addc_u32 s1, s1, 0
	global_load_dwordx4 v[224:227], v240, s[0:1]
	s_waitcnt lgkmcnt(0)
	s_barrier
	ds_read_b128 v[66:69], v239
	ds_read_b128 v[70:73], v239 offset:4224
	ds_read_b128 v[74:77], v239 offset:8448
	ds_read_b128 v[78:81], v239 offset:12672
	ds_read_b128 v[82:85], v239 offset:16896
	ds_read_b128 v[86:89], v239 offset:21120
	ds_read_b128 v[90:93], v239 offset:25344
	ds_read_b128 v[94:97], v239 offset:29568
	ds_read_b128 v[98:101], v239 offset:33792
	ds_read_b128 v[102:105], v239 offset:38016
	ds_read_b128 v[106:109], v239 offset:42240
	ds_read_b128 v[110:113], v239 offset:46464
	ds_read_b128 v[114:117], v239 offset:50688
	ds_read_b128 v[118:121], v239 offset:54912
	ds_read_b128 v[122:125], v239 offset:59136
	ds_read_b128 v[126:129], v239 offset:63360
	s_mov_b32 s0, s58
	s_mov_b32 s1, s59
	s_waitcnt vmcnt(15) lgkmcnt(15)
	v_pk_add_f32 v[66:67], v[66:67], v[136:137]
	v_pk_add_f32 v[68:69], v[68:69], v[138:139]
	s_waitcnt vmcnt(14) lgkmcnt(14)
	v_pk_add_f32 v[70:71], v[70:71], v[140:141]
	v_pk_add_f32 v[72:73], v[72:73], v[142:143]
	s_waitcnt vmcnt(13) lgkmcnt(13)
	v_pk_add_f32 v[74:75], v[74:75], v[144:145]
	v_pk_add_f32 v[76:77], v[76:77], v[146:147]
	s_waitcnt vmcnt(12) lgkmcnt(12)
	v_pk_add_f32 v[78:79], v[78:79], v[148:149]
	v_pk_add_f32 v[80:81], v[80:81], v[150:151]
	s_waitcnt vmcnt(11) lgkmcnt(11)
	v_pk_add_f32 v[82:83], v[82:83], v[172:173]
	v_pk_add_f32 v[84:85], v[84:85], v[174:175]
	s_waitcnt vmcnt(10) lgkmcnt(10)
	v_pk_add_f32 v[86:87], v[86:87], v[176:177]
	v_pk_add_f32 v[88:89], v[88:89], v[178:179]
	s_waitcnt vmcnt(9) lgkmcnt(9)
	v_pk_add_f32 v[90:91], v[90:91], v[180:181]
	v_pk_add_f32 v[92:93], v[92:93], v[182:183]
	s_waitcnt vmcnt(8) lgkmcnt(8)
	v_pk_add_f32 v[94:95], v[94:95], v[184:185]
	v_pk_add_f32 v[96:97], v[96:97], v[186:187]
	s_waitcnt vmcnt(7) lgkmcnt(7)
	v_pk_add_f32 v[98:99], v[98:99], v[188:189]
	v_pk_add_f32 v[100:101], v[100:101], v[190:191]
	s_waitcnt vmcnt(6) lgkmcnt(6)
	v_pk_add_f32 v[102:103], v[102:103], v[196:197]
	v_pk_add_f32 v[104:105], v[104:105], v[198:199]
	s_waitcnt vmcnt(5) lgkmcnt(5)
	v_pk_add_f32 v[106:107], v[106:107], v[200:201]
	v_pk_add_f32 v[108:109], v[108:109], v[202:203]
	s_waitcnt vmcnt(4) lgkmcnt(4)
	v_pk_add_f32 v[110:111], v[110:111], v[204:205]
	v_pk_add_f32 v[112:113], v[112:113], v[206:207]
	s_waitcnt vmcnt(3) lgkmcnt(3)
	v_pk_add_f32 v[114:115], v[114:115], v[212:213]
	v_pk_add_f32 v[116:117], v[116:117], v[214:215]
	s_waitcnt vmcnt(2) lgkmcnt(2)
	v_pk_add_f32 v[118:119], v[118:119], v[216:217]
	v_pk_add_f32 v[120:121], v[120:121], v[218:219]
	s_waitcnt vmcnt(1) lgkmcnt(1)
	v_pk_add_f32 v[122:123], v[122:123], v[220:221]
	v_pk_add_f32 v[124:125], v[124:125], v[222:223]
	s_waitcnt vmcnt(0) lgkmcnt(0)
	v_pk_add_f32 v[126:127], v[126:127], v[224:225]
	v_pk_add_f32 v[128:129], v[128:129], v[226:227]
	global_store_dwordx4 v240, v[66:69], s[0:1]
	s_add_u32 s0, s0, 0x10000
	s_addc_u32 s1, s1, 0
	global_store_dwordx4 v240, v[70:73], s[0:1]
	s_add_u32 s0, s0, 0x10000
	s_addc_u32 s1, s1, 0
	global_store_dwordx4 v240, v[74:77], s[0:1]
	s_add_u32 s0, s0, 0x10000
	s_addc_u32 s1, s1, 0
	global_store_dwordx4 v240, v[78:81], s[0:1]
	s_add_u32 s0, s0, 0x10000
	s_addc_u32 s1, s1, 0
	global_store_dwordx4 v240, v[82:85], s[0:1]
	s_add_u32 s0, s0, 0x10000
	s_addc_u32 s1, s1, 0
	global_store_dwordx4 v240, v[86:89], s[0:1]
	s_add_u32 s0, s0, 0x10000
	s_addc_u32 s1, s1, 0
	global_store_dwordx4 v240, v[90:93], s[0:1]
	s_add_u32 s0, s0, 0x10000
	s_addc_u32 s1, s1, 0
	global_store_dwordx4 v240, v[94:97], s[0:1]
	s_add_u32 s0, s0, 0x10000
	s_addc_u32 s1, s1, 0
	global_store_dwordx4 v240, v[98:101], s[0:1]
	s_add_u32 s0, s0, 0x10000
	s_addc_u32 s1, s1, 0
	global_store_dwordx4 v240, v[102:105], s[0:1]
	s_add_u32 s0, s0, 0x10000
	s_addc_u32 s1, s1, 0
	global_store_dwordx4 v240, v[106:109], s[0:1]
	s_add_u32 s0, s0, 0x10000
	s_addc_u32 s1, s1, 0
	global_store_dwordx4 v240, v[110:113], s[0:1]
	s_add_u32 s0, s0, 0x10000
	s_addc_u32 s1, s1, 0
	global_store_dwordx4 v240, v[114:117], s[0:1]
	s_add_u32 s0, s0, 0x10000
	s_addc_u32 s1, s1, 0
	global_store_dwordx4 v240, v[118:121], s[0:1]
	s_add_u32 s0, s0, 0x10000
	s_addc_u32 s1, s1, 0
	global_store_dwordx4 v240, v[122:125], s[0:1]
	s_add_u32 s0, s0, 0x10000
	s_addc_u32 s1, s1, 0
	global_store_dwordx4 v240, v[126:129], s[0:1]
	s_add_i32 s21, s21, s72
	s_cmpk_lt_i32 s21, 0x200
	s_waitcnt lgkmcnt(0)
	s_barrier
	s_cbranch_scc1 .Lfin3_tile
.Lfin3_done:
	s_setprio 0

.Lgu2_loop_a0:
	s_setprio 3
	v_add_u32_e32 v236, s40, v232
	v_add_u32_e32 v237, s40, v233
	ds_read_b128 v[188:191], v236
	ds_read_b128 v[196:199], v236 offset:2048
	ds_read_b128 v[200:203], v236 offset:4096
	ds_read_b128 v[204:207], v236 offset:6144
	ds_read_b128 v[212:215], v237
	ds_read_b128 v[216:219], v237 offset:2048
	ds_read_b128 v[220:223], v237 offset:4096
	ds_read_b128 v[224:227], v237 offset:6144
	s_mov_b32 m0, s51
	s_nop 0
	global_load_lds_dwordx4 v229, s[46:47]
	s_add_i32 m0, s51, 0x400
	s_nop 0
	global_load_lds_dwordx4 v231, s[46:47]
	s_add_i32 m0, s51, 0x2000
	s_nop 0
	global_load_lds_dwordx4 v228, s[48:49]
	s_add_i32 m0, s51, 0x2400
	s_nop 0
	global_load_lds_dwordx4 v230, s[48:49]
	s_add_i32 m0, s51, 0x4000
	s_nop 0
	global_load_lds_dwordx4 v229, s[48:49]
	s_add_i32 m0, s51, 0x4400
	s_nop 0
	global_load_lds_dwordx4 v231, s[48:49]
	s_waitcnt lgkmcnt(7)
	s_setprio 1
	v_mfma_f32_16x16x32_bf16 v[66:69], v[136:139], v[188:191], v[66:69]
	v_mfma_f32_16x16x32_bf16 v[82:85], v[140:143], v[188:191], v[82:85]
	v_mfma_f32_16x16x32_bf16 v[98:101], v[144:147], v[188:191], v[98:101]
	v_mfma_f32_16x16x32_bf16 v[114:117], v[148:151], v[188:191], v[114:117]
	s_waitcnt lgkmcnt(6)
	v_mfma_f32_16x16x32_bf16 v[70:73], v[136:139], v[196:199], v[70:73]
	v_mfma_f32_16x16x32_bf16 v[86:89], v[140:143], v[196:199], v[86:89]
	v_mfma_f32_16x16x32_bf16 v[102:105], v[144:147], v[196:199], v[102:105]
	v_mfma_f32_16x16x32_bf16 v[118:121], v[148:151], v[196:199], v[118:121]
	s_waitcnt lgkmcnt(5)
	v_mfma_f32_16x16x32_bf16 v[74:77], v[136:139], v[200:203], v[74:77]
	v_mfma_f32_16x16x32_bf16 v[90:93], v[140:143], v[200:203], v[90:93]
	v_mfma_f32_16x16x32_bf16 v[106:109], v[144:147], v[200:203], v[106:109]
	v_mfma_f32_16x16x32_bf16 v[122:125], v[148:151], v[200:203], v[122:125]
	s_waitcnt lgkmcnt(4)
	v_mfma_f32_16x16x32_bf16 v[78:81], v[136:139], v[204:207], v[78:81]
	v_mfma_f32_16x16x32_bf16 v[94:97], v[140:143], v[204:207], v[94:97]
	v_mfma_f32_16x16x32_bf16 v[110:113], v[144:147], v[204:207], v[110:113]
	v_mfma_f32_16x16x32_bf16 v[126:129], v[148:151], v[204:207], v[126:129]
	s_waitcnt lgkmcnt(3)
	v_mfma_f32_16x16x32_bf16 v[66:69], v[172:175], v[212:215], v[66:69]
	v_mfma_f32_16x16x32_bf16 v[82:85], v[176:179], v[212:215], v[82:85]
	v_mfma_f32_16x16x32_bf16 v[98:101], v[180:183], v[212:215], v[98:101]
	v_mfma_f32_16x16x32_bf16 v[114:117], v[184:187], v[212:215], v[114:117]
	s_waitcnt lgkmcnt(2)
	v_mfma_f32_16x16x32_bf16 v[70:73], v[172:175], v[216:219], v[70:73]
	v_mfma_f32_16x16x32_bf16 v[86:89], v[176:179], v[216:219], v[86:89]
	v_mfma_f32_16x16x32_bf16 v[102:105], v[180:183], v[216:219], v[102:105]
	v_mfma_f32_16x16x32_bf16 v[118:121], v[184:187], v[216:219], v[118:121]
	s_waitcnt lgkmcnt(1)
	v_mfma_f32_16x16x32_bf16 v[74:77], v[172:175], v[220:223], v[74:77]
	v_mfma_f32_16x16x32_bf16 v[90:93], v[176:179], v[220:223], v[90:93]
	v_mfma_f32_16x16x32_bf16 v[106:109], v[180:183], v[220:223], v[106:109]
	v_mfma_f32_16x16x32_bf16 v[122:125], v[184:187], v[220:223], v[122:125]
	s_waitcnt lgkmcnt(0)
	v_mfma_f32_16x16x32_bf16 v[78:81], v[172:175], v[224:227], v[78:81]
	v_mfma_f32_16x16x32_bf16 v[94:97], v[176:179], v[224:227], v[94:97]
	v_mfma_f32_16x16x32_bf16 v[110:113], v[180:183], v[224:227], v[110:113]
	v_mfma_f32_16x16x32_bf16 v[126:129], v[184:187], v[224:227], v[126:129]
	s_setprio 0
	v_add_u32_e32 v228, 0x80, v228
	v_add_u32_e32 v229, 0x80, v229
	v_add_u32_e32 v230, 0x80, v230
	v_add_u32_e32 v231, 0x80, v231
	s_waitcnt vmcnt(4)
	s_barrier
	s_setprio 3
	v_add_u32_e32 v234, s23, v232
	v_add_u32_e32 v236, s29, v232
	v_add_u32_e32 v235, s23, v233
	v_add_u32_e32 v237, s29, v233
	ds_read_b128 v[136:139], v234
	ds_read_b128 v[188:191], v236
	ds_read_b128 v[196:199], v236 offset:2048
	ds_read_b128 v[200:203], v236 offset:4096
	ds_read_b128 v[204:207], v236 offset:6144
	ds_read_b128 v[140:143], v234 offset:2048
	ds_read_b128 v[144:147], v234 offset:4096
	ds_read_b128 v[148:151], v234 offset:6144
	ds_read_b128 v[172:175], v235
	ds_read_b128 v[212:215], v237
	ds_read_b128 v[216:219], v237 offset:2048
	ds_read_b128 v[220:223], v237 offset:4096
	ds_read_b128 v[224:227], v237 offset:6144
	ds_read_b128 v[176:179], v235 offset:2048
	ds_read_b128 v[180:183], v235 offset:4096
	ds_read_b128 v[184:187], v235 offset:6144
	s_add_i32 m0, s51, 0x6000
	s_nop 0
	global_load_lds_dwordx4 v228, s[44:45]
	s_add_i32 m0, s51, 0x6400
	s_nop 0
	global_load_lds_dwordx4 v230, s[44:45]
	s_add_i32 m0, s51, 0x8000
	s_nop 0
	global_load_lds_dwordx4 v229, s[44:45]
	s_add_i32 m0, s51, 0x8400
	s_nop 0
	global_load_lds_dwordx4 v231, s[44:45]
	s_add_i32 m0, s51, 0xa000
	s_nop 0
	global_load_lds_dwordx4 v228, s[46:47]
	s_add_i32 m0, s51, 0xa400
	s_nop 0
	global_load_lds_dwordx4 v230, s[46:47]
	s_waitcnt lgkmcnt(11)
	s_setprio 1
	v_mfma_f32_16x16x32_bf16 v[2:5], v[136:139], v[188:191], v[2:5]
	v_mfma_f32_16x16x32_bf16 v[6:9], v[136:139], v[196:199], v[6:9]
	v_mfma_f32_16x16x32_bf16 v[10:13], v[136:139], v[200:203], v[10:13]
	v_mfma_f32_16x16x32_bf16 v[14:17], v[136:139], v[204:207], v[14:17]
	s_waitcnt lgkmcnt(10)
	v_mfma_f32_16x16x32_bf16 v[18:21], v[140:143], v[188:191], v[18:21]
	v_mfma_f32_16x16x32_bf16 v[22:25], v[140:143], v[196:199], v[22:25]
	v_mfma_f32_16x16x32_bf16 v[26:29], v[140:143], v[200:203], v[26:29]
	v_mfma_f32_16x16x32_bf16 v[30:33], v[140:143], v[204:207], v[30:33]
	s_waitcnt lgkmcnt(9)
	v_mfma_f32_16x16x32_bf16 v[34:37], v[144:147], v[188:191], v[34:37]
	v_mfma_f32_16x16x32_bf16 v[38:41], v[144:147], v[196:199], v[38:41]
	v_mfma_f32_16x16x32_bf16 v[42:45], v[144:147], v[200:203], v[42:45]
	v_mfma_f32_16x16x32_bf16 v[46:49], v[144:147], v[204:207], v[46:49]
	s_waitcnt lgkmcnt(8)
	v_mfma_f32_16x16x32_bf16 v[50:53], v[148:151], v[188:191], v[50:53]
	v_mfma_f32_16x16x32_bf16 v[54:57], v[148:151], v[196:199], v[54:57]
	v_mfma_f32_16x16x32_bf16 v[58:61], v[148:151], v[200:203], v[58:61]
	v_mfma_f32_16x16x32_bf16 v[62:65], v[148:151], v[204:207], v[62:65]
	s_waitcnt lgkmcnt(3)
	v_mfma_f32_16x16x32_bf16 v[2:5], v[172:175], v[212:215], v[2:5]
	v_mfma_f32_16x16x32_bf16 v[6:9], v[172:175], v[216:219], v[6:9]
	v_mfma_f32_16x16x32_bf16 v[10:13], v[172:175], v[220:223], v[10:13]
	v_mfma_f32_16x16x32_bf16 v[14:17], v[172:175], v[224:227], v[14:17]
	s_waitcnt lgkmcnt(2)
	v_mfma_f32_16x16x32_bf16 v[18:21], v[176:179], v[212:215], v[18:21]
	v_mfma_f32_16x16x32_bf16 v[22:25], v[176:179], v[216:219], v[22:25]
	v_mfma_f32_16x16x32_bf16 v[26:29], v[176:179], v[220:223], v[26:29]
	v_mfma_f32_16x16x32_bf16 v[30:33], v[176:179], v[224:227], v[30:33]
	s_waitcnt lgkmcnt(1)
	v_mfma_f32_16x16x32_bf16 v[34:37], v[180:183], v[212:215], v[34:37]
	v_mfma_f32_16x16x32_bf16 v[38:41], v[180:183], v[216:219], v[38:41]
	v_mfma_f32_16x16x32_bf16 v[42:45], v[180:183], v[220:223], v[42:45]
	v_mfma_f32_16x16x32_bf16 v[46:49], v[180:183], v[224:227], v[46:49]
	s_waitcnt lgkmcnt(0)
	v_mfma_f32_16x16x32_bf16 v[50:53], v[184:187], v[212:215], v[50:53]
	v_mfma_f32_16x16x32_bf16 v[54:57], v[184:187], v[216:219], v[54:57]
	v_mfma_f32_16x16x32_bf16 v[58:61], v[184:187], v[220:223], v[58:61]
	v_mfma_f32_16x16x32_bf16 v[62:65], v[184:187], v[224:227], v[62:65]
	s_setprio 0
	s_waitcnt vmcnt(6)
	s_barrier
	s_setprio 3
	v_add_u32_e32 v236, s41, v232
	v_add_u32_e32 v237, s41, v233
	ds_read_b128 v[188:191], v236
	ds_read_b128 v[196:199], v236 offset:2048
	ds_read_b128 v[200:203], v236 offset:4096
	ds_read_b128 v[204:207], v236 offset:6144
	ds_read_b128 v[212:215], v237
	ds_read_b128 v[216:219], v237 offset:2048
	ds_read_b128 v[220:223], v237 offset:4096
	ds_read_b128 v[224:227], v237 offset:6144
	s_add_i32 m0, s51, 0xc000
	s_nop 0
	global_load_lds_dwordx4 v229, s[46:47]
	s_add_i32 m0, s51, 0xc400
	s_nop 0
	global_load_lds_dwordx4 v231, s[46:47]
	s_add_i32 m0, s51, 0xe000
	s_nop 0
	global_load_lds_dwordx4 v228, s[48:49]
	s_add_i32 m0, s51, 0xe400
	s_nop 0
	global_load_lds_dwordx4 v230, s[48:49]
	s_add_i32 m0, s51, 0x10000
	s_nop 0
	global_load_lds_dwordx4 v229, s[48:49]
	s_add_i32 m0, s51, 0x10400
	s_nop 0
	global_load_lds_dwordx4 v231, s[48:49]
	s_waitcnt lgkmcnt(7)
	s_setprio 1
	v_mfma_f32_16x16x32_bf16 v[66:69], v[136:139], v[188:191], v[66:69]
	v_mfma_f32_16x16x32_bf16 v[82:85], v[140:143], v[188:191], v[82:85]
	v_mfma_f32_16x16x32_bf16 v[98:101], v[144:147], v[188:191], v[98:101]
	v_mfma_f32_16x16x32_bf16 v[114:117], v[148:151], v[188:191], v[114:117]
	s_waitcnt lgkmcnt(6)
	v_mfma_f32_16x16x32_bf16 v[70:73], v[136:139], v[196:199], v[70:73]
	v_mfma_f32_16x16x32_bf16 v[86:89], v[140:143], v[196:199], v[86:89]
	v_mfma_f32_16x16x32_bf16 v[102:105], v[144:147], v[196:199], v[102:105]
	v_mfma_f32_16x16x32_bf16 v[118:121], v[148:151], v[196:199], v[118:121]
	s_waitcnt lgkmcnt(5)
	v_mfma_f32_16x16x32_bf16 v[74:77], v[136:139], v[200:203], v[74:77]
	v_mfma_f32_16x16x32_bf16 v[90:93], v[140:143], v[200:203], v[90:93]
	v_mfma_f32_16x16x32_bf16 v[106:109], v[144:147], v[200:203], v[106:109]
	v_mfma_f32_16x16x32_bf16 v[122:125], v[148:151], v[200:203], v[122:125]
	s_waitcnt lgkmcnt(4)
	v_mfma_f32_16x16x32_bf16 v[78:81], v[136:139], v[204:207], v[78:81]
	v_mfma_f32_16x16x32_bf16 v[94:97], v[140:143], v[204:207], v[94:97]
	v_mfma_f32_16x16x32_bf16 v[110:113], v[144:147], v[204:207], v[110:113]
	v_mfma_f32_16x16x32_bf16 v[126:129], v[148:151], v[204:207], v[126:129]
	s_waitcnt lgkmcnt(3)
	v_mfma_f32_16x16x32_bf16 v[66:69], v[172:175], v[212:215], v[66:69]
	v_mfma_f32_16x16x32_bf16 v[82:85], v[176:179], v[212:215], v[82:85]
	v_mfma_f32_16x16x32_bf16 v[98:101], v[180:183], v[212:215], v[98:101]
	v_mfma_f32_16x16x32_bf16 v[114:117], v[184:187], v[212:215], v[114:117]
	s_waitcnt lgkmcnt(2)
	v_mfma_f32_16x16x32_bf16 v[70:73], v[172:175], v[216:219], v[70:73]
	v_mfma_f32_16x16x32_bf16 v[86:89], v[176:179], v[216:219], v[86:89]
	v_mfma_f32_16x16x32_bf16 v[102:105], v[180:183], v[216:219], v[102:105]
	v_mfma_f32_16x16x32_bf16 v[118:121], v[184:187], v[216:219], v[118:121]
	s_waitcnt lgkmcnt(1)
	v_mfma_f32_16x16x32_bf16 v[74:77], v[172:175], v[220:223], v[74:77]
	v_mfma_f32_16x16x32_bf16 v[90:93], v[176:179], v[220:223], v[90:93]
	v_mfma_f32_16x16x32_bf16 v[106:109], v[180:183], v[220:223], v[106:109]
	v_mfma_f32_16x16x32_bf16 v[122:125], v[184:187], v[220:223], v[122:125]
	s_waitcnt lgkmcnt(0)
	v_mfma_f32_16x16x32_bf16 v[78:81], v[172:175], v[224:227], v[78:81]
	v_mfma_f32_16x16x32_bf16 v[94:97], v[176:179], v[224:227], v[94:97]
	v_mfma_f32_16x16x32_bf16 v[110:113], v[180:183], v[224:227], v[110:113]
	v_mfma_f32_16x16x32_bf16 v[126:129], v[184:187], v[224:227], v[126:129]
	s_setprio 0
	v_add_u32_e32 v228, 0x80, v228
	v_add_u32_e32 v229, 0x80, v229
	v_add_u32_e32 v230, 0x80, v230
	v_add_u32_e32 v231, 0x80, v231
	s_waitcnt vmcnt(4)
	s_barrier
	s_setprio 3
	v_add_u32_e32 v234, s24, v232
	v_add_u32_e32 v236, s30, v232
	v_add_u32_e32 v235, s24, v233
	v_add_u32_e32 v237, s30, v233
	ds_read_b128 v[136:139], v234
	ds_read_b128 v[188:191], v236
	ds_read_b128 v[196:199], v236 offset:2048
	ds_read_b128 v[200:203], v236 offset:4096
	ds_read_b128 v[204:207], v236 offset:6144
	ds_read_b128 v[140:143], v234 offset:2048
	ds_read_b128 v[144:147], v234 offset:4096
	ds_read_b128 v[148:151], v234 offset:6144
	ds_read_b128 v[172:175], v235
	ds_read_b128 v[212:215], v237
	ds_read_b128 v[216:219], v237 offset:2048
	ds_read_b128 v[220:223], v237 offset:4096
	ds_read_b128 v[224:227], v237 offset:6144
	ds_read_b128 v[176:179], v235 offset:2048
	ds_read_b128 v[180:183], v235 offset:4096
	ds_read_b128 v[184:187], v235 offset:6144
	s_mov_b32 m0, s51
	s_nop 0
	global_load_lds_dwordx4 v228, s[44:45]
	s_add_i32 m0, s51, 0x400
	s_nop 0
	global_load_lds_dwordx4 v230, s[44:45]
	s_add_i32 m0, s51, 0x2000
	s_nop 0
	global_load_lds_dwordx4 v229, s[44:45]
	s_add_i32 m0, s51, 0x2400
	s_nop 0
	global_load_lds_dwordx4 v231, s[44:45]
	s_add_i32 m0, s51, 0x4000
	s_nop 0
	global_load_lds_dwordx4 v228, s[46:47]
	s_add_i32 m0, s51, 0x4400
	s_nop 0
	global_load_lds_dwordx4 v230, s[46:47]
	s_waitcnt lgkmcnt(11)
	s_setprio 1
	v_mfma_f32_16x16x32_bf16 v[2:5], v[136:139], v[188:191], v[2:5]
	v_mfma_f32_16x16x32_bf16 v[6:9], v[136:139], v[196:199], v[6:9]
	v_mfma_f32_16x16x32_bf16 v[10:13], v[136:139], v[200:203], v[10:13]
	v_mfma_f32_16x16x32_bf16 v[14:17], v[136:139], v[204:207], v[14:17]
	s_waitcnt lgkmcnt(10)
	v_mfma_f32_16x16x32_bf16 v[18:21], v[140:143], v[188:191], v[18:21]
	v_mfma_f32_16x16x32_bf16 v[22:25], v[140:143], v[196:199], v[22:25]
	v_mfma_f32_16x16x32_bf16 v[26:29], v[140:143], v[200:203], v[26:29]
	v_mfma_f32_16x16x32_bf16 v[30:33], v[140:143], v[204:207], v[30:33]
	s_waitcnt lgkmcnt(9)
	v_mfma_f32_16x16x32_bf16 v[34:37], v[144:147], v[188:191], v[34:37]
	v_mfma_f32_16x16x32_bf16 v[38:41], v[144:147], v[196:199], v[38:41]
	v_mfma_f32_16x16x32_bf16 v[42:45], v[144:147], v[200:203], v[42:45]
	v_mfma_f32_16x16x32_bf16 v[46:49], v[144:147], v[204:207], v[46:49]
	s_waitcnt lgkmcnt(8)
	v_mfma_f32_16x16x32_bf16 v[50:53], v[148:151], v[188:191], v[50:53]
	v_mfma_f32_16x16x32_bf16 v[54:57], v[148:151], v[196:199], v[54:57]
	v_mfma_f32_16x16x32_bf16 v[58:61], v[148:151], v[200:203], v[58:61]
	v_mfma_f32_16x16x32_bf16 v[62:65], v[148:151], v[204:207], v[62:65]
	s_waitcnt lgkmcnt(3)
	v_mfma_f32_16x16x32_bf16 v[2:5], v[172:175], v[212:215], v[2:5]
	v_mfma_f32_16x16x32_bf16 v[6:9], v[172:175], v[216:219], v[6:9]
	v_mfma_f32_16x16x32_bf16 v[10:13], v[172:175], v[220:223], v[10:13]
	v_mfma_f32_16x16x32_bf16 v[14:17], v[172:175], v[224:227], v[14:17]
	s_waitcnt lgkmcnt(2)
	v_mfma_f32_16x16x32_bf16 v[18:21], v[176:179], v[212:215], v[18:21]
	v_mfma_f32_16x16x32_bf16 v[22:25], v[176:179], v[216:219], v[22:25]
	v_mfma_f32_16x16x32_bf16 v[26:29], v[176:179], v[220:223], v[26:29]
	v_mfma_f32_16x16x32_bf16 v[30:33], v[176:179], v[224:227], v[30:33]
	s_waitcnt lgkmcnt(1)
	v_mfma_f32_16x16x32_bf16 v[34:37], v[180:183], v[212:215], v[34:37]
	v_mfma_f32_16x16x32_bf16 v[38:41], v[180:183], v[216:219], v[38:41]
	v_mfma_f32_16x16x32_bf16 v[42:45], v[180:183], v[220:223], v[42:45]
	v_mfma_f32_16x16x32_bf16 v[46:49], v[180:183], v[224:227], v[46:49]
	s_waitcnt lgkmcnt(0)
	v_mfma_f32_16x16x32_bf16 v[50:53], v[184:187], v[212:215], v[50:53]
	v_mfma_f32_16x16x32_bf16 v[54:57], v[184:187], v[216:219], v[54:57]
	v_mfma_f32_16x16x32_bf16 v[58:61], v[184:187], v[220:223], v[58:61]
	v_mfma_f32_16x16x32_bf16 v[62:65], v[184:187], v[224:227], v[62:65]
	s_setprio 0
	s_waitcnt vmcnt(6)
	s_barrier
	s_setprio 3
	v_add_u32_e32 v236, s42, v232
	v_add_u32_e32 v237, s42, v233
	ds_read_b128 v[188:191], v236
	ds_read_b128 v[196:199], v236 offset:2048
	ds_read_b128 v[200:203], v236 offset:4096
	ds_read_b128 v[204:207], v236 offset:6144
	ds_read_b128 v[212:215], v237
	ds_read_b128 v[216:219], v237 offset:2048
	ds_read_b128 v[220:223], v237 offset:4096
	ds_read_b128 v[224:227], v237 offset:6144
	s_add_i32 m0, s51, 0x6000
	s_nop 0
	global_load_lds_dwordx4 v229, s[46:47]
	s_add_i32 m0, s51, 0x6400
	s_nop 0
	global_load_lds_dwordx4 v231, s[46:47]
	s_add_i32 m0, s51, 0x8000
	s_nop 0
	global_load_lds_dwordx4 v228, s[48:49]
	s_add_i32 m0, s51, 0x8400
	s_nop 0
	global_load_lds_dwordx4 v230, s[48:49]
	s_add_i32 m0, s51, 0xa000
	s_nop 0
	global_load_lds_dwordx4 v229, s[48:49]
	s_add_i32 m0, s51, 0xa400
	s_nop 0
	global_load_lds_dwordx4 v231, s[48:49]
	s_waitcnt lgkmcnt(7)
	s_setprio 1
	v_mfma_f32_16x16x32_bf16 v[66:69], v[136:139], v[188:191], v[66:69]
	v_mfma_f32_16x16x32_bf16 v[82:85], v[140:143], v[188:191], v[82:85]
	v_mfma_f32_16x16x32_bf16 v[98:101], v[144:147], v[188:191], v[98:101]
	v_mfma_f32_16x16x32_bf16 v[114:117], v[148:151], v[188:191], v[114:117]
	s_waitcnt lgkmcnt(6)
	v_mfma_f32_16x16x32_bf16 v[70:73], v[136:139], v[196:199], v[70:73]
	v_mfma_f32_16x16x32_bf16 v[86:89], v[140:143], v[196:199], v[86:89]
	v_mfma_f32_16x16x32_bf16 v[102:105], v[144:147], v[196:199], v[102:105]
	v_mfma_f32_16x16x32_bf16 v[118:121], v[148:151], v[196:199], v[118:121]
	s_waitcnt lgkmcnt(5)
	v_mfma_f32_16x16x32_bf16 v[74:77], v[136:139], v[200:203], v[74:77]
	v_mfma_f32_16x16x32_bf16 v[90:93], v[140:143], v[200:203], v[90:93]
	v_mfma_f32_16x16x32_bf16 v[106:109], v[144:147], v[200:203], v[106:109]
	v_mfma_f32_16x16x32_bf16 v[122:125], v[148:151], v[200:203], v[122:125]
	s_waitcnt lgkmcnt(4)
	v_mfma_f32_16x16x32_bf16 v[78:81], v[136:139], v[204:207], v[78:81]
	v_mfma_f32_16x16x32_bf16 v[94:97], v[140:143], v[204:207], v[94:97]
	v_mfma_f32_16x16x32_bf16 v[110:113], v[144:147], v[204:207], v[110:113]
	v_mfma_f32_16x16x32_bf16 v[126:129], v[148:151], v[204:207], v[126:129]
	s_waitcnt lgkmcnt(3)
	v_mfma_f32_16x16x32_bf16 v[66:69], v[172:175], v[212:215], v[66:69]
	v_mfma_f32_16x16x32_bf16 v[82:85], v[176:179], v[212:215], v[82:85]
	v_mfma_f32_16x16x32_bf16 v[98:101], v[180:183], v[212:215], v[98:101]
	v_mfma_f32_16x16x32_bf16 v[114:117], v[184:187], v[212:215], v[114:117]
	s_waitcnt lgkmcnt(2)
	v_mfma_f32_16x16x32_bf16 v[70:73], v[172:175], v[216:219], v[70:73]
	v_mfma_f32_16x16x32_bf16 v[86:89], v[176:179], v[216:219], v[86:89]
	v_mfma_f32_16x16x32_bf16 v[102:105], v[180:183], v[216:219], v[102:105]
	v_mfma_f32_16x16x32_bf16 v[118:121], v[184:187], v[216:219], v[118:121]
	s_waitcnt lgkmcnt(1)
	v_mfma_f32_16x16x32_bf16 v[74:77], v[172:175], v[220:223], v[74:77]
	v_mfma_f32_16x16x32_bf16 v[90:93], v[176:179], v[220:223], v[90:93]
	v_mfma_f32_16x16x32_bf16 v[106:109], v[180:183], v[220:223], v[106:109]
	v_mfma_f32_16x16x32_bf16 v[122:125], v[184:187], v[220:223], v[122:125]
	s_waitcnt lgkmcnt(0)
	v_mfma_f32_16x16x32_bf16 v[78:81], v[172:175], v[224:227], v[78:81]
	v_mfma_f32_16x16x32_bf16 v[94:97], v[176:179], v[224:227], v[94:97]
	v_mfma_f32_16x16x32_bf16 v[110:113], v[180:183], v[224:227], v[110:113]
	v_mfma_f32_16x16x32_bf16 v[126:129], v[184:187], v[224:227], v[126:129]
	s_setprio 0
	v_add_u32_e32 v228, 0x80, v228
	v_add_u32_e32 v229, 0x80, v229
	v_add_u32_e32 v230, 0x80, v230
	v_add_u32_e32 v231, 0x80, v231
	s_waitcnt vmcnt(4)
	s_barrier
	s_add_i32 s52, s52, 1
	s_cmp_lt_u32 s52, 10
	s_cbranch_scc1 .Lgu2_loop
	s_setprio 3
	v_add_u32_e32 v234, s22, v232
	v_add_u32_e32 v236, s28, v232
	v_add_u32_e32 v235, s22, v233
	v_add_u32_e32 v237, s28, v233
	ds_read_b128 v[136:139], v234
	ds_read_b128 v[188:191], v236
	ds_read_b128 v[196:199], v236 offset:2048
	ds_read_b128 v[200:203], v236 offset:4096
	ds_read_b128 v[204:207], v236 offset:6144
	ds_read_b128 v[140:143], v234 offset:2048
	ds_read_b128 v[144:147], v234 offset:4096
	ds_read_b128 v[148:151], v234 offset:6144
	ds_read_b128 v[172:175], v235
	ds_read_b128 v[212:215], v237
	ds_read_b128 v[216:219], v237 offset:2048
	ds_read_b128 v[220:223], v237 offset:4096
	ds_read_b128 v[224:227], v237 offset:6144
	ds_read_b128 v[176:179], v235 offset:2048
	ds_read_b128 v[180:183], v235 offset:4096
	ds_read_b128 v[184:187], v235 offset:6144
	s_add_i32 m0, s51, 0xc000
	s_nop 0
	global_load_lds_dwordx4 v228, s[44:45]
	s_add_i32 m0, s51, 0xc400
	s_nop 0
	global_load_lds_dwordx4 v230, s[44:45]
	s_add_i32 m0, s51, 0xe000
	s_nop 0
	global_load_lds_dwordx4 v229, s[44:45]
	s_add_i32 m0, s51, 0xe400
	s_nop 0
	global_load_lds_dwordx4 v231, s[44:45]
	s_add_i32 m0, s51, 0x10000
	s_nop 0
	global_load_lds_dwordx4 v228, s[46:47]
	s_add_i32 m0, s51, 0x10400
	s_nop 0
	global_load_lds_dwordx4 v230, s[46:47]
	s_waitcnt lgkmcnt(11)
	s_setprio 1
	v_mfma_f32_16x16x32_bf16 v[2:5], v[136:139], v[188:191], v[2:5]
	v_mfma_f32_16x16x32_bf16 v[6:9], v[136:139], v[196:199], v[6:9]
	v_mfma_f32_16x16x32_bf16 v[10:13], v[136:139], v[200:203], v[10:13]
	v_mfma_f32_16x16x32_bf16 v[14:17], v[136:139], v[204:207], v[14:17]
	s_waitcnt lgkmcnt(10)
	v_mfma_f32_16x16x32_bf16 v[18:21], v[140:143], v[188:191], v[18:21]
	v_mfma_f32_16x16x32_bf16 v[22:25], v[140:143], v[196:199], v[22:25]
	v_mfma_f32_16x16x32_bf16 v[26:29], v[140:143], v[200:203], v[26:29]
	v_mfma_f32_16x16x32_bf16 v[30:33], v[140:143], v[204:207], v[30:33]
	s_waitcnt lgkmcnt(9)
	v_mfma_f32_16x16x32_bf16 v[34:37], v[144:147], v[188:191], v[34:37]
	v_mfma_f32_16x16x32_bf16 v[38:41], v[144:147], v[196:199], v[38:41]
	v_mfma_f32_16x16x32_bf16 v[42:45], v[144:147], v[200:203], v[42:45]
	v_mfma_f32_16x16x32_bf16 v[46:49], v[144:147], v[204:207], v[46:49]
	s_waitcnt lgkmcnt(8)
	v_mfma_f32_16x16x32_bf16 v[50:53], v[148:151], v[188:191], v[50:53]
	v_mfma_f32_16x16x32_bf16 v[54:57], v[148:151], v[196:199], v[54:57]
	v_mfma_f32_16x16x32_bf16 v[58:61], v[148:151], v[200:203], v[58:61]
	v_mfma_f32_16x16x32_bf16 v[62:65], v[148:151], v[204:207], v[62:65]
	s_waitcnt lgkmcnt(3)
	v_mfma_f32_16x16x32_bf16 v[2:5], v[172:175], v[212:215], v[2:5]
	v_mfma_f32_16x16x32_bf16 v[6:9], v[172:175], v[216:219], v[6:9]
	v_mfma_f32_16x16x32_bf16 v[10:13], v[172:175], v[220:223], v[10:13]
	v_mfma_f32_16x16x32_bf16 v[14:17], v[172:175], v[224:227], v[14:17]
	s_waitcnt lgkmcnt(2)
	v_mfma_f32_16x16x32_bf16 v[18:21], v[176:179], v[212:215], v[18:21]
	v_mfma_f32_16x16x32_bf16 v[22:25], v[176:179], v[216:219], v[22:25]
	v_mfma_f32_16x16x32_bf16 v[26:29], v[176:179], v[220:223], v[26:29]
	v_mfma_f32_16x16x32_bf16 v[30:33], v[176:179], v[224:227], v[30:33]
	s_waitcnt lgkmcnt(1)
	v_mfma_f32_16x16x32_bf16 v[34:37], v[180:183], v[212:215], v[34:37]
	v_mfma_f32_16x16x32_bf16 v[38:41], v[180:183], v[216:219], v[38:41]
	v_mfma_f32_16x16x32_bf16 v[42:45], v[180:183], v[220:223], v[42:45]
	v_mfma_f32_16x16x32_bf16 v[46:49], v[180:183], v[224:227], v[46:49]
	s_waitcnt lgkmcnt(0)
	v_mfma_f32_16x16x32_bf16 v[50:53], v[184:187], v[212:215], v[50:53]
	v_mfma_f32_16x16x32_bf16 v[54:57], v[184:187], v[216:219], v[54:57]
	v_mfma_f32_16x16x32_bf16 v[58:61], v[184:187], v[220:223], v[58:61]
	v_mfma_f32_16x16x32_bf16 v[62:65], v[184:187], v[224:227], v[62:65]
	s_setprio 0
	s_waitcnt vmcnt(6)
	s_barrier
	s_setprio 3
	v_add_u32_e32 v236, s40, v232
	v_add_u32_e32 v237, s40, v233
	ds_read_b128 v[188:191], v236
	ds_read_b128 v[196:199], v236 offset:2048
	ds_read_b128 v[200:203], v236 offset:4096
	ds_read_b128 v[204:207], v236 offset:6144
	ds_read_b128 v[212:215], v237
	ds_read_b128 v[216:219], v237 offset:2048
	ds_read_b128 v[220:223], v237 offset:4096
	ds_read_b128 v[224:227], v237 offset:6144
	s_mov_b32 m0, s51
	s_nop 0
	global_load_lds_dwordx4 v229, s[46:47]
	s_add_i32 m0, s51, 0x400
	s_nop 0
	global_load_lds_dwordx4 v231, s[46:47]
	s_add_i32 m0, s51, 0x2000
	s_nop 0
	global_load_lds_dwordx4 v228, s[48:49]
	s_add_i32 m0, s51, 0x2400
	s_nop 0
	global_load_lds_dwordx4 v230, s[48:49]
	s_add_i32 m0, s51, 0x4000
	s_nop 0
	global_load_lds_dwordx4 v229, s[48:49]
	s_add_i32 m0, s51, 0x4400
	s_nop 0
	global_load_lds_dwordx4 v231, s[48:49]
	s_waitcnt lgkmcnt(7)
	s_setprio 1
	v_mfma_f32_16x16x32_bf16 v[66:69], v[136:139], v[188:191], v[66:69]
	v_mfma_f32_16x16x32_bf16 v[82:85], v[140:143], v[188:191], v[82:85]
	v_mfma_f32_16x16x32_bf16 v[98:101], v[144:147], v[188:191], v[98:101]
	v_mfma_f32_16x16x32_bf16 v[114:117], v[148:151], v[188:191], v[114:117]
	s_waitcnt lgkmcnt(6)
	v_mfma_f32_16x16x32_bf16 v[70:73], v[136:139], v[196:199], v[70:73]
	v_mfma_f32_16x16x32_bf16 v[86:89], v[140:143], v[196:199], v[86:89]
	v_mfma_f32_16x16x32_bf16 v[102:105], v[144:147], v[196:199], v[102:105]
	v_mfma_f32_16x16x32_bf16 v[118:121], v[148:151], v[196:199], v[118:121]
	s_waitcnt lgkmcnt(5)
	v_mfma_f32_16x16x32_bf16 v[74:77], v[136:139], v[200:203], v[74:77]
	v_mfma_f32_16x16x32_bf16 v[90:93], v[140:143], v[200:203], v[90:93]
	v_mfma_f32_16x16x32_bf16 v[106:109], v[144:147], v[200:203], v[106:109]
	v_mfma_f32_16x16x32_bf16 v[122:125], v[148:151], v[200:203], v[122:125]
	s_waitcnt lgkmcnt(4)
	v_mfma_f32_16x16x32_bf16 v[78:81], v[136:139], v[204:207], v[78:81]
	v_mfma_f32_16x16x32_bf16 v[94:97], v[140:143], v[204:207], v[94:97]
	v_mfma_f32_16x16x32_bf16 v[110:113], v[144:147], v[204:207], v[110:113]
	v_mfma_f32_16x16x32_bf16 v[126:129], v[148:151], v[204:207], v[126:129]
	s_waitcnt lgkmcnt(3)
	v_mfma_f32_16x16x32_bf16 v[66:69], v[172:175], v[212:215], v[66:69]
	v_mfma_f32_16x16x32_bf16 v[82:85], v[176:179], v[212:215], v[82:85]
	v_mfma_f32_16x16x32_bf16 v[98:101], v[180:183], v[212:215], v[98:101]
	v_mfma_f32_16x16x32_bf16 v[114:117], v[184:187], v[212:215], v[114:117]
	s_waitcnt lgkmcnt(2)
	v_mfma_f32_16x16x32_bf16 v[70:73], v[172:175], v[216:219], v[70:73]
	v_mfma_f32_16x16x32_bf16 v[86:89], v[176:179], v[216:219], v[86:89]
	v_mfma_f32_16x16x32_bf16 v[102:105], v[180:183], v[216:219], v[102:105]
	v_mfma_f32_16x16x32_bf16 v[118:121], v[184:187], v[216:219], v[118:121]
	s_waitcnt lgkmcnt(1)
	v_mfma_f32_16x16x32_bf16 v[74:77], v[172:175], v[220:223], v[74:77]
	v_mfma_f32_16x16x32_bf16 v[90:93], v[176:179], v[220:223], v[90:93]
	v_mfma_f32_16x16x32_bf16 v[106:109], v[180:183], v[220:223], v[106:109]
	v_mfma_f32_16x16x32_bf16 v[122:125], v[184:187], v[220:223], v[122:125]
	s_waitcnt lgkmcnt(0)
	v_mfma_f32_16x16x32_bf16 v[78:81], v[172:175], v[224:227], v[78:81]
	v_mfma_f32_16x16x32_bf16 v[94:97], v[176:179], v[224:227], v[94:97]
	v_mfma_f32_16x16x32_bf16 v[110:113], v[180:183], v[224:227], v[110:113]
	v_mfma_f32_16x16x32_bf16 v[126:129], v[184:187], v[224:227], v[126:129]
	s_setprio 0
	v_add_u32_e32 v228, 0x80, v228
	v_add_u32_e32 v229, 0x80, v229
	v_add_u32_e32 v230, 0x80, v230
	v_add_u32_e32 v231, 0x80, v231
	s_waitcnt vmcnt(4)
	s_barrier
	s_setprio 3
	v_add_u32_e32 v234, s23, v232
	v_add_u32_e32 v236, s29, v232
	v_add_u32_e32 v235, s23, v233
	v_add_u32_e32 v237, s29, v233
	ds_read_b128 v[136:139], v234
	ds_read_b128 v[188:191], v236
	ds_read_b128 v[196:199], v236 offset:2048
	ds_read_b128 v[200:203], v236 offset:4096
	ds_read_b128 v[204:207], v236 offset:6144
	ds_read_b128 v[140:143], v234 offset:2048
	ds_read_b128 v[144:147], v234 offset:4096
	ds_read_b128 v[148:151], v234 offset:6144
	ds_read_b128 v[172:175], v235
	ds_read_b128 v[212:215], v237
	ds_read_b128 v[216:219], v237 offset:2048
	ds_read_b128 v[220:223], v237 offset:4096
	ds_read_b128 v[224:227], v237 offset:6144
	ds_read_b128 v[176:179], v235 offset:2048
	ds_read_b128 v[180:183], v235 offset:4096
	ds_read_b128 v[184:187], v235 offset:6144
	s_waitcnt lgkmcnt(11)
	s_setprio 1
	v_mfma_f32_16x16x32_bf16 v[2:5], v[136:139], v[188:191], v[2:5]
	v_mfma_f32_16x16x32_bf16 v[6:9], v[136:139], v[196:199], v[6:9]
	v_mfma_f32_16x16x32_bf16 v[10:13], v[136:139], v[200:203], v[10:13]
	v_mfma_f32_16x16x32_bf16 v[14:17], v[136:139], v[204:207], v[14:17]
	s_waitcnt lgkmcnt(10)
	v_mfma_f32_16x16x32_bf16 v[18:21], v[140:143], v[188:191], v[18:21]
	v_mfma_f32_16x16x32_bf16 v[22:25], v[140:143], v[196:199], v[22:25]
	v_mfma_f32_16x16x32_bf16 v[26:29], v[140:143], v[200:203], v[26:29]
	v_mfma_f32_16x16x32_bf16 v[30:33], v[140:143], v[204:207], v[30:33]
	s_waitcnt lgkmcnt(9)
	v_mfma_f32_16x16x32_bf16 v[34:37], v[144:147], v[188:191], v[34:37]
	v_mfma_f32_16x16x32_bf16 v[38:41], v[144:147], v[196:199], v[38:41]
	v_mfma_f32_16x16x32_bf16 v[42:45], v[144:147], v[200:203], v[42:45]
	v_mfma_f32_16x16x32_bf16 v[46:49], v[144:147], v[204:207], v[46:49]
	s_waitcnt lgkmcnt(8)
	v_mfma_f32_16x16x32_bf16 v[50:53], v[148:151], v[188:191], v[50:53]
	v_mfma_f32_16x16x32_bf16 v[54:57], v[148:151], v[196:199], v[54:57]
	v_mfma_f32_16x16x32_bf16 v[58:61], v[148:151], v[200:203], v[58:61]
	v_mfma_f32_16x16x32_bf16 v[62:65], v[148:151], v[204:207], v[62:65]
	s_waitcnt lgkmcnt(3)
	v_mfma_f32_16x16x32_bf16 v[2:5], v[172:175], v[212:215], v[2:5]
	v_mfma_f32_16x16x32_bf16 v[6:9], v[172:175], v[216:219], v[6:9]
	v_mfma_f32_16x16x32_bf16 v[10:13], v[172:175], v[220:223], v[10:13]
	v_mfma_f32_16x16x32_bf16 v[14:17], v[172:175], v[224:227], v[14:17]
	s_waitcnt lgkmcnt(2)
	v_mfma_f32_16x16x32_bf16 v[18:21], v[176:179], v[212:215], v[18:21]
	v_mfma_f32_16x16x32_bf16 v[22:25], v[176:179], v[216:219], v[22:25]
	v_mfma_f32_16x16x32_bf16 v[26:29], v[176:179], v[220:223], v[26:29]
	v_mfma_f32_16x16x32_bf16 v[30:33], v[176:179], v[224:227], v[30:33]
	s_waitcnt lgkmcnt(1)
	v_mfma_f32_16x16x32_bf16 v[34:37], v[180:183], v[212:215], v[34:37]
	v_mfma_f32_16x16x32_bf16 v[38:41], v[180:183], v[216:219], v[38:41]
	v_mfma_f32_16x16x32_bf16 v[42:45], v[180:183], v[220:223], v[42:45]
	v_mfma_f32_16x16x32_bf16 v[46:49], v[180:183], v[224:227], v[46:49]
	s_waitcnt lgkmcnt(0)
	v_mfma_f32_16x16x32_bf16 v[50:53], v[184:187], v[212:215], v[50:53]
	v_mfma_f32_16x16x32_bf16 v[54:57], v[184:187], v[216:219], v[54:57]
	v_mfma_f32_16x16x32_bf16 v[58:61], v[184:187], v[220:223], v[58:61]
	v_mfma_f32_16x16x32_bf16 v[62:65], v[184:187], v[224:227], v[62:65]
	s_setprio 0
	s_waitcnt vmcnt(0)
	s_barrier
	s_setprio 3
	v_add_u32_e32 v236, s41, v232
	v_add_u32_e32 v237, s41, v233
	ds_read_b128 v[188:191], v236
	ds_read_b128 v[196:199], v236 offset:2048
	ds_read_b128 v[200:203], v236 offset:4096
	ds_read_b128 v[204:207], v236 offset:6144
	ds_read_b128 v[212:215], v237
	ds_read_b128 v[216:219], v237 offset:2048
	ds_read_b128 v[220:223], v237 offset:4096
	ds_read_b128 v[224:227], v237 offset:6144
	s_waitcnt lgkmcnt(7)
	s_setprio 1
	v_mfma_f32_16x16x32_bf16 v[66:69], v[136:139], v[188:191], v[66:69]
	v_mfma_f32_16x16x32_bf16 v[82:85], v[140:143], v[188:191], v[82:85]
	v_mfma_f32_16x16x32_bf16 v[98:101], v[144:147], v[188:191], v[98:101]
	v_mfma_f32_16x16x32_bf16 v[114:117], v[148:151], v[188:191], v[114:117]
	s_waitcnt lgkmcnt(6)
	v_mfma_f32_16x16x32_bf16 v[70:73], v[136:139], v[196:199], v[70:73]
	v_mfma_f32_16x16x32_bf16 v[86:89], v[140:143], v[196:199], v[86:89]
	v_mfma_f32_16x16x32_bf16 v[102:105], v[144:147], v[196:199], v[102:105]
	v_mfma_f32_16x16x32_bf16 v[118:121], v[148:151], v[196:199], v[118:121]
	s_waitcnt lgkmcnt(5)
	v_mfma_f32_16x16x32_bf16 v[74:77], v[136:139], v[200:203], v[74:77]
	v_mfma_f32_16x16x32_bf16 v[90:93], v[140:143], v[200:203], v[90:93]
	v_mfma_f32_16x16x32_bf16 v[106:109], v[144:147], v[200:203], v[106:109]
	v_mfma_f32_16x16x32_bf16 v[122:125], v[148:151], v[200:203], v[122:125]
	s_waitcnt lgkmcnt(4)
	v_mfma_f32_16x16x32_bf16 v[78:81], v[136:139], v[204:207], v[78:81]
	v_mfma_f32_16x16x32_bf16 v[94:97], v[140:143], v[204:207], v[94:97]
	v_mfma_f32_16x16x32_bf16 v[110:113], v[144:147], v[204:207], v[110:113]
	v_mfma_f32_16x16x32_bf16 v[126:129], v[148:151], v[204:207], v[126:129]
	s_waitcnt lgkmcnt(3)
	v_mfma_f32_16x16x32_bf16 v[66:69], v[172:175], v[212:215], v[66:69]
	v_mfma_f32_16x16x32_bf16 v[82:85], v[176:179], v[212:215], v[82:85]
	v_mfma_f32_16x16x32_bf16 v[98:101], v[180:183], v[212:215], v[98:101]
	v_mfma_f32_16x16x32_bf16 v[114:117], v[184:187], v[212:215], v[114:117]
	s_waitcnt lgkmcnt(2)
	v_mfma_f32_16x16x32_bf16 v[70:73], v[172:175], v[216:219], v[70:73]
	v_mfma_f32_16x16x32_bf16 v[86:89], v[176:179], v[216:219], v[86:89]
	v_mfma_f32_16x16x32_bf16 v[102:105], v[180:183], v[216:219], v[102:105]
	v_mfma_f32_16x16x32_bf16 v[118:121], v[184:187], v[216:219], v[118:121]
	s_waitcnt lgkmcnt(1)
	v_mfma_f32_16x16x32_bf16 v[74:77], v[172:175], v[220:223], v[74:77]
	v_mfma_f32_16x16x32_bf16 v[90:93], v[176:179], v[220:223], v[90:93]
	v_mfma_f32_16x16x32_bf16 v[106:109], v[180:183], v[220:223], v[106:109]
	v_mfma_f32_16x16x32_bf16 v[122:125], v[184:187], v[220:223], v[122:125]
	s_waitcnt lgkmcnt(0)
	v_mfma_f32_16x16x32_bf16 v[78:81], v[172:175], v[224:227], v[78:81]
	v_mfma_f32_16x16x32_bf16 v[94:97], v[176:179], v[224:227], v[94:97]
	v_mfma_f32_16x16x32_bf16 v[110:113], v[180:183], v[224:227], v[110:113]
	v_mfma_f32_16x16x32_bf16 v[126:129], v[184:187], v[224:227], v[126:129]
	s_setprio 0
	s_nop 7
	s_barrier
	s_setprio 2
	s_mul_i32 s43, s53, 0x2c80
	s_add_i32 s43, s43, s54
	s_add_i32 s55, s55, 1
	s_cmp_lt_u32 s55, 5
	s_cbranch_scc0 .Lgu2_nonext
	s_load_dwordx2 s[44:45], s[12:13], 0x160
	s_load_dwordx2 s[46:47], s[12:13], 0x130
	s_bfe_u32 s53, s21, 0x30006
	s_lshl_b32 s53, s53, 3
	s_and_b32 s56, s21, 7
	s_or_b32 s53, s53, s56
	s_lshl_b32 s53, s53, 7
	s_bfe_u32 s54, s21, 0x30003
	s_lshl_b32 s56, s55, 4
	s_add_i32 s54, s54, s56
	s_lshl_b32 s54, s54, 7
	v_lshrrev_b32_e32 v196, 6, v131
	v_and_b32_e32 v197, 63, v131
	s_nop 0
	v_readfirstlane_b32 s50, v196
	v_lshrrev_b32_e32 v196, 3, v197
	v_lshrrev_b32_e32 v198, 4, v197
	v_and_b32_e32 v199, 7, v197
	s_movk_i32 s56, 0x1080
	v_xor_b32_e32 v200, v199, v198
	v_lshlrev_b32_e32 v200, 4, v200
	v_mad_u32_u24 v228, v196, s56, v200
	v_or_b32_e32 v198, 4, v198
	v_xor_b32_e32 v200, v199, v198
	v_lshlrev_b32_e32 v200, 4, v200
	v_add_u32_e32 v196, 8, v196
	v_mad_u32_u24 v230, v196, s56, v200
	v_add_u32_e32 v229, 0x42000, v228
	v_add_u32_e32 v231, 0x42000, v230
	v_and_b32_e32 v196, 15, v197
	v_lshrrev_b32_e32 v198, 4, v197
	v_bfe_u32 v199, v197, 1, 3
	v_xor_b32_e32 v199, v198, v199
	v_lshlrev_b32_e32 v199, 4, v199
	v_lshl_or_b32 v232, v196, 7, v199
	v_xor_b32_e32 v233, 64, v232
	s_lshr_b32 s56, s50, 1
	s_and_b32 s57, s50, 1
	s_mul_i32 s0, s56, 64*528
	s_lshl_b32 s52, s57, 8
	s_add_i32 s0, s0, s52
	s_add_i32 s0, s0, 16
	v_mul_u32_u24_e32 v198, 4*528, v198
	v_lshl_add_u32 v198, v196, 2, v198
	v_add_u32_e32 v238, s0, v198
	s_add_i32 s22, s56, 0
	s_lshl_b32 s22, s22, 13
	s_add_i32 s22, s22, 16
	s_add_i32 s28, s57, 2
	s_lshl_b32 s28, s28, 13
	s_add_i32 s28, s28, 16
	s_add_i32 s40, s57, 4
	s_lshl_b32 s40, s40, 13
	s_add_i32 s40, s40, 16
	s_add_i32 s23, s56, 6
	s_lshl_b32 s23, s23, 13
	s_add_i32 s23, s23, 16
	s_add_i32 s29, s57, 8
	s_cmp_ge_u32 s29, 9
	s_cselect_b32 s0, 9, 0
	s_sub_i32 s29, s29, s0
	s_lshl_b32 s29, s29, 13
	s_add_i32 s29, s29, 16
	s_add_i32 s41, s57, 1
	s_lshl_b32 s41, s41, 13
	s_add_i32 s41, s41, 16
	s_add_i32 s24, s56, 3
	s_lshl_b32 s24, s24, 13
	s_add_i32 s24, s24, 16
	s_add_i32 s30, s57, 5
	s_lshl_b32 s30, s30, 13
	s_add_i32 s30, s30, 16
	s_add_i32 s42, s57, 7
	s_lshl_b32 s42, s42, 13
	s_add_i32 s42, s42, 16
	s_lshl_b32 s56, s50, 4
	s_add_i32 s57, s53, s56
	s_add_i32 s56, s54, s56
	s_mul_i32 s57, s57, 0x1080
	s_mul_i32 s56, s56, 0x1080
	s_waitcnt lgkmcnt(0)
	s_add_u32 s44, s44, s57
	s_addc_u32 s45, s45, 0
	s_add_u32 s46, s46, s56
	s_addc_u32 s47, s47, 0
	s_add_u32 s48, s46, 0x420000
	s_addc_u32 s49, s47, 0
	s_lshl_b32 s51, s50, 11
	s_add_i32 s51, s51, 16
	s_mov_b32 m0, s51
	s_nop 0
	global_load_lds_dwordx4 v228, s[44:45]
	s_add_i32 m0, s51, 0x400
	s_nop 0
	global_load_lds_dwordx4 v230, s[44:45]
	s_add_i32 m0, s51, 0x2000
	s_nop 0
	global_load_lds_dwordx4 v229, s[44:45]
	s_add_i32 m0, s51, 0x2400
	s_nop 0
	global_load_lds_dwordx4 v231, s[44:45]
	s_add_i32 m0, s51, 0x4000
	s_nop 0
	global_load_lds_dwordx4 v228, s[46:47]
	s_add_i32 m0, s51, 0x4400
	s_nop 0
	global_load_lds_dwordx4 v230, s[46:47]
	s_add_i32 m0, s51, 0x6000
	s_nop 0
	global_load_lds_dwordx4 v229, s[46:47]
	s_add_i32 m0, s51, 0x6400
	s_nop 0
	global_load_lds_dwordx4 v231, s[46:47]
	s_add_i32 m0, s51, 0x8000
	s_nop 0
	global_load_lds_dwordx4 v228, s[48:49]
	s_add_i32 m0, s51, 0x8400
	s_nop 0
	global_load_lds_dwordx4 v230, s[48:49]
	s_add_i32 m0, s51, 0xa000
	s_nop 0
	global_load_lds_dwordx4 v229, s[48:49]
	s_add_i32 m0, s51, 0xa400
	s_nop 0
	global_load_lds_dwordx4 v231, s[48:49]
	v_add_u32_e32 v228, 0x80, v228
	v_add_u32_e32 v229, 0x80, v229
	v_add_u32_e32 v230, 0x80, v230
	v_add_u32_e32 v231, 0x80, v231

.Lgu2_done:
	s_setprio 0
	s_cmpk_gt_i32 s60, 0x1ff
	s_cbranch_scc1 .LBB0_97
	s_add_i32 s20, s60, 0x1400
	s_lshl_b32 s8, s20, 7
	s_branch .LBB0_93

.Lres1_loop:
	s_setprio 3
	v_add_u32_e32 v234, s22, v232
	v_add_u32_e32 v236, s28, v232
	v_add_u32_e32 v235, s22, v233
	v_add_u32_e32 v237, s28, v233
	ds_read_b128 v[136:139], v234
	ds_read_b128 v[188:191], v236
	ds_read_b128 v[196:199], v236 offset:2048
	ds_read_b128 v[200:203], v236 offset:4096
	ds_read_b128 v[204:207], v236 offset:6144
	ds_read_b128 v[140:143], v234 offset:2048
	ds_read_b128 v[144:147], v234 offset:4096
	ds_read_b128 v[148:151], v234 offset:6144
	ds_read_b128 v[172:175], v235
	ds_read_b128 v[212:215], v237
	ds_read_b128 v[216:219], v237 offset:2048
	ds_read_b128 v[220:223], v237 offset:4096
	ds_read_b128 v[224:227], v237 offset:6144
	ds_read_b128 v[176:179], v235 offset:2048
	ds_read_b128 v[180:183], v235 offset:4096
	ds_read_b128 v[184:187], v235 offset:6144
	s_add_i32 m0, s51, 0xc000
	s_nop 0
	global_load_lds_dwordx4 v228, s[44:45]
	s_add_i32 m0, s51, 0xc400
	s_nop 0
	global_load_lds_dwordx4 v230, s[44:45]
	s_add_i32 m0, s51, 0xe000
	s_nop 0
	global_load_lds_dwordx4 v229, s[44:45]
	s_add_i32 m0, s51, 0xe400
	s_nop 0
	global_load_lds_dwordx4 v231, s[44:45]
	s_add_i32 m0, s51, 0x10000
	s_nop 0
	global_load_lds_dwordx4 v228, s[46:47]
	s_add_i32 m0, s51, 0x10400
	s_nop 0
	global_load_lds_dwordx4 v230, s[46:47]
	s_waitcnt lgkmcnt(11)
	s_setprio 1
	v_mfma_f32_16x16x32_bf16 v[2:5], v[136:139], v[188:191], v[2:5]
	v_mfma_f32_16x16x32_bf16 v[6:9], v[136:139], v[196:199], v[6:9]
	v_mfma_f32_16x16x32_bf16 v[10:13], v[136:139], v[200:203], v[10:13]
	v_mfma_f32_16x16x32_bf16 v[14:17], v[136:139], v[204:207], v[14:17]
	s_waitcnt lgkmcnt(10)
	v_mfma_f32_16x16x32_bf16 v[18:21], v[140:143], v[188:191], v[18:21]
	v_mfma_f32_16x16x32_bf16 v[22:25], v[140:143], v[196:199], v[22:25]
	v_mfma_f32_16x16x32_bf16 v[26:29], v[140:143], v[200:203], v[26:29]
	v_mfma_f32_16x16x32_bf16 v[30:33], v[140:143], v[204:207], v[30:33]
	s_waitcnt lgkmcnt(9)
	v_mfma_f32_16x16x32_bf16 v[34:37], v[144:147], v[188:191], v[34:37]
	v_mfma_f32_16x16x32_bf16 v[38:41], v[144:147], v[196:199], v[38:41]
	v_mfma_f32_16x16x32_bf16 v[42:45], v[144:147], v[200:203], v[42:45]
	v_mfma_f32_16x16x32_bf16 v[46:49], v[144:147], v[204:207], v[46:49]
	s_waitcnt lgkmcnt(8)
	v_mfma_f32_16x16x32_bf16 v[50:53], v[148:151], v[188:191], v[50:53]
	v_mfma_f32_16x16x32_bf16 v[54:57], v[148:151], v[196:199], v[54:57]
	v_mfma_f32_16x16x32_bf16 v[58:61], v[148:151], v[200:203], v[58:61]
	v_mfma_f32_16x16x32_bf16 v[62:65], v[148:151], v[204:207], v[62:65]
	s_waitcnt lgkmcnt(3)
	v_mfma_f32_16x16x32_bf16 v[2:5], v[172:175], v[212:215], v[2:5]
	v_mfma_f32_16x16x32_bf16 v[6:9], v[172:175], v[216:219], v[6:9]
	v_mfma_f32_16x16x32_bf16 v[10:13], v[172:175], v[220:223], v[10:13]
	v_mfma_f32_16x16x32_bf16 v[14:17], v[172:175], v[224:227], v[14:17]
	s_waitcnt lgkmcnt(2)
	v_mfma_f32_16x16x32_bf16 v[18:21], v[176:179], v[212:215], v[18:21]
	v_mfma_f32_16x16x32_bf16 v[22:25], v[176:179], v[216:219], v[22:25]
	v_mfma_f32_16x16x32_bf16 v[26:29], v[176:179], v[220:223], v[26:29]
	v_mfma_f32_16x16x32_bf16 v[30:33], v[176:179], v[224:227], v[30:33]
	s_waitcnt lgkmcnt(1)
	v_mfma_f32_16x16x32_bf16 v[34:37], v[180:183], v[212:215], v[34:37]
	v_mfma_f32_16x16x32_bf16 v[38:41], v[180:183], v[216:219], v[38:41]
	v_mfma_f32_16x16x32_bf16 v[42:45], v[180:183], v[220:223], v[42:45]
	v_mfma_f32_16x16x32_bf16 v[46:49], v[180:183], v[224:227], v[46:49]
	s_waitcnt lgkmcnt(0)
	v_mfma_f32_16x16x32_bf16 v[50:53], v[184:187], v[212:215], v[50:53]
	v_mfma_f32_16x16x32_bf16 v[54:57], v[184:187], v[216:219], v[54:57]
	v_mfma_f32_16x16x32_bf16 v[58:61], v[184:187], v[220:223], v[58:61]
	v_mfma_f32_16x16x32_bf16 v[62:65], v[184:187], v[224:227], v[62:65]
	s_setprio 0
	s_waitcnt vmcnt(6)
	s_barrier
	s_setprio 3
	v_add_u32_e32 v236, s40, v232
	v_add_u32_e32 v237, s40, v233
	ds_read_b128 v[188:191], v236
	ds_read_b128 v[196:199], v236 offset:2048
	ds_read_b128 v[200:203], v236 offset:4096
	ds_read_b128 v[204:207], v236 offset:6144
	ds_read_b128 v[212:215], v237
	ds_read_b128 v[216:219], v237 offset:2048
	ds_read_b128 v[220:223], v237 offset:4096
	ds_read_b128 v[224:227], v237 offset:6144
	s_mov_b32 m0, s51
	s_nop 0
	global_load_lds_dwordx4 v229, s[46:47]
	s_add_i32 m0, s51, 0x400
	s_nop 0
	global_load_lds_dwordx4 v231, s[46:47]
	s_add_i32 m0, s51, 0x2000
	s_nop 0
	global_load_lds_dwordx4 v228, s[48:49]
	s_add_i32 m0, s51, 0x2400
	s_nop 0
	global_load_lds_dwordx4 v230, s[48:49]
	s_add_i32 m0, s51, 0x4000
	s_nop 0
	global_load_lds_dwordx4 v229, s[48:49]
	s_add_i32 m0, s51, 0x4400
	s_nop 0
	global_load_lds_dwordx4 v231, s[48:49]
	s_waitcnt lgkmcnt(7)
	s_setprio 1
	v_mfma_f32_16x16x32_bf16 v[66:69], v[136:139], v[188:191], v[66:69]
	v_mfma_f32_16x16x32_bf16 v[82:85], v[140:143], v[188:191], v[82:85]
	v_mfma_f32_16x16x32_bf16 v[98:101], v[144:147], v[188:191], v[98:101]
	v_mfma_f32_16x16x32_bf16 v[114:117], v[148:151], v[188:191], v[114:117]
	s_waitcnt lgkmcnt(6)
	v_mfma_f32_16x16x32_bf16 v[70:73], v[136:139], v[196:199], v[70:73]
	v_mfma_f32_16x16x32_bf16 v[86:89], v[140:143], v[196:199], v[86:89]
	v_mfma_f32_16x16x32_bf16 v[102:105], v[144:147], v[196:199], v[102:105]
	v_mfma_f32_16x16x32_bf16 v[118:121], v[148:151], v[196:199], v[118:121]
	s_waitcnt lgkmcnt(5)
	v_mfma_f32_16x16x32_bf16 v[74:77], v[136:139], v[200:203], v[74:77]
	v_mfma_f32_16x16x32_bf16 v[90:93], v[140:143], v[200:203], v[90:93]
	v_mfma_f32_16x16x32_bf16 v[106:109], v[144:147], v[200:203], v[106:109]
	v_mfma_f32_16x16x32_bf16 v[122:125], v[148:151], v[200:203], v[122:125]
	s_waitcnt lgkmcnt(4)
	v_mfma_f32_16x16x32_bf16 v[78:81], v[136:139], v[204:207], v[78:81]
	v_mfma_f32_16x16x32_bf16 v[94:97], v[140:143], v[204:207], v[94:97]
	v_mfma_f32_16x16x32_bf16 v[110:113], v[144:147], v[204:207], v[110:113]
	v_mfma_f32_16x16x32_bf16 v[126:129], v[148:151], v[204:207], v[126:129]
	s_waitcnt lgkmcnt(3)
	v_mfma_f32_16x16x32_bf16 v[66:69], v[172:175], v[212:215], v[66:69]
	v_mfma_f32_16x16x32_bf16 v[82:85], v[176:179], v[212:215], v[82:85]
	v_mfma_f32_16x16x32_bf16 v[98:101], v[180:183], v[212:215], v[98:101]
	v_mfma_f32_16x16x32_bf16 v[114:117], v[184:187], v[212:215], v[114:117]
	s_waitcnt lgkmcnt(2)
	v_mfma_f32_16x16x32_bf16 v[70:73], v[172:175], v[216:219], v[70:73]
	v_mfma_f32_16x16x32_bf16 v[86:89], v[176:179], v[216:219], v[86:89]
	v_mfma_f32_16x16x32_bf16 v[102:105], v[180:183], v[216:219], v[102:105]
	v_mfma_f32_16x16x32_bf16 v[118:121], v[184:187], v[216:219], v[118:121]
	s_waitcnt lgkmcnt(1)
	v_mfma_f32_16x16x32_bf16 v[74:77], v[172:175], v[220:223], v[74:77]
	v_mfma_f32_16x16x32_bf16 v[90:93], v[176:179], v[220:223], v[90:93]
	v_mfma_f32_16x16x32_bf16 v[106:109], v[180:183], v[220:223], v[106:109]
	v_mfma_f32_16x16x32_bf16 v[122:125], v[184:187], v[220:223], v[122:125]
	s_waitcnt lgkmcnt(0)
	v_mfma_f32_16x16x32_bf16 v[78:81], v[172:175], v[224:227], v[78:81]
	v_mfma_f32_16x16x32_bf16 v[94:97], v[176:179], v[224:227], v[94:97]
	v_mfma_f32_16x16x32_bf16 v[110:113], v[180:183], v[224:227], v[110:113]
	v_mfma_f32_16x16x32_bf16 v[126:129], v[184:187], v[224:227], v[126:129]
	s_setprio 0
	v_add_u32_e32 v228, 0x80, v228
	v_add_u32_e32 v229, 0x80, v229
	v_add_u32_e32 v230, 0x80, v230
	v_add_u32_e32 v231, 0x80, v231
	s_waitcnt vmcnt(4)
	s_barrier
	s_setprio 3
	v_add_u32_e32 v234, s23, v232
	v_add_u32_e32 v236, s29, v232
	v_add_u32_e32 v235, s23, v233
	v_add_u32_e32 v237, s29, v233
	ds_read_b128 v[136:139], v234
	ds_read_b128 v[188:191], v236
	ds_read_b128 v[196:199], v236 offset:2048
	ds_read_b128 v[200:203], v236 offset:4096
	ds_read_b128 v[204:207], v236 offset:6144
	ds_read_b128 v[140:143], v234 offset:2048
	ds_read_b128 v[144:147], v234 offset:4096
	ds_read_b128 v[148:151], v234 offset:6144
	ds_read_b128 v[172:175], v235
	ds_read_b128 v[212:215], v237
	ds_read_b128 v[216:219], v237 offset:2048
	ds_read_b128 v[220:223], v237 offset:4096
	ds_read_b128 v[224:227], v237 offset:6144
	ds_read_b128 v[176:179], v235 offset:2048
	ds_read_b128 v[180:183], v235 offset:4096
	ds_read_b128 v[184:187], v235 offset:6144
	s_add_i32 m0, s51, 0x6000
	s_nop 0
	global_load_lds_dwordx4 v228, s[44:45]
	s_add_i32 m0, s51, 0x6400
	s_nop 0
	global_load_lds_dwordx4 v230, s[44:45]
	s_add_i32 m0, s51, 0x8000
	s_nop 0
	global_load_lds_dwordx4 v229, s[44:45]
	s_add_i32 m0, s51, 0x8400
	s_nop 0
	global_load_lds_dwordx4 v231, s[44:45]
	s_add_i32 m0, s51, 0xa000
	s_nop 0
	global_load_lds_dwordx4 v228, s[46:47]
	s_add_i32 m0, s51, 0xa400
	s_nop 0
	global_load_lds_dwordx4 v230, s[46:47]
	s_waitcnt lgkmcnt(11)
	s_setprio 1
	v_mfma_f32_16x16x32_bf16 v[2:5], v[136:139], v[188:191], v[2:5]
	v_mfma_f32_16x16x32_bf16 v[6:9], v[136:139], v[196:199], v[6:9]
	v_mfma_f32_16x16x32_bf16 v[10:13], v[136:139], v[200:203], v[10:13]
	v_mfma_f32_16x16x32_bf16 v[14:17], v[136:139], v[204:207], v[14:17]
	s_waitcnt lgkmcnt(10)
	v_mfma_f32_16x16x32_bf16 v[18:21], v[140:143], v[188:191], v[18:21]
	v_mfma_f32_16x16x32_bf16 v[22:25], v[140:143], v[196:199], v[22:25]
	v_mfma_f32_16x16x32_bf16 v[26:29], v[140:143], v[200:203], v[26:29]
	v_mfma_f32_16x16x32_bf16 v[30:33], v[140:143], v[204:207], v[30:33]
	s_waitcnt lgkmcnt(9)
	v_mfma_f32_16x16x32_bf16 v[34:37], v[144:147], v[188:191], v[34:37]
	v_mfma_f32_16x16x32_bf16 v[38:41], v[144:147], v[196:199], v[38:41]
	v_mfma_f32_16x16x32_bf16 v[42:45], v[144:147], v[200:203], v[42:45]
	v_mfma_f32_16x16x32_bf16 v[46:49], v[144:147], v[204:207], v[46:49]
	s_waitcnt lgkmcnt(8)
	v_mfma_f32_16x16x32_bf16 v[50:53], v[148:151], v[188:191], v[50:53]
	v_mfma_f32_16x16x32_bf16 v[54:57], v[148:151], v[196:199], v[54:57]
	v_mfma_f32_16x16x32_bf16 v[58:61], v[148:151], v[200:203], v[58:61]
	v_mfma_f32_16x16x32_bf16 v[62:65], v[148:151], v[204:207], v[62:65]
	s_waitcnt lgkmcnt(3)
	v_mfma_f32_16x16x32_bf16 v[2:5], v[172:175], v[212:215], v[2:5]
	v_mfma_f32_16x16x32_bf16 v[6:9], v[172:175], v[216:219], v[6:9]
	v_mfma_f32_16x16x32_bf16 v[10:13], v[172:175], v[220:223], v[10:13]
	v_mfma_f32_16x16x32_bf16 v[14:17], v[172:175], v[224:227], v[14:17]
	s_waitcnt lgkmcnt(2)
	v_mfma_f32_16x16x32_bf16 v[18:21], v[176:179], v[212:215], v[18:21]
	v_mfma_f32_16x16x32_bf16 v[22:25], v[176:179], v[216:219], v[22:25]
	v_mfma_f32_16x16x32_bf16 v[26:29], v[176:179], v[220:223], v[26:29]
	v_mfma_f32_16x16x32_bf16 v[30:33], v[176:179], v[224:227], v[30:33]
	s_waitcnt lgkmcnt(1)
	v_mfma_f32_16x16x32_bf16 v[34:37], v[180:183], v[212:215], v[34:37]
	v_mfma_f32_16x16x32_bf16 v[38:41], v[180:183], v[216:219], v[38:41]
	v_mfma_f32_16x16x32_bf16 v[42:45], v[180:183], v[220:223], v[42:45]
	v_mfma_f32_16x16x32_bf16 v[46:49], v[180:183], v[224:227], v[46:49]
	s_waitcnt lgkmcnt(0)
	v_mfma_f32_16x16x32_bf16 v[50:53], v[184:187], v[212:215], v[50:53]
	v_mfma_f32_16x16x32_bf16 v[54:57], v[184:187], v[216:219], v[54:57]
	v_mfma_f32_16x16x32_bf16 v[58:61], v[184:187], v[220:223], v[58:61]
	v_mfma_f32_16x16x32_bf16 v[62:65], v[184:187], v[224:227], v[62:65]
	s_setprio 0
	s_waitcnt vmcnt(6)
	s_barrier
	s_setprio 3
	v_add_u32_e32 v236, s41, v232
	v_add_u32_e32 v237, s41, v233
	ds_read_b128 v[188:191], v236
	ds_read_b128 v[196:199], v236 offset:2048
	ds_read_b128 v[200:203], v236 offset:4096
	ds_read_b128 v[204:207], v236 offset:6144
	ds_read_b128 v[212:215], v237
	ds_read_b128 v[216:219], v237 offset:2048
	ds_read_b128 v[220:223], v237 offset:4096
	ds_read_b128 v[224:227], v237 offset:6144
	s_add_i32 m0, s51, 0xc000
	s_nop 0
	global_load_lds_dwordx4 v229, s[46:47]
	s_add_i32 m0, s51, 0xc400
	s_nop 0
	global_load_lds_dwordx4 v231, s[46:47]
	s_add_i32 m0, s51, 0xe000
	s_nop 0
	global_load_lds_dwordx4 v228, s[48:49]
	s_add_i32 m0, s51, 0xe400
	s_nop 0
	global_load_lds_dwordx4 v230, s[48:49]
	s_add_i32 m0, s51, 0x10000
	s_nop 0
	global_load_lds_dwordx4 v229, s[48:49]
	s_add_i32 m0, s51, 0x10400
	s_nop 0
	global_load_lds_dwordx4 v231, s[48:49]
	s_waitcnt lgkmcnt(7)
	s_setprio 1
	v_mfma_f32_16x16x32_bf16 v[66:69], v[136:139], v[188:191], v[66:69]
	v_mfma_f32_16x16x32_bf16 v[82:85], v[140:143], v[188:191], v[82:85]
	v_mfma_f32_16x16x32_bf16 v[98:101], v[144:147], v[188:191], v[98:101]
	v_mfma_f32_16x16x32_bf16 v[114:117], v[148:151], v[188:191], v[114:117]
	s_waitcnt lgkmcnt(6)
	v_mfma_f32_16x16x32_bf16 v[70:73], v[136:139], v[196:199], v[70:73]
	v_mfma_f32_16x16x32_bf16 v[86:89], v[140:143], v[196:199], v[86:89]
	v_mfma_f32_16x16x32_bf16 v[102:105], v[144:147], v[196:199], v[102:105]
	v_mfma_f32_16x16x32_bf16 v[118:121], v[148:151], v[196:199], v[118:121]
	s_waitcnt lgkmcnt(5)
	v_mfma_f32_16x16x32_bf16 v[74:77], v[136:139], v[200:203], v[74:77]
	v_mfma_f32_16x16x32_bf16 v[90:93], v[140:143], v[200:203], v[90:93]
	v_mfma_f32_16x16x32_bf16 v[106:109], v[144:147], v[200:203], v[106:109]
	v_mfma_f32_16x16x32_bf16 v[122:125], v[148:151], v[200:203], v[122:125]
	s_waitcnt lgkmcnt(4)
	v_mfma_f32_16x16x32_bf16 v[78:81], v[136:139], v[204:207], v[78:81]
	v_mfma_f32_16x16x32_bf16 v[94:97], v[140:143], v[204:207], v[94:97]
	v_mfma_f32_16x16x32_bf16 v[110:113], v[144:147], v[204:207], v[110:113]
	v_mfma_f32_16x16x32_bf16 v[126:129], v[148:151], v[204:207], v[126:129]
	s_waitcnt lgkmcnt(3)
	v_mfma_f32_16x16x32_bf16 v[66:69], v[172:175], v[212:215], v[66:69]
	v_mfma_f32_16x16x32_bf16 v[82:85], v[176:179], v[212:215], v[82:85]
	v_mfma_f32_16x16x32_bf16 v[98:101], v[180:183], v[212:215], v[98:101]
	v_mfma_f32_16x16x32_bf16 v[114:117], v[184:187], v[212:215], v[114:117]
	s_waitcnt lgkmcnt(2)
	v_mfma_f32_16x16x32_bf16 v[70:73], v[172:175], v[216:219], v[70:73]
	v_mfma_f32_16x16x32_bf16 v[86:89], v[176:179], v[216:219], v[86:89]
	v_mfma_f32_16x16x32_bf16 v[102:105], v[180:183], v[216:219], v[102:105]
	v_mfma_f32_16x16x32_bf16 v[118:121], v[184:187], v[216:219], v[118:121]
	s_waitcnt lgkmcnt(1)
	v_mfma_f32_16x16x32_bf16 v[74:77], v[172:175], v[220:223], v[74:77]
	v_mfma_f32_16x16x32_bf16 v[90:93], v[176:179], v[220:223], v[90:93]
	v_mfma_f32_16x16x32_bf16 v[106:109], v[180:183], v[220:223], v[106:109]
	v_mfma_f32_16x16x32_bf16 v[122:125], v[184:187], v[220:223], v[122:125]
	s_waitcnt lgkmcnt(0)
	v_mfma_f32_16x16x32_bf16 v[78:81], v[172:175], v[224:227], v[78:81]
	v_mfma_f32_16x16x32_bf16 v[94:97], v[176:179], v[224:227], v[94:97]
	v_mfma_f32_16x16x32_bf16 v[110:113], v[180:183], v[224:227], v[110:113]
	v_mfma_f32_16x16x32_bf16 v[126:129], v[184:187], v[224:227], v[126:129]
	s_setprio 0
	v_add_u32_e32 v228, 0x80, v228
	v_add_u32_e32 v229, 0x80, v229
	v_add_u32_e32 v230, 0x80, v230
	v_add_u32_e32 v231, 0x80, v231
	s_waitcnt vmcnt(4)
	s_barrier
	s_setprio 3
	v_add_u32_e32 v234, s24, v232
	v_add_u32_e32 v236, s30, v232
	v_add_u32_e32 v235, s24, v233
	v_add_u32_e32 v237, s30, v233
	ds_read_b128 v[136:139], v234
	ds_read_b128 v[188:191], v236
	ds_read_b128 v[196:199], v236 offset:2048
	ds_read_b128 v[200:203], v236 offset:4096
	ds_read_b128 v[204:207], v236 offset:6144
	ds_read_b128 v[140:143], v234 offset:2048
	ds_read_b128 v[144:147], v234 offset:4096
	ds_read_b128 v[148:151], v234 offset:6144
	ds_read_b128 v[172:175], v235
	ds_read_b128 v[212:215], v237
	ds_read_b128 v[216:219], v237 offset:2048
	ds_read_b128 v[220:223], v237 offset:4096
	ds_read_b128 v[224:227], v237 offset:6144
	ds_read_b128 v[176:179], v235 offset:2048
	ds_read_b128 v[180:183], v235 offset:4096
	ds_read_b128 v[184:187], v235 offset:6144
	s_mov_b32 m0, s51
	s_nop 0
	global_load_lds_dwordx4 v228, s[44:45]
	s_add_i32 m0, s51, 0x400
	s_nop 0
	global_load_lds_dwordx4 v230, s[44:45]
	s_add_i32 m0, s51, 0x2000
	s_nop 0
	global_load_lds_dwordx4 v229, s[44:45]
	s_add_i32 m0, s51, 0x2400
	s_nop 0
	global_load_lds_dwordx4 v231, s[44:45]
	s_add_i32 m0, s51, 0x4000
	s_nop 0
	global_load_lds_dwordx4 v228, s[46:47]
	s_add_i32 m0, s51, 0x4400
	s_nop 0
	global_load_lds_dwordx4 v230, s[46:47]
	s_waitcnt lgkmcnt(11)
	s_setprio 1
	v_mfma_f32_16x16x32_bf16 v[2:5], v[136:139], v[188:191], v[2:5]
	v_mfma_f32_16x16x32_bf16 v[6:9], v[136:139], v[196:199], v[6:9]
	v_mfma_f32_16x16x32_bf16 v[10:13], v[136:139], v[200:203], v[10:13]
	v_mfma_f32_16x16x32_bf16 v[14:17], v[136:139], v[204:207], v[14:17]
	s_waitcnt lgkmcnt(10)
	v_mfma_f32_16x16x32_bf16 v[18:21], v[140:143], v[188:191], v[18:21]
	v_mfma_f32_16x16x32_bf16 v[22:25], v[140:143], v[196:199], v[22:25]
	v_mfma_f32_16x16x32_bf16 v[26:29], v[140:143], v[200:203], v[26:29]
	v_mfma_f32_16x16x32_bf16 v[30:33], v[140:143], v[204:207], v[30:33]
	s_waitcnt lgkmcnt(9)
	v_mfma_f32_16x16x32_bf16 v[34:37], v[144:147], v[188:191], v[34:37]
	v_mfma_f32_16x16x32_bf16 v[38:41], v[144:147], v[196:199], v[38:41]
	v_mfma_f32_16x16x32_bf16 v[42:45], v[144:147], v[200:203], v[42:45]
	v_mfma_f32_16x16x32_bf16 v[46:49], v[144:147], v[204:207], v[46:49]
	s_waitcnt lgkmcnt(8)
	v_mfma_f32_16x16x32_bf16 v[50:53], v[148:151], v[188:191], v[50:53]
	v_mfma_f32_16x16x32_bf16 v[54:57], v[148:151], v[196:199], v[54:57]
	v_mfma_f32_16x16x32_bf16 v[58:61], v[148:151], v[200:203], v[58:61]
	v_mfma_f32_16x16x32_bf16 v[62:65], v[148:151], v[204:207], v[62:65]
	s_waitcnt lgkmcnt(3)
	v_mfma_f32_16x16x32_bf16 v[2:5], v[172:175], v[212:215], v[2:5]
	v_mfma_f32_16x16x32_bf16 v[6:9], v[172:175], v[216:219], v[6:9]
	v_mfma_f32_16x16x32_bf16 v[10:13], v[172:175], v[220:223], v[10:13]
	v_mfma_f32_16x16x32_bf16 v[14:17], v[172:175], v[224:227], v[14:17]
	s_waitcnt lgkmcnt(2)
	v_mfma_f32_16x16x32_bf16 v[18:21], v[176:179], v[212:215], v[18:21]
	v_mfma_f32_16x16x32_bf16 v[22:25], v[176:179], v[216:219], v[22:25]
	v_mfma_f32_16x16x32_bf16 v[26:29], v[176:179], v[220:223], v[26:29]
	v_mfma_f32_16x16x32_bf16 v[30:33], v[176:179], v[224:227], v[30:33]
	s_waitcnt lgkmcnt(1)
	v_mfma_f32_16x16x32_bf16 v[34:37], v[180:183], v[212:215], v[34:37]
	v_mfma_f32_16x16x32_bf16 v[38:41], v[180:183], v[216:219], v[38:41]
	v_mfma_f32_16x16x32_bf16 v[42:45], v[180:183], v[220:223], v[42:45]
	v_mfma_f32_16x16x32_bf16 v[46:49], v[180:183], v[224:227], v[46:49]
	s_waitcnt lgkmcnt(0)
	v_mfma_f32_16x16x32_bf16 v[50:53], v[184:187], v[212:215], v[50:53]
	v_mfma_f32_16x16x32_bf16 v[54:57], v[184:187], v[216:219], v[54:57]
	v_mfma_f32_16x16x32_bf16 v[58:61], v[184:187], v[220:223], v[58:61]
	v_mfma_f32_16x16x32_bf16 v[62:65], v[184:187], v[224:227], v[62:65]
	s_setprio 0
	s_waitcnt vmcnt(6)
	s_barrier
	s_setprio 3
	v_add_u32_e32 v236, s42, v232
	v_add_u32_e32 v237, s42, v233
	ds_read_b128 v[188:191], v236
	ds_read_b128 v[196:199], v236 offset:2048
	ds_read_b128 v[200:203], v236 offset:4096
	ds_read_b128 v[204:207], v236 offset:6144
	ds_read_b128 v[212:215], v237
	ds_read_b128 v[216:219], v237 offset:2048
	ds_read_b128 v[220:223], v237 offset:4096
	ds_read_b128 v[224:227], v237 offset:6144
	s_add_i32 m0, s51, 0x6000
	s_nop 0
	global_load_lds_dwordx4 v229, s[46:47]
	s_add_i32 m0, s51, 0x6400
	s_nop 0
	global_load_lds_dwordx4 v231, s[46:47]
	s_add_i32 m0, s51, 0x8000
	s_nop 0
	global_load_lds_dwordx4 v228, s[48:49]
	s_add_i32 m0, s51, 0x8400
	s_nop 0
	global_load_lds_dwordx4 v230, s[48:49]
	s_add_i32 m0, s51, 0xa000
	s_nop 0
	global_load_lds_dwordx4 v229, s[48:49]
	s_add_i32 m0, s51, 0xa400
	s_nop 0
	global_load_lds_dwordx4 v231, s[48:49]
	s_waitcnt lgkmcnt(7)
	s_setprio 1
	v_mfma_f32_16x16x32_bf16 v[66:69], v[136:139], v[188:191], v[66:69]
	v_mfma_f32_16x16x32_bf16 v[82:85], v[140:143], v[188:191], v[82:85]
	v_mfma_f32_16x16x32_bf16 v[98:101], v[144:147], v[188:191], v[98:101]
	v_mfma_f32_16x16x32_bf16 v[114:117], v[148:151], v[188:191], v[114:117]
	s_waitcnt lgkmcnt(6)
	v_mfma_f32_16x16x32_bf16 v[70:73], v[136:139], v[196:199], v[70:73]
	v_mfma_f32_16x16x32_bf16 v[86:89], v[140:143], v[196:199], v[86:89]
	v_mfma_f32_16x16x32_bf16 v[102:105], v[144:147], v[196:199], v[102:105]
	v_mfma_f32_16x16x32_bf16 v[118:121], v[148:151], v[196:199], v[118:121]
	s_waitcnt lgkmcnt(5)
	v_mfma_f32_16x16x32_bf16 v[74:77], v[136:139], v[200:203], v[74:77]
	v_mfma_f32_16x16x32_bf16 v[90:93], v[140:143], v[200:203], v[90:93]
	v_mfma_f32_16x16x32_bf16 v[106:109], v[144:147], v[200:203], v[106:109]
	v_mfma_f32_16x16x32_bf16 v[122:125], v[148:151], v[200:203], v[122:125]
	s_waitcnt lgkmcnt(4)
	v_mfma_f32_16x16x32_bf16 v[78:81], v[136:139], v[204:207], v[78:81]
	v_mfma_f32_16x16x32_bf16 v[94:97], v[140:143], v[204:207], v[94:97]
	v_mfma_f32_16x16x32_bf16 v[110:113], v[144:147], v[204:207], v[110:113]
	v_mfma_f32_16x16x32_bf16 v[126:129], v[148:151], v[204:207], v[126:129]
	s_waitcnt lgkmcnt(3)
	v_mfma_f32_16x16x32_bf16 v[66:69], v[172:175], v[212:215], v[66:69]
	v_mfma_f32_16x16x32_bf16 v[82:85], v[176:179], v[212:215], v[82:85]
	v_mfma_f32_16x16x32_bf16 v[98:101], v[180:183], v[212:215], v[98:101]
	v_mfma_f32_16x16x32_bf16 v[114:117], v[184:187], v[212:215], v[114:117]
	s_waitcnt lgkmcnt(2)
	v_mfma_f32_16x16x32_bf16 v[70:73], v[172:175], v[216:219], v[70:73]
	v_mfma_f32_16x16x32_bf16 v[86:89], v[176:179], v[216:219], v[86:89]
	v_mfma_f32_16x16x32_bf16 v[102:105], v[180:183], v[216:219], v[102:105]
	v_mfma_f32_16x16x32_bf16 v[118:121], v[184:187], v[216:219], v[118:121]
	s_waitcnt lgkmcnt(1)
	v_mfma_f32_16x16x32_bf16 v[74:77], v[172:175], v[220:223], v[74:77]
	v_mfma_f32_16x16x32_bf16 v[90:93], v[176:179], v[220:223], v[90:93]
	v_mfma_f32_16x16x32_bf16 v[106:109], v[180:183], v[220:223], v[106:109]
	v_mfma_f32_16x16x32_bf16 v[122:125], v[184:187], v[220:223], v[122:125]
	s_waitcnt lgkmcnt(0)
	v_mfma_f32_16x16x32_bf16 v[78:81], v[172:175], v[224:227], v[78:81]
	v_mfma_f32_16x16x32_bf16 v[94:97], v[176:179], v[224:227], v[94:97]
	v_mfma_f32_16x16x32_bf16 v[110:113], v[180:183], v[224:227], v[110:113]
	v_mfma_f32_16x16x32_bf16 v[126:129], v[184:187], v[224:227], v[126:129]
	s_setprio 0
	v_add_u32_e32 v228, 0x80, v228
	v_add_u32_e32 v229, 0x80, v229
	v_add_u32_e32 v230, 0x80, v230
	v_add_u32_e32 v231, 0x80, v231
	s_waitcnt vmcnt(4)
	s_barrier
	s_add_i32 s52, s52, 1
	s_cmp_lt_u32 s52, 10
	s_cbranch_scc1 .Lres1_loop
	s_setprio 3
	v_add_u32_e32 v234, s22, v232
	v_add_u32_e32 v236, s28, v232
	v_add_u32_e32 v235, s22, v233
	v_add_u32_e32 v237, s28, v233
	ds_read_b128 v[136:139], v234
	ds_read_b128 v[188:191], v236
	ds_read_b128 v[196:199], v236 offset:2048
	ds_read_b128 v[200:203], v236 offset:4096
	ds_read_b128 v[204:207], v236 offset:6144
	ds_read_b128 v[140:143], v234 offset:2048
	ds_read_b128 v[144:147], v234 offset:4096
	ds_read_b128 v[148:151], v234 offset:6144
	ds_read_b128 v[172:175], v235
	ds_read_b128 v[212:215], v237
	ds_read_b128 v[216:219], v237 offset:2048
	ds_read_b128 v[220:223], v237 offset:4096
	ds_read_b128 v[224:227], v237 offset:6144
	ds_read_b128 v[176:179], v235 offset:2048
	ds_read_b128 v[180:183], v235 offset:4096
	ds_read_b128 v[184:187], v235 offset:6144
	s_add_i32 m0, s51, 0xc000
	s_nop 0
	global_load_lds_dwordx4 v228, s[44:45]
	s_add_i32 m0, s51, 0xc400
	s_nop 0
	global_load_lds_dwordx4 v230, s[44:45]
	s_add_i32 m0, s51, 0xe000
	s_nop 0
	global_load_lds_dwordx4 v229, s[44:45]
	s_add_i32 m0, s51, 0xe400
	s_nop 0
	global_load_lds_dwordx4 v231, s[44:45]
	s_add_i32 m0, s51, 0x10000
	s_nop 0
	global_load_lds_dwordx4 v228, s[46:47]
	s_add_i32 m0, s51, 0x10400
	s_nop 0
	global_load_lds_dwordx4 v230, s[46:47]
	s_waitcnt lgkmcnt(11)
	s_setprio 1
	v_mfma_f32_16x16x32_bf16 v[2:5], v[136:139], v[188:191], v[2:5]
	v_mfma_f32_16x16x32_bf16 v[6:9], v[136:139], v[196:199], v[6:9]
	v_mfma_f32_16x16x32_bf16 v[10:13], v[136:139], v[200:203], v[10:13]
	v_mfma_f32_16x16x32_bf16 v[14:17], v[136:139], v[204:207], v[14:17]
	s_waitcnt lgkmcnt(10)
	v_mfma_f32_16x16x32_bf16 v[18:21], v[140:143], v[188:191], v[18:21]
	v_mfma_f32_16x16x32_bf16 v[22:25], v[140:143], v[196:199], v[22:25]
	v_mfma_f32_16x16x32_bf16 v[26:29], v[140:143], v[200:203], v[26:29]
	v_mfma_f32_16x16x32_bf16 v[30:33], v[140:143], v[204:207], v[30:33]
	s_waitcnt lgkmcnt(9)
	v_mfma_f32_16x16x32_bf16 v[34:37], v[144:147], v[188:191], v[34:37]
	v_mfma_f32_16x16x32_bf16 v[38:41], v[144:147], v[196:199], v[38:41]
	v_mfma_f32_16x16x32_bf16 v[42:45], v[144:147], v[200:203], v[42:45]
	v_mfma_f32_16x16x32_bf16 v[46:49], v[144:147], v[204:207], v[46:49]
	s_waitcnt lgkmcnt(8)
	v_mfma_f32_16x16x32_bf16 v[50:53], v[148:151], v[188:191], v[50:53]
	v_mfma_f32_16x16x32_bf16 v[54:57], v[148:151], v[196:199], v[54:57]
	v_mfma_f32_16x16x32_bf16 v[58:61], v[148:151], v[200:203], v[58:61]
	v_mfma_f32_16x16x32_bf16 v[62:65], v[148:151], v[204:207], v[62:65]
	s_waitcnt lgkmcnt(3)
	v_mfma_f32_16x16x32_bf16 v[2:5], v[172:175], v[212:215], v[2:5]
	v_mfma_f32_16x16x32_bf16 v[6:9], v[172:175], v[216:219], v[6:9]
	v_mfma_f32_16x16x32_bf16 v[10:13], v[172:175], v[220:223], v[10:13]
	v_mfma_f32_16x16x32_bf16 v[14:17], v[172:175], v[224:227], v[14:17]
	s_waitcnt lgkmcnt(2)
	v_mfma_f32_16x16x32_bf16 v[18:21], v[176:179], v[212:215], v[18:21]
	v_mfma_f32_16x16x32_bf16 v[22:25], v[176:179], v[216:219], v[22:25]
	v_mfma_f32_16x16x32_bf16 v[26:29], v[176:179], v[220:223], v[26:29]
	v_mfma_f32_16x16x32_bf16 v[30:33], v[176:179], v[224:227], v[30:33]
	s_waitcnt lgkmcnt(1)
	v_mfma_f32_16x16x32_bf16 v[34:37], v[180:183], v[212:215], v[34:37]
	v_mfma_f32_16x16x32_bf16 v[38:41], v[180:183], v[216:219], v[38:41]
	v_mfma_f32_16x16x32_bf16 v[42:45], v[180:183], v[220:223], v[42:45]
	v_mfma_f32_16x16x32_bf16 v[46:49], v[180:183], v[224:227], v[46:49]
	s_waitcnt lgkmcnt(0)
	v_mfma_f32_16x16x32_bf16 v[50:53], v[184:187], v[212:215], v[50:53]
	v_mfma_f32_16x16x32_bf16 v[54:57], v[184:187], v[216:219], v[54:57]
	v_mfma_f32_16x16x32_bf16 v[58:61], v[184:187], v[220:223], v[58:61]
	v_mfma_f32_16x16x32_bf16 v[62:65], v[184:187], v[224:227], v[62:65]
	s_setprio 0
	s_waitcnt vmcnt(6)
	s_barrier
	s_setprio 3
	v_add_u32_e32 v236, s40, v232
	v_add_u32_e32 v237, s40, v233
	ds_read_b128 v[188:191], v236
	ds_read_b128 v[196:199], v236 offset:2048
	ds_read_b128 v[200:203], v236 offset:4096
	ds_read_b128 v[204:207], v236 offset:6144
	ds_read_b128 v[212:215], v237
	ds_read_b128 v[216:219], v237 offset:2048
	ds_read_b128 v[220:223], v237 offset:4096
	ds_read_b128 v[224:227], v237 offset:6144
	s_mov_b32 m0, s51
	s_nop 0
	global_load_lds_dwordx4 v229, s[46:47]
	s_add_i32 m0, s51, 0x400
	s_nop 0
	global_load_lds_dwordx4 v231, s[46:47]
	s_add_i32 m0, s51, 0x2000
	s_nop 0
	global_load_lds_dwordx4 v228, s[48:49]
	s_add_i32 m0, s51, 0x2400
	s_nop 0
	global_load_lds_dwordx4 v230, s[48:49]
	s_add_i32 m0, s51, 0x4000
	s_nop 0
	global_load_lds_dwordx4 v229, s[48:49]
	s_add_i32 m0, s51, 0x4400
	s_nop 0
	global_load_lds_dwordx4 v231, s[48:49]
	s_waitcnt lgkmcnt(7)
	s_setprio 1
	v_mfma_f32_16x16x32_bf16 v[66:69], v[136:139], v[188:191], v[66:69]
	v_mfma_f32_16x16x32_bf16 v[82:85], v[140:143], v[188:191], v[82:85]
	v_mfma_f32_16x16x32_bf16 v[98:101], v[144:147], v[188:191], v[98:101]
	v_mfma_f32_16x16x32_bf16 v[114:117], v[148:151], v[188:191], v[114:117]
	s_waitcnt lgkmcnt(6)
	v_mfma_f32_16x16x32_bf16 v[70:73], v[136:139], v[196:199], v[70:73]
	v_mfma_f32_16x16x32_bf16 v[86:89], v[140:143], v[196:199], v[86:89]
	v_mfma_f32_16x16x32_bf16 v[102:105], v[144:147], v[196:199], v[102:105]
	v_mfma_f32_16x16x32_bf16 v[118:121], v[148:151], v[196:199], v[118:121]
	s_waitcnt lgkmcnt(5)
	v_mfma_f32_16x16x32_bf16 v[74:77], v[136:139], v[200:203], v[74:77]
	v_mfma_f32_16x16x32_bf16 v[90:93], v[140:143], v[200:203], v[90:93]
	v_mfma_f32_16x16x32_bf16 v[106:109], v[144:147], v[200:203], v[106:109]
	v_mfma_f32_16x16x32_bf16 v[122:125], v[148:151], v[200:203], v[122:125]
	s_waitcnt lgkmcnt(4)
	v_mfma_f32_16x16x32_bf16 v[78:81], v[136:139], v[204:207], v[78:81]
	v_mfma_f32_16x16x32_bf16 v[94:97], v[140:143], v[204:207], v[94:97]
	v_mfma_f32_16x16x32_bf16 v[110:113], v[144:147], v[204:207], v[110:113]
	v_mfma_f32_16x16x32_bf16 v[126:129], v[148:151], v[204:207], v[126:129]
	s_waitcnt lgkmcnt(3)
	v_mfma_f32_16x16x32_bf16 v[66:69], v[172:175], v[212:215], v[66:69]
	v_mfma_f32_16x16x32_bf16 v[82:85], v[176:179], v[212:215], v[82:85]
	v_mfma_f32_16x16x32_bf16 v[98:101], v[180:183], v[212:215], v[98:101]
	v_mfma_f32_16x16x32_bf16 v[114:117], v[184:187], v[212:215], v[114:117]
	s_waitcnt lgkmcnt(2)
	v_mfma_f32_16x16x32_bf16 v[70:73], v[172:175], v[216:219], v[70:73]
	v_mfma_f32_16x16x32_bf16 v[86:89], v[176:179], v[216:219], v[86:89]
	v_mfma_f32_16x16x32_bf16 v[102:105], v[180:183], v[216:219], v[102:105]
	v_mfma_f32_16x16x32_bf16 v[118:121], v[184:187], v[216:219], v[118:121]
	s_waitcnt lgkmcnt(1)
	v_mfma_f32_16x16x32_bf16 v[74:77], v[172:175], v[220:223], v[74:77]
	v_mfma_f32_16x16x32_bf16 v[90:93], v[176:179], v[220:223], v[90:93]
	v_mfma_f32_16x16x32_bf16 v[106:109], v[180:183], v[220:223], v[106:109]
	v_mfma_f32_16x16x32_bf16 v[122:125], v[184:187], v[220:223], v[122:125]
	s_waitcnt lgkmcnt(0)
	v_mfma_f32_16x16x32_bf16 v[78:81], v[172:175], v[224:227], v[78:81]
	v_mfma_f32_16x16x32_bf16 v[94:97], v[176:179], v[224:227], v[94:97]
	v_mfma_f32_16x16x32_bf16 v[110:113], v[180:183], v[224:227], v[110:113]
	v_mfma_f32_16x16x32_bf16 v[126:129], v[184:187], v[224:227], v[126:129]
	s_setprio 0
	v_add_u32_e32 v228, 0x80, v228
	v_add_u32_e32 v229, 0x80, v229
	v_add_u32_e32 v230, 0x80, v230
	v_add_u32_e32 v231, 0x80, v231
	s_waitcnt vmcnt(4)
	s_barrier
	s_setprio 3
	v_add_u32_e32 v234, s23, v232
	v_add_u32_e32 v236, s29, v232
	v_add_u32_e32 v235, s23, v233
	v_add_u32_e32 v237, s29, v233
	ds_read_b128 v[136:139], v234
	ds_read_b128 v[188:191], v236
	ds_read_b128 v[196:199], v236 offset:2048
	ds_read_b128 v[200:203], v236 offset:4096
	ds_read_b128 v[204:207], v236 offset:6144
	ds_read_b128 v[140:143], v234 offset:2048
	ds_read_b128 v[144:147], v234 offset:4096
	ds_read_b128 v[148:151], v234 offset:6144
	ds_read_b128 v[172:175], v235
	ds_read_b128 v[212:215], v237
	ds_read_b128 v[216:219], v237 offset:2048
	ds_read_b128 v[220:223], v237 offset:4096
	ds_read_b128 v[224:227], v237 offset:6144
	ds_read_b128 v[176:179], v235 offset:2048
	ds_read_b128 v[180:183], v235 offset:4096
	ds_read_b128 v[184:187], v235 offset:6144
	s_waitcnt lgkmcnt(11)
	s_setprio 1
	v_mfma_f32_16x16x32_bf16 v[2:5], v[136:139], v[188:191], v[2:5]
	v_mfma_f32_16x16x32_bf16 v[6:9], v[136:139], v[196:199], v[6:9]
	v_mfma_f32_16x16x32_bf16 v[10:13], v[136:139], v[200:203], v[10:13]
	v_mfma_f32_16x16x32_bf16 v[14:17], v[136:139], v[204:207], v[14:17]
	s_waitcnt lgkmcnt(10)
	v_mfma_f32_16x16x32_bf16 v[18:21], v[140:143], v[188:191], v[18:21]
	v_mfma_f32_16x16x32_bf16 v[22:25], v[140:143], v[196:199], v[22:25]
	v_mfma_f32_16x16x32_bf16 v[26:29], v[140:143], v[200:203], v[26:29]
	v_mfma_f32_16x16x32_bf16 v[30:33], v[140:143], v[204:207], v[30:33]
	s_waitcnt lgkmcnt(9)
	v_mfma_f32_16x16x32_bf16 v[34:37], v[144:147], v[188:191], v[34:37]
	v_mfma_f32_16x16x32_bf16 v[38:41], v[144:147], v[196:199], v[38:41]
	v_mfma_f32_16x16x32_bf16 v[42:45], v[144:147], v[200:203], v[42:45]
	v_mfma_f32_16x16x32_bf16 v[46:49], v[144:147], v[204:207], v[46:49]
	s_waitcnt lgkmcnt(8)
	v_mfma_f32_16x16x32_bf16 v[50:53], v[148:151], v[188:191], v[50:53]
	v_mfma_f32_16x16x32_bf16 v[54:57], v[148:151], v[196:199], v[54:57]
	v_mfma_f32_16x16x32_bf16 v[58:61], v[148:151], v[200:203], v[58:61]
	v_mfma_f32_16x16x32_bf16 v[62:65], v[148:151], v[204:207], v[62:65]
	s_waitcnt lgkmcnt(3)
	v_mfma_f32_16x16x32_bf16 v[2:5], v[172:175], v[212:215], v[2:5]
	v_mfma_f32_16x16x32_bf16 v[6:9], v[172:175], v[216:219], v[6:9]
	v_mfma_f32_16x16x32_bf16 v[10:13], v[172:175], v[220:223], v[10:13]
	v_mfma_f32_16x16x32_bf16 v[14:17], v[172:175], v[224:227], v[14:17]
	s_waitcnt lgkmcnt(2)
	v_mfma_f32_16x16x32_bf16 v[18:21], v[176:179], v[212:215], v[18:21]
	v_mfma_f32_16x16x32_bf16 v[22:25], v[176:179], v[216:219], v[22:25]
	v_mfma_f32_16x16x32_bf16 v[26:29], v[176:179], v[220:223], v[26:29]
	v_mfma_f32_16x16x32_bf16 v[30:33], v[176:179], v[224:227], v[30:33]
	s_waitcnt lgkmcnt(1)
	v_mfma_f32_16x16x32_bf16 v[34:37], v[180:183], v[212:215], v[34:37]
	v_mfma_f32_16x16x32_bf16 v[38:41], v[180:183], v[216:219], v[38:41]
	v_mfma_f32_16x16x32_bf16 v[42:45], v[180:183], v[220:223], v[42:45]
	v_mfma_f32_16x16x32_bf16 v[46:49], v[180:183], v[224:227], v[46:49]
	s_waitcnt lgkmcnt(0)
	v_mfma_f32_16x16x32_bf16 v[50:53], v[184:187], v[212:215], v[50:53]
	v_mfma_f32_16x16x32_bf16 v[54:57], v[184:187], v[216:219], v[54:57]
	v_mfma_f32_16x16x32_bf16 v[58:61], v[184:187], v[220:223], v[58:61]
	v_mfma_f32_16x16x32_bf16 v[62:65], v[184:187], v[224:227], v[62:65]
	s_setprio 0
	s_waitcnt vmcnt(0)
	s_barrier
	s_setprio 3
	v_add_u32_e32 v236, s41, v232
	v_add_u32_e32 v237, s41, v233
	ds_read_b128 v[188:191], v236
	ds_read_b128 v[196:199], v236 offset:2048
	ds_read_b128 v[200:203], v236 offset:4096
	ds_read_b128 v[204:207], v236 offset:6144
	ds_read_b128 v[212:215], v237
	ds_read_b128 v[216:219], v237 offset:2048
	ds_read_b128 v[220:223], v237 offset:4096
	ds_read_b128 v[224:227], v237 offset:6144
	s_waitcnt lgkmcnt(7)
	s_setprio 1
	v_mfma_f32_16x16x32_bf16 v[66:69], v[136:139], v[188:191], v[66:69]
	v_mfma_f32_16x16x32_bf16 v[82:85], v[140:143], v[188:191], v[82:85]
	v_mfma_f32_16x16x32_bf16 v[98:101], v[144:147], v[188:191], v[98:101]
	v_mfma_f32_16x16x32_bf16 v[114:117], v[148:151], v[188:191], v[114:117]
	s_waitcnt lgkmcnt(6)
	v_mfma_f32_16x16x32_bf16 v[70:73], v[136:139], v[196:199], v[70:73]
	v_mfma_f32_16x16x32_bf16 v[86:89], v[140:143], v[196:199], v[86:89]
	v_mfma_f32_16x16x32_bf16 v[102:105], v[144:147], v[196:199], v[102:105]
	v_mfma_f32_16x16x32_bf16 v[118:121], v[148:151], v[196:199], v[118:121]
	s_waitcnt lgkmcnt(5)
	v_mfma_f32_16x16x32_bf16 v[74:77], v[136:139], v[200:203], v[74:77]
	v_mfma_f32_16x16x32_bf16 v[90:93], v[140:143], v[200:203], v[90:93]
	v_mfma_f32_16x16x32_bf16 v[106:109], v[144:147], v[200:203], v[106:109]
	v_mfma_f32_16x16x32_bf16 v[122:125], v[148:151], v[200:203], v[122:125]
	s_waitcnt lgkmcnt(4)
	v_mfma_f32_16x16x32_bf16 v[78:81], v[136:139], v[204:207], v[78:81]
	v_mfma_f32_16x16x32_bf16 v[94:97], v[140:143], v[204:207], v[94:97]
	v_mfma_f32_16x16x32_bf16 v[110:113], v[144:147], v[204:207], v[110:113]
	v_mfma_f32_16x16x32_bf16 v[126:129], v[148:151], v[204:207], v[126:129]
	s_waitcnt lgkmcnt(3)
	v_mfma_f32_16x16x32_bf16 v[66:69], v[172:175], v[212:215], v[66:69]
	v_mfma_f32_16x16x32_bf16 v[82:85], v[176:179], v[212:215], v[82:85]
	v_mfma_f32_16x16x32_bf16 v[98:101], v[180:183], v[212:215], v[98:101]
	v_mfma_f32_16x16x32_bf16 v[114:117], v[184:187], v[212:215], v[114:117]
	s_waitcnt lgkmcnt(2)
	v_mfma_f32_16x16x32_bf16 v[70:73], v[172:175], v[216:219], v[70:73]
	v_mfma_f32_16x16x32_bf16 v[86:89], v[176:179], v[216:219], v[86:89]
	v_mfma_f32_16x16x32_bf16 v[102:105], v[180:183], v[216:219], v[102:105]
	v_mfma_f32_16x16x32_bf16 v[118:121], v[184:187], v[216:219], v[118:121]
	s_waitcnt lgkmcnt(1)
	v_mfma_f32_16x16x32_bf16 v[74:77], v[172:175], v[220:223], v[74:77]
	v_mfma_f32_16x16x32_bf16 v[90:93], v[176:179], v[220:223], v[90:93]
	v_mfma_f32_16x16x32_bf16 v[106:109], v[180:183], v[220:223], v[106:109]
	v_mfma_f32_16x16x32_bf16 v[122:125], v[184:187], v[220:223], v[122:125]
	s_waitcnt lgkmcnt(0)
	v_mfma_f32_16x16x32_bf16 v[78:81], v[172:175], v[224:227], v[78:81]
	v_mfma_f32_16x16x32_bf16 v[94:97], v[176:179], v[224:227], v[94:97]
	v_mfma_f32_16x16x32_bf16 v[110:113], v[180:183], v[224:227], v[110:113]
	v_mfma_f32_16x16x32_bf16 v[126:129], v[184:187], v[224:227], v[126:129]
	s_setprio 0
	s_nop 7
	s_barrier
	s_setprio 2
	s_load_dwordx2 s[44:45], s[12:13], 0x0
	s_load_dwordx2 s[58:59], s[12:13], 0x100
	s_load_dwordx2 s[46:47], s[12:13], 0x160
	s_load_dwordx2 s[48:49], s[12:13], 0x1c8
	v_lshrrev_b32_e32 v241, 5, v131
	v_and_b32_e32 v242, 31, v131
	v_lshlrev_b32_e32 v243, 4, v242
	s_movk_i32 s56, 0x210
	v_mad_u32_u24 v239, v241, s56, v243
	v_add_u32_e32 v239, 16, v239
	v_lshlrev_b32_e32 v240, 13, v241
	v_or_b32_e32 v240, v240, v243
	v_lshlrev_b32_e32 v244, 3, v242
	v_mad_u32_u24 v244, v241, s81, v244
	v_lshlrev_b32_e32 v245, 2, v241
	s_lshl_b32 s56, s53, 13
	s_lshl_b32 s57, s54, 2
	s_add_i32 s56, s56, s57
	s_mul_i32 s57, s53, s81
	s_lshl_b32 s0, s54, 1
	s_add_i32 s57, s57, s0
	s_lshl_b32 s0, s53, 2
	s_waitcnt lgkmcnt(0)
	s_add_u32 s44, s44, s56
	s_addc_u32 s45, s45, 0
	s_add_u32 s58, s58, s56
	s_addc_u32 s59, s59, 0
	s_add_u32 s46, s46, s57
	s_addc_u32 s47, s47, 0
	s_add_u32 s48, s48, s0
	s_addc_u32 s49, s49, 0
	s_mov_b32 s56, s44
	s_mov_b32 s57, s45
	global_load_dwordx4 v[136:139], v240, s[56:57]
	s_add_u32 s56, s56, 0x10000
	s_addc_u32 s57, s57, 0
	global_load_dwordx4 v[140:143], v240, s[56:57]
	s_add_u32 s56, s56, 0x10000
	s_addc_u32 s57, s57, 0
	global_load_dwordx4 v[144:147], v240, s[56:57]
	s_add_u32 s56, s56, 0x10000
	s_addc_u32 s57, s57, 0
	global_load_dwordx4 v[148:151], v240, s[56:57]
	s_add_u32 s56, s56, 0x10000
	s_addc_u32 s57, s57, 0
	global_load_dwordx4 v[172:175], v240, s[56:57]
	s_add_u32 s56, s56, 0x10000
	s_addc_u32 s57, s57, 0
	global_load_dwordx4 v[176:179], v240, s[56:57]
	s_add_u32 s56, s56, 0x10000
	s_addc_u32 s57, s57, 0
	global_load_dwordx4 v[180:183], v240, s[56:57]
	s_add_u32 s56, s56, 0x10000
	s_addc_u32 s57, s57, 0
	global_load_dwordx4 v[184:187], v240, s[56:57]
	s_add_u32 s56, s56, 0x10000
	s_addc_u32 s57, s57, 0
	global_load_dwordx4 v[188:191], v240, s[56:57]
	s_add_u32 s56, s56, 0x10000
	s_addc_u32 s57, s57, 0
	global_load_dwordx4 v[196:199], v240, s[56:57]
	s_add_u32 s56, s56, 0x10000
	s_addc_u32 s57, s57, 0
	global_load_dwordx4 v[200:203], v240, s[56:57]
	s_add_u32 s56, s56, 0x10000
	s_addc_u32 s57, s57, 0
	global_load_dwordx4 v[204:207], v240, s[56:57]
	s_add_u32 s56, s56, 0x10000
	s_addc_u32 s57, s57, 0
	global_load_dwordx4 v[212:215], v240, s[56:57]
	s_add_u32 s56, s56, 0x10000
	s_addc_u32 s57, s57, 0
	global_load_dwordx4 v[216:219], v240, s[56:57]
	s_add_u32 s56, s56, 0x10000
	s_addc_u32 s57, s57, 0
	global_load_dwordx4 v[220:223], v240, s[56:57]
	s_add_u32 s56, s56, 0x10000
	s_addc_u32 s57, s57, 0
	global_load_dwordx4 v[224:227], v240, s[56:57]
	ds_write_b32 v238, v2
	ds_write_b32 v238, v3 offset:528
	ds_write_b32 v238, v4 offset:1056
	ds_write_b32 v238, v5 offset:1584
	ds_write_b32 v238, v6 offset:64
	ds_write_b32 v238, v7 offset:592
	ds_write_b32 v238, v8 offset:1120
	ds_write_b32 v238, v9 offset:1648
	ds_write_b32 v238, v10 offset:128
	ds_write_b32 v238, v11 offset:656
	ds_write_b32 v238, v12 offset:1184
	ds_write_b32 v238, v13 offset:1712
	ds_write_b32 v238, v14 offset:192
	ds_write_b32 v238, v15 offset:720
	ds_write_b32 v238, v16 offset:1248
	ds_write_b32 v238, v17 offset:1776
	ds_write_b32 v238, v18 offset:8448
	ds_write_b32 v238, v19 offset:8976
	ds_write_b32 v238, v20 offset:9504
	ds_write_b32 v238, v21 offset:10032
	ds_write_b32 v238, v22 offset:8512
	ds_write_b32 v238, v23 offset:9040
	ds_write_b32 v238, v24 offset:9568
	ds_write_b32 v238, v25 offset:10096
	ds_write_b32 v238, v26 offset:8576
	ds_write_b32 v238, v27 offset:9104
	ds_write_b32 v238, v28 offset:9632
	ds_write_b32 v238, v29 offset:10160
	ds_write_b32 v238, v30 offset:8640
	ds_write_b32 v238, v31 offset:9168
	ds_write_b32 v238, v32 offset:9696
	ds_write_b32 v238, v33 offset:10224
	ds_write_b32 v238, v34 offset:16896
	ds_write_b32 v238, v35 offset:17424
	ds_write_b32 v238, v36 offset:17952
	ds_write_b32 v238, v37 offset:18480
	ds_write_b32 v238, v38 offset:16960
	ds_write_b32 v238, v39 offset:17488
	ds_write_b32 v238, v40 offset:18016
	ds_write_b32 v238, v41 offset:18544
	ds_write_b32 v238, v42 offset:17024
	ds_write_b32 v238, v43 offset:17552
	ds_write_b32 v238, v44 offset:18080
	ds_write_b32 v238, v45 offset:18608
	ds_write_b32 v238, v46 offset:17088
	ds_write_b32 v238, v47 offset:17616
	ds_write_b32 v238, v48 offset:18144
	ds_write_b32 v238, v49 offset:18672
	ds_write_b32 v238, v50 offset:25344
	ds_write_b32 v238, v51 offset:25872
	ds_write_b32 v238, v52 offset:26400
	ds_write_b32 v238, v53 offset:26928
	ds_write_b32 v238, v54 offset:25408
	ds_write_b32 v238, v55 offset:25936
	ds_write_b32 v238, v56 offset:26464
	ds_write_b32 v238, v57 offset:26992
	ds_write_b32 v238, v58 offset:25472
	ds_write_b32 v238, v59 offset:26000
	ds_write_b32 v238, v60 offset:26528
	ds_write_b32 v238, v61 offset:27056
	ds_write_b32 v238, v62 offset:25536
	ds_write_b32 v238, v63 offset:26064
	ds_write_b32 v238, v64 offset:26592
	ds_write_b32 v238, v65 offset:27120
	s_waitcnt lgkmcnt(0)
	s_barrier
	ds_read_b128 v[2:5], v239
	ds_read_b128 v[6:9], v239 offset:4224
	ds_read_b128 v[10:13], v239 offset:8448
	ds_read_b128 v[14:17], v239 offset:12672
	ds_read_b128 v[18:21], v239 offset:16896
	ds_read_b128 v[22:25], v239 offset:21120
	ds_read_b128 v[26:29], v239 offset:25344
	ds_read_b128 v[30:33], v239 offset:29568
	ds_read_b128 v[34:37], v239 offset:33792
	ds_read_b128 v[38:41], v239 offset:38016
	ds_read_b128 v[42:45], v239 offset:42240
	ds_read_b128 v[46:49], v239 offset:46464
	ds_read_b128 v[50:53], v239 offset:50688
	ds_read_b128 v[54:57], v239 offset:54912
	ds_read_b128 v[58:61], v239 offset:59136
	ds_read_b128 v[62:65], v239 offset:63360
	s_waitcnt vmcnt(15) lgkmcnt(15)
	v_pk_add_f32 v[2:3], v[2:3], v[136:137]
	v_pk_add_f32 v[4:5], v[4:5], v[138:139]
	v_cvt_pk_bf16_f32 v136, v2, v3
	v_cvt_pk_bf16_f32 v137, v4, v5
	v_mul_f32_e32 v138, v2, v2
	v_fmac_f32_e32 v138, v3, v3
	v_fmac_f32_e32 v138, v4, v4
	v_fmac_f32_e32 v138, v5, v5
	s_waitcnt vmcnt(14) lgkmcnt(14)
	v_pk_add_f32 v[6:7], v[6:7], v[140:141]
	v_pk_add_f32 v[8:9], v[8:9], v[142:143]
	v_cvt_pk_bf16_f32 v140, v6, v7
	v_cvt_pk_bf16_f32 v141, v8, v9
	v_mul_f32_e32 v142, v6, v6
	v_fmac_f32_e32 v142, v7, v7
	v_fmac_f32_e32 v142, v8, v8
	v_fmac_f32_e32 v142, v9, v9
	s_waitcnt vmcnt(13) lgkmcnt(13)
	v_pk_add_f32 v[10:11], v[10:11], v[144:145]
	v_pk_add_f32 v[12:13], v[12:13], v[146:147]
	v_cvt_pk_bf16_f32 v144, v10, v11
	v_cvt_pk_bf16_f32 v145, v12, v13
	v_mul_f32_e32 v146, v10, v10
	v_fmac_f32_e32 v146, v11, v11
	v_fmac_f32_e32 v146, v12, v12
	v_fmac_f32_e32 v146, v13, v13
	s_waitcnt vmcnt(12) lgkmcnt(12)
	v_pk_add_f32 v[14:15], v[14:15], v[148:149]
	v_pk_add_f32 v[16:17], v[16:17], v[150:151]
	v_cvt_pk_bf16_f32 v148, v14, v15
	v_cvt_pk_bf16_f32 v149, v16, v17
	v_mul_f32_e32 v150, v14, v14
	v_fmac_f32_e32 v150, v15, v15
	v_fmac_f32_e32 v150, v16, v16
	v_fmac_f32_e32 v150, v17, v17
	s_waitcnt vmcnt(11) lgkmcnt(11)
	v_pk_add_f32 v[18:19], v[18:19], v[172:173]
	v_pk_add_f32 v[20:21], v[20:21], v[174:175]
	v_cvt_pk_bf16_f32 v172, v18, v19
	v_cvt_pk_bf16_f32 v173, v20, v21
	v_mul_f32_e32 v174, v18, v18
	v_fmac_f32_e32 v174, v19, v19
	v_fmac_f32_e32 v174, v20, v20
	v_fmac_f32_e32 v174, v21, v21
	s_waitcnt vmcnt(10) lgkmcnt(10)
	v_pk_add_f32 v[22:23], v[22:23], v[176:177]
	v_pk_add_f32 v[24:25], v[24:25], v[178:179]
	v_cvt_pk_bf16_f32 v176, v22, v23
	v_cvt_pk_bf16_f32 v177, v24, v25
	v_mul_f32_e32 v178, v22, v22
	v_fmac_f32_e32 v178, v23, v23
	v_fmac_f32_e32 v178, v24, v24
	v_fmac_f32_e32 v178, v25, v25
	s_waitcnt vmcnt(9) lgkmcnt(9)
	v_pk_add_f32 v[26:27], v[26:27], v[180:181]
	v_pk_add_f32 v[28:29], v[28:29], v[182:183]
	v_cvt_pk_bf16_f32 v180, v26, v27
	v_cvt_pk_bf16_f32 v181, v28, v29
	v_mul_f32_e32 v182, v26, v26
	v_fmac_f32_e32 v182, v27, v27
	v_fmac_f32_e32 v182, v28, v28
	v_fmac_f32_e32 v182, v29, v29
	s_waitcnt vmcnt(8) lgkmcnt(8)
	v_pk_add_f32 v[30:31], v[30:31], v[184:185]
	v_pk_add_f32 v[32:33], v[32:33], v[186:187]
	v_cvt_pk_bf16_f32 v184, v30, v31
	v_cvt_pk_bf16_f32 v185, v32, v33
	v_mul_f32_e32 v186, v30, v30
	v_fmac_f32_e32 v186, v31, v31
	v_fmac_f32_e32 v186, v32, v32
	v_fmac_f32_e32 v186, v33, v33
	s_waitcnt vmcnt(7) lgkmcnt(7)
	v_pk_add_f32 v[34:35], v[34:35], v[188:189]
	v_pk_add_f32 v[36:37], v[36:37], v[190:191]
	v_cvt_pk_bf16_f32 v188, v34, v35
	v_cvt_pk_bf16_f32 v189, v36, v37
	v_mul_f32_e32 v190, v34, v34
	v_fmac_f32_e32 v190, v35, v35
	v_fmac_f32_e32 v190, v36, v36
	v_fmac_f32_e32 v190, v37, v37
	s_waitcnt vmcnt(6) lgkmcnt(6)
	v_pk_add_f32 v[38:39], v[38:39], v[196:197]
	v_pk_add_f32 v[40:41], v[40:41], v[198:199]
	v_cvt_pk_bf16_f32 v196, v38, v39
	v_cvt_pk_bf16_f32 v197, v40, v41
	v_mul_f32_e32 v198, v38, v38
	v_fmac_f32_e32 v198, v39, v39
	v_fmac_f32_e32 v198, v40, v40
	v_fmac_f32_e32 v198, v41, v41
	s_waitcnt vmcnt(5) lgkmcnt(5)
	v_pk_add_f32 v[42:43], v[42:43], v[200:201]
	v_pk_add_f32 v[44:45], v[44:45], v[202:203]
	v_cvt_pk_bf16_f32 v200, v42, v43
	v_cvt_pk_bf16_f32 v201, v44, v45
	v_mul_f32_e32 v202, v42, v42
	v_fmac_f32_e32 v202, v43, v43
	v_fmac_f32_e32 v202, v44, v44
	v_fmac_f32_e32 v202, v45, v45
	s_waitcnt vmcnt(4) lgkmcnt(4)
	v_pk_add_f32 v[46:47], v[46:47], v[204:205]
	v_pk_add_f32 v[48:49], v[48:49], v[206:207]
	v_cvt_pk_bf16_f32 v204, v46, v47
	v_cvt_pk_bf16_f32 v205, v48, v49
	v_mul_f32_e32 v206, v46, v46
	v_fmac_f32_e32 v206, v47, v47
	v_fmac_f32_e32 v206, v48, v48
	v_fmac_f32_e32 v206, v49, v49
	s_waitcnt vmcnt(3) lgkmcnt(3)
	v_pk_add_f32 v[50:51], v[50:51], v[212:213]
	v_pk_add_f32 v[52:53], v[52:53], v[214:215]
	v_cvt_pk_bf16_f32 v212, v50, v51
	v_cvt_pk_bf16_f32 v213, v52, v53
	v_mul_f32_e32 v214, v50, v50
	v_fmac_f32_e32 v214, v51, v51
	v_fmac_f32_e32 v214, v52, v52
	v_fmac_f32_e32 v214, v53, v53
	s_waitcnt vmcnt(2) lgkmcnt(2)
	v_pk_add_f32 v[54:55], v[54:55], v[216:217]
	v_pk_add_f32 v[56:57], v[56:57], v[218:219]
	v_cvt_pk_bf16_f32 v216, v54, v55
	v_cvt_pk_bf16_f32 v217, v56, v57
	v_mul_f32_e32 v218, v54, v54
	v_fmac_f32_e32 v218, v55, v55
	v_fmac_f32_e32 v218, v56, v56
	v_fmac_f32_e32 v218, v57, v57
	s_waitcnt vmcnt(1) lgkmcnt(1)
	v_pk_add_f32 v[58:59], v[58:59], v[220:221]
	v_pk_add_f32 v[60:61], v[60:61], v[222:223]
	v_cvt_pk_bf16_f32 v220, v58, v59
	v_cvt_pk_bf16_f32 v221, v60, v61
	v_mul_f32_e32 v222, v58, v58
	v_fmac_f32_e32 v222, v59, v59
	v_fmac_f32_e32 v222, v60, v60
	v_fmac_f32_e32 v222, v61, v61
	s_waitcnt vmcnt(0) lgkmcnt(0)
	v_pk_add_f32 v[62:63], v[62:63], v[224:225]
	v_pk_add_f32 v[64:65], v[64:65], v[226:227]
	v_cvt_pk_bf16_f32 v224, v62, v63
	v_cvt_pk_bf16_f32 v225, v64, v65
	v_mul_f32_e32 v226, v62, v62
	v_fmac_f32_e32 v226, v63, v63
	v_fmac_f32_e32 v226, v64, v64
	v_fmac_f32_e32 v226, v65, v65
	s_mov_b32 s56, s58
	s_mov_b32 s57, s59
	s_mov_b32 s40, s46
	s_mov_b32 s41, s47
	global_store_dwordx4 v240, v[2:5], s[56:57]
	global_store_dwordx2 v244, v[136:137], s[40:41]
	s_add_u32 s56, s56, 0x10000
	s_addc_u32 s57, s57, 0
	s_add_u32 s40, s40, 0x8400
	s_addc_u32 s41, s41, 0
	global_store_dwordx4 v240, v[6:9], s[56:57]
	global_store_dwordx2 v244, v[140:141], s[40:41]
	s_add_u32 s56, s56, 0x10000
	s_addc_u32 s57, s57, 0
	s_add_u32 s40, s40, 0x8400
	s_addc_u32 s41, s41, 0
	global_store_dwordx4 v240, v[10:13], s[56:57]
	global_store_dwordx2 v244, v[144:145], s[40:41]
	s_add_u32 s56, s56, 0x10000
	s_addc_u32 s57, s57, 0
	s_add_u32 s40, s40, 0x8400
	s_addc_u32 s41, s41, 0
	global_store_dwordx4 v240, v[14:17], s[56:57]
	global_store_dwordx2 v244, v[148:149], s[40:41]
	s_add_u32 s56, s56, 0x10000
	s_addc_u32 s57, s57, 0
	s_add_u32 s40, s40, 0x8400
	s_addc_u32 s41, s41, 0
	global_store_dwordx4 v240, v[18:21], s[56:57]
	global_store_dwordx2 v244, v[172:173], s[40:41]
	s_add_u32 s56, s56, 0x10000
	s_addc_u32 s57, s57, 0
	s_add_u32 s40, s40, 0x8400
	s_addc_u32 s41, s41, 0
	global_store_dwordx4 v240, v[22:25], s[56:57]
	global_store_dwordx2 v244, v[176:177], s[40:41]
	s_add_u32 s56, s56, 0x10000
	s_addc_u32 s57, s57, 0
	s_add_u32 s40, s40, 0x8400
	s_addc_u32 s41, s41, 0
	global_store_dwordx4 v240, v[26:29], s[56:57]
	global_store_dwordx2 v244, v[180:181], s[40:41]
	s_add_u32 s56, s56, 0x10000
	s_addc_u32 s57, s57, 0
	s_add_u32 s40, s40, 0x8400
	s_addc_u32 s41, s41, 0
	global_store_dwordx4 v240, v[30:33], s[56:57]
	global_store_dwordx2 v244, v[184:185], s[40:41]
	s_add_u32 s56, s56, 0x10000
	s_addc_u32 s57, s57, 0
	s_add_u32 s40, s40, 0x8400
	s_addc_u32 s41, s41, 0
	global_store_dwordx4 v240, v[34:37], s[56:57]
	global_store_dwordx2 v244, v[188:189], s[40:41]
	s_add_u32 s56, s56, 0x10000
	s_addc_u32 s57, s57, 0
	s_add_u32 s40, s40, 0x8400
	s_addc_u32 s41, s41, 0
	global_store_dwordx4 v240, v[38:41], s[56:57]
	global_store_dwordx2 v244, v[196:197], s[40:41]
	s_add_u32 s56, s56, 0x10000
	s_addc_u32 s57, s57, 0
	s_add_u32 s40, s40, 0x8400
	s_addc_u32 s41, s41, 0
	global_store_dwordx4 v240, v[42:45], s[56:57]
	global_store_dwordx2 v244, v[200:201], s[40:41]
	s_add_u32 s56, s56, 0x10000
	s_addc_u32 s57, s57, 0
	s_add_u32 s40, s40, 0x8400
	s_addc_u32 s41, s41, 0
	global_store_dwordx4 v240, v[46:49], s[56:57]
	global_store_dwordx2 v244, v[204:205], s[40:41]
	s_add_u32 s56, s56, 0x10000
	s_addc_u32 s57, s57, 0
	s_add_u32 s40, s40, 0x8400
	s_addc_u32 s41, s41, 0
	global_store_dwordx4 v240, v[50:53], s[56:57]
	global_store_dwordx2 v244, v[212:213], s[40:41]
	s_add_u32 s56, s56, 0x10000
	s_addc_u32 s57, s57, 0
	s_add_u32 s40, s40, 0x8400
	s_addc_u32 s41, s41, 0
	global_store_dwordx4 v240, v[54:57], s[56:57]
	global_store_dwordx2 v244, v[216:217], s[40:41]
	s_add_u32 s56, s56, 0x10000
	s_addc_u32 s57, s57, 0
	s_add_u32 s40, s40, 0x8400
	s_addc_u32 s41, s41, 0
	global_store_dwordx4 v240, v[58:61], s[56:57]
	global_store_dwordx2 v244, v[220:221], s[40:41]
	s_add_u32 s56, s56, 0x10000
	s_addc_u32 s57, s57, 0
	s_add_u32 s40, s40, 0x8400
	s_addc_u32 s41, s41, 0
	global_store_dwordx4 v240, v[62:65], s[56:57]
	global_store_dwordx2 v244, v[224:225], s[40:41]
	v_add_f32_dpp v138, v138, v138 quad_perm:[1,0,3,2] row_mask:0xf bank_mask:0xf
	v_add_f32_dpp v142, v142, v142 quad_perm:[1,0,3,2] row_mask:0xf bank_mask:0xf
	v_add_f32_dpp v146, v146, v146 quad_perm:[1,0,3,2] row_mask:0xf bank_mask:0xf
	v_add_f32_dpp v150, v150, v150 quad_perm:[1,0,3,2] row_mask:0xf bank_mask:0xf
	v_add_f32_dpp v174, v174, v174 quad_perm:[1,0,3,2] row_mask:0xf bank_mask:0xf
	v_add_f32_dpp v178, v178, v178 quad_perm:[1,0,3,2] row_mask:0xf bank_mask:0xf
	v_add_f32_dpp v182, v182, v182 quad_perm:[1,0,3,2] row_mask:0xf bank_mask:0xf
	v_add_f32_dpp v186, v186, v186 quad_perm:[1,0,3,2] row_mask:0xf bank_mask:0xf
	v_add_f32_dpp v190, v190, v190 quad_perm:[1,0,3,2] row_mask:0xf bank_mask:0xf
	v_add_f32_dpp v198, v198, v198 quad_perm:[1,0,3,2] row_mask:0xf bank_mask:0xf
	v_add_f32_dpp v202, v202, v202 quad_perm:[1,0,3,2] row_mask:0xf bank_mask:0xf
	v_add_f32_dpp v206, v206, v206 quad_perm:[1,0,3,2] row_mask:0xf bank_mask:0xf
	v_add_f32_dpp v214, v214, v214 quad_perm:[1,0,3,2] row_mask:0xf bank_mask:0xf
	v_add_f32_dpp v218, v218, v218 quad_perm:[1,0,3,2] row_mask:0xf bank_mask:0xf
	v_add_f32_dpp v222, v222, v222 quad_perm:[1,0,3,2] row_mask:0xf bank_mask:0xf
	v_add_f32_dpp v226, v226, v226 quad_perm:[1,0,3,2] row_mask:0xf bank_mask:0xf
	v_add_f32_dpp v138, v138, v138 quad_perm:[2,3,0,1] row_mask:0xf bank_mask:0xf
	v_add_f32_dpp v142, v142, v142 quad_perm:[2,3,0,1] row_mask:0xf bank_mask:0xf
	v_add_f32_dpp v146, v146, v146 quad_perm:[2,3,0,1] row_mask:0xf bank_mask:0xf
	v_add_f32_dpp v150, v150, v150 quad_perm:[2,3,0,1] row_mask:0xf bank_mask:0xf
	v_add_f32_dpp v174, v174, v174 quad_perm:[2,3,0,1] row_mask:0xf bank_mask:0xf
	v_add_f32_dpp v178, v178, v178 quad_perm:[2,3,0,1] row_mask:0xf bank_mask:0xf
	v_add_f32_dpp v182, v182, v182 quad_perm:[2,3,0,1] row_mask:0xf bank_mask:0xf
	v_add_f32_dpp v186, v186, v186 quad_perm:[2,3,0,1] row_mask:0xf bank_mask:0xf
	v_add_f32_dpp v190, v190, v190 quad_perm:[2,3,0,1] row_mask:0xf bank_mask:0xf
	v_add_f32_dpp v198, v198, v198 quad_perm:[2,3,0,1] row_mask:0xf bank_mask:0xf
	v_add_f32_dpp v202, v202, v202 quad_perm:[2,3,0,1] row_mask:0xf bank_mask:0xf
	v_add_f32_dpp v206, v206, v206 quad_perm:[2,3,0,1] row_mask:0xf bank_mask:0xf
	v_add_f32_dpp v214, v214, v214 quad_perm:[2,3,0,1] row_mask:0xf bank_mask:0xf
	v_add_f32_dpp v218, v218, v218 quad_perm:[2,3,0,1] row_mask:0xf bank_mask:0xf
	v_add_f32_dpp v222, v222, v222 quad_perm:[2,3,0,1] row_mask:0xf bank_mask:0xf
	v_add_f32_dpp v226, v226, v226 quad_perm:[2,3,0,1] row_mask:0xf bank_mask:0xf
	v_add_f32_dpp v138, v138, v138 row_half_mirror row_mask:0xf bank_mask:0xf
	v_add_f32_dpp v142, v142, v142 row_half_mirror row_mask:0xf bank_mask:0xf
	v_add_f32_dpp v146, v146, v146 row_half_mirror row_mask:0xf bank_mask:0xf
	v_add_f32_dpp v150, v150, v150 row_half_mirror row_mask:0xf bank_mask:0xf
	v_add_f32_dpp v174, v174, v174 row_half_mirror row_mask:0xf bank_mask:0xf
	v_add_f32_dpp v178, v178, v178 row_half_mirror row_mask:0xf bank_mask:0xf
	v_add_f32_dpp v182, v182, v182 row_half_mirror row_mask:0xf bank_mask:0xf
	v_add_f32_dpp v186, v186, v186 row_half_mirror row_mask:0xf bank_mask:0xf
	v_add_f32_dpp v190, v190, v190 row_half_mirror row_mask:0xf bank_mask:0xf
	v_add_f32_dpp v198, v198, v198 row_half_mirror row_mask:0xf bank_mask:0xf
	v_add_f32_dpp v202, v202, v202 row_half_mirror row_mask:0xf bank_mask:0xf
	v_add_f32_dpp v206, v206, v206 row_half_mirror row_mask:0xf bank_mask:0xf
	v_add_f32_dpp v214, v214, v214 row_half_mirror row_mask:0xf bank_mask:0xf
	v_add_f32_dpp v218, v218, v218 row_half_mirror row_mask:0xf bank_mask:0xf
	v_add_f32_dpp v222, v222, v222 row_half_mirror row_mask:0xf bank_mask:0xf
	v_add_f32_dpp v226, v226, v226 row_half_mirror row_mask:0xf bank_mask:0xf
	v_add_f32_dpp v138, v138, v138 row_mirror row_mask:0xf bank_mask:0xf
	v_add_f32_dpp v142, v142, v142 row_mirror row_mask:0xf bank_mask:0xf
	v_add_f32_dpp v146, v146, v146 row_mirror row_mask:0xf bank_mask:0xf
	v_add_f32_dpp v150, v150, v150 row_mirror row_mask:0xf bank_mask:0xf
	v_add_f32_dpp v174, v174, v174 row_mirror row_mask:0xf bank_mask:0xf
	v_add_f32_dpp v178, v178, v178 row_mirror row_mask:0xf bank_mask:0xf
	v_add_f32_dpp v182, v182, v182 row_mirror row_mask:0xf bank_mask:0xf
	v_add_f32_dpp v186, v186, v186 row_mirror row_mask:0xf bank_mask:0xf
	v_add_f32_dpp v190, v190, v190 row_mirror row_mask:0xf bank_mask:0xf
	v_add_f32_dpp v198, v198, v198 row_mirror row_mask:0xf bank_mask:0xf
	v_add_f32_dpp v202, v202, v202 row_mirror row_mask:0xf bank_mask:0xf
	v_add_f32_dpp v206, v206, v206 row_mirror row_mask:0xf bank_mask:0xf
	v_add_f32_dpp v214, v214, v214 row_mirror row_mask:0xf bank_mask:0xf
	v_add_f32_dpp v218, v218, v218 row_mirror row_mask:0xf bank_mask:0xf
	v_add_f32_dpp v222, v222, v222 row_mirror row_mask:0xf bank_mask:0xf
	v_add_f32_dpp v226, v226, v226 row_mirror row_mask:0xf bank_mask:0xf
	v_add_f32_dpp v138, v138, v138 row_bcast:15 row_mask:0xa bank_mask:0xf
	v_add_f32_dpp v142, v142, v142 row_bcast:15 row_mask:0xa bank_mask:0xf
	v_add_f32_dpp v146, v146, v146 row_bcast:15 row_mask:0xa bank_mask:0xf
	v_add_f32_dpp v150, v150, v150 row_bcast:15 row_mask:0xa bank_mask:0xf
	v_add_f32_dpp v174, v174, v174 row_bcast:15 row_mask:0xa bank_mask:0xf
	v_add_f32_dpp v178, v178, v178 row_bcast:15 row_mask:0xa bank_mask:0xf
	v_add_f32_dpp v182, v182, v182 row_bcast:15 row_mask:0xa bank_mask:0xf
	v_add_f32_dpp v186, v186, v186 row_bcast:15 row_mask:0xa bank_mask:0xf
	v_add_f32_dpp v190, v190, v190 row_bcast:15 row_mask:0xa bank_mask:0xf
	v_add_f32_dpp v198, v198, v198 row_bcast:15 row_mask:0xa bank_mask:0xf
	v_add_f32_dpp v202, v202, v202 row_bcast:15 row_mask:0xa bank_mask:0xf
	v_add_f32_dpp v206, v206, v206 row_bcast:15 row_mask:0xa bank_mask:0xf
	v_add_f32_dpp v214, v214, v214 row_bcast:15 row_mask:0xa bank_mask:0xf
	v_add_f32_dpp v218, v218, v218 row_bcast:15 row_mask:0xa bank_mask:0xf
	v_add_f32_dpp v222, v222, v222 row_bcast:15 row_mask:0xa bank_mask:0xf
	v_add_f32_dpp v226, v226, v226 row_bcast:15 row_mask:0xa bank_mask:0xf
	s_mov_b32 exec_lo, 0x10000
	s_mov_b32 exec_hi, 0x10000
	global_atomic_add_f32 v245, v138, s[48:49]
	global_atomic_add_f32 v245, v142, s[48:49] offset:32
	global_atomic_add_f32 v245, v146, s[48:49] offset:64
	global_atomic_add_f32 v245, v150, s[48:49] offset:96
	global_atomic_add_f32 v245, v174, s[48:49] offset:128
	global_atomic_add_f32 v245, v178, s[48:49] offset:160
	global_atomic_add_f32 v245, v182, s[48:49] offset:192
	global_atomic_add_f32 v245, v186, s[48:49] offset:224
	global_atomic_add_f32 v245, v190, s[48:49] offset:256
	global_atomic_add_f32 v245, v198, s[48:49] offset:288
	global_atomic_add_f32 v245, v202, s[48:49] offset:320
	global_atomic_add_f32 v245, v206, s[48:49] offset:352
	global_atomic_add_f32 v245, v214, s[48:49] offset:384
	global_atomic_add_f32 v245, v218, s[48:49] offset:416
	global_atomic_add_f32 v245, v222, s[48:49] offset:448
	global_atomic_add_f32 v245, v226, s[48:49] offset:480
	s_mov_b64 exec, -1
	s_add_u32 s44, s44, 0x1000
	s_addc_u32 s45, s45, 0
	s_add_u32 s58, s58, 0x1000
	s_addc_u32 s59, s59, 0
	s_add_u32 s46, s46, 0x800
	s_addc_u32 s47, s47, 0
	s_waitcnt lgkmcnt(0)
	s_barrier
	s_mov_b32 s56, s44
	s_mov_b32 s57, s45
	global_load_dwordx4 v[136:139], v240, s[56:57]
	s_add_u32 s56, s56, 0x10000
	s_addc_u32 s57, s57, 0
	global_load_dwordx4 v[140:143], v240, s[56:57]
	s_add_u32 s56, s56, 0x10000
	s_addc_u32 s57, s57, 0
	global_load_dwordx4 v[144:147], v240, s[56:57]
	s_add_u32 s56, s56, 0x10000
	s_addc_u32 s57, s57, 0
	global_load_dwordx4 v[148:151], v240, s[56:57]
	s_add_u32 s56, s56, 0x10000
	s_addc_u32 s57, s57, 0
	global_load_dwordx4 v[172:175], v240, s[56:57]
	s_add_u32 s56, s56, 0x10000
	s_addc_u32 s57, s57, 0
	global_load_dwordx4 v[176:179], v240, s[56:57]
	s_add_u32 s56, s56, 0x10000
	s_addc_u32 s57, s57, 0
	global_load_dwordx4 v[180:183], v240, s[56:57]
	s_add_u32 s56, s56, 0x10000
	s_addc_u32 s57, s57, 0
	global_load_dwordx4 v[184:187], v240, s[56:57]
	s_add_u32 s56, s56, 0x10000
	s_addc_u32 s57, s57, 0
	global_load_dwordx4 v[188:191], v240, s[56:57]
	s_add_u32 s56, s56, 0x10000
	s_addc_u32 s57, s57, 0
	global_load_dwordx4 v[196:199], v240, s[56:57]
	s_add_u32 s56, s56, 0x10000
	s_addc_u32 s57, s57, 0
	global_load_dwordx4 v[200:203], v240, s[56:57]
	s_add_u32 s56, s56, 0x10000
	s_addc_u32 s57, s57, 0
	global_load_dwordx4 v[204:207], v240, s[56:57]
	s_add_u32 s56, s56, 0x10000
	s_addc_u32 s57, s57, 0
	global_load_dwordx4 v[212:215], v240, s[56:57]
	s_add_u32 s56, s56, 0x10000
	s_addc_u32 s57, s57, 0
	global_load_dwordx4 v[216:219], v240, s[56:57]
	s_add_u32 s56, s56, 0x10000
	s_addc_u32 s57, s57, 0
	global_load_dwordx4 v[220:223], v240, s[56:57]
	s_add_u32 s56, s56, 0x10000
	s_addc_u32 s57, s57, 0
	global_load_dwordx4 v[224:227], v240, s[56:57]
	ds_write_b32 v238, v66
	ds_write_b32 v238, v67 offset:528
	ds_write_b32 v238, v68 offset:1056
	ds_write_b32 v238, v69 offset:1584
	ds_write_b32 v238, v70 offset:64
	ds_write_b32 v238, v71 offset:592
	ds_write_b32 v238, v72 offset:1120
	ds_write_b32 v238, v73 offset:1648
	ds_write_b32 v238, v74 offset:128
	ds_write_b32 v238, v75 offset:656
	ds_write_b32 v238, v76 offset:1184
	ds_write_b32 v238, v77 offset:1712
	ds_write_b32 v238, v78 offset:192
	ds_write_b32 v238, v79 offset:720
	ds_write_b32 v238, v80 offset:1248
	ds_write_b32 v238, v81 offset:1776
	ds_write_b32 v238, v82 offset:8448
	ds_write_b32 v238, v83 offset:8976
	ds_write_b32 v238, v84 offset:9504
	ds_write_b32 v238, v85 offset:10032
	ds_write_b32 v238, v86 offset:8512
	ds_write_b32 v238, v87 offset:9040
	ds_write_b32 v238, v88 offset:9568
	ds_write_b32 v238, v89 offset:10096
	ds_write_b32 v238, v90 offset:8576
	ds_write_b32 v238, v91 offset:9104
	ds_write_b32 v238, v92 offset:9632
	ds_write_b32 v238, v93 offset:10160
	ds_write_b32 v238, v94 offset:8640
	ds_write_b32 v238, v95 offset:9168
	ds_write_b32 v238, v96 offset:9696
	ds_write_b32 v238, v97 offset:10224
	ds_write_b32 v238, v98 offset:16896
	ds_write_b32 v238, v99 offset:17424
	ds_write_b32 v238, v100 offset:17952
	ds_write_b32 v238, v101 offset:18480
	ds_write_b32 v238, v102 offset:16960
	ds_write_b32 v238, v103 offset:17488
	ds_write_b32 v238, v104 offset:18016
	ds_write_b32 v238, v105 offset:18544
	ds_write_b32 v238, v106 offset:17024
	ds_write_b32 v238, v107 offset:17552
	ds_write_b32 v238, v108 offset:18080
	ds_write_b32 v238, v109 offset:18608
	ds_write_b32 v238, v110 offset:17088
	ds_write_b32 v238, v111 offset:17616
	ds_write_b32 v238, v112 offset:18144
	ds_write_b32 v238, v113 offset:18672
	ds_write_b32 v238, v114 offset:25344
	ds_write_b32 v238, v115 offset:25872
	ds_write_b32 v238, v116 offset:26400
	ds_write_b32 v238, v117 offset:26928
	ds_write_b32 v238, v118 offset:25408
	ds_write_b32 v238, v119 offset:25936
	ds_write_b32 v238, v120 offset:26464
	ds_write_b32 v238, v121 offset:26992
	ds_write_b32 v238, v122 offset:25472
	ds_write_b32 v238, v123 offset:26000
	ds_write_b32 v238, v124 offset:26528
	ds_write_b32 v238, v125 offset:27056
	ds_write_b32 v238, v126 offset:25536
	ds_write_b32 v238, v127 offset:26064
	ds_write_b32 v238, v128 offset:26592
	ds_write_b32 v238, v129 offset:27120
	s_waitcnt lgkmcnt(0)
	s_barrier
	ds_read_b128 v[66:69], v239
	ds_read_b128 v[70:73], v239 offset:4224
	ds_read_b128 v[74:77], v239 offset:8448
	ds_read_b128 v[78:81], v239 offset:12672
	ds_read_b128 v[82:85], v239 offset:16896
	ds_read_b128 v[86:89], v239 offset:21120
	ds_read_b128 v[90:93], v239 offset:25344
	ds_read_b128 v[94:97], v239 offset:29568
	ds_read_b128 v[98:101], v239 offset:33792
	ds_read_b128 v[102:105], v239 offset:38016
	ds_read_b128 v[106:109], v239 offset:42240
	ds_read_b128 v[110:113], v239 offset:46464
	ds_read_b128 v[114:117], v239 offset:50688
	ds_read_b128 v[118:121], v239 offset:54912
	ds_read_b128 v[122:125], v239 offset:59136
	ds_read_b128 v[126:129], v239 offset:63360
	s_waitcnt vmcnt(15) lgkmcnt(15)
	v_pk_add_f32 v[66:67], v[66:67], v[136:137]
	v_pk_add_f32 v[68:69], v[68:69], v[138:139]
	v_cvt_pk_bf16_f32 v136, v66, v67
	v_cvt_pk_bf16_f32 v137, v68, v69
	v_mul_f32_e32 v138, v66, v66
	v_fmac_f32_e32 v138, v67, v67
	v_fmac_f32_e32 v138, v68, v68
	v_fmac_f32_e32 v138, v69, v69
	s_waitcnt vmcnt(14) lgkmcnt(14)
	v_pk_add_f32 v[70:71], v[70:71], v[140:141]
	v_pk_add_f32 v[72:73], v[72:73], v[142:143]
	v_cvt_pk_bf16_f32 v140, v70, v71
	v_cvt_pk_bf16_f32 v141, v72, v73
	v_mul_f32_e32 v142, v70, v70
	v_fmac_f32_e32 v142, v71, v71
	v_fmac_f32_e32 v142, v72, v72
	v_fmac_f32_e32 v142, v73, v73
	s_waitcnt vmcnt(13) lgkmcnt(13)
	v_pk_add_f32 v[74:75], v[74:75], v[144:145]
	v_pk_add_f32 v[76:77], v[76:77], v[146:147]
	v_cvt_pk_bf16_f32 v144, v74, v75
	v_cvt_pk_bf16_f32 v145, v76, v77
	v_mul_f32_e32 v146, v74, v74
	v_fmac_f32_e32 v146, v75, v75
	v_fmac_f32_e32 v146, v76, v76
	v_fmac_f32_e32 v146, v77, v77
	s_waitcnt vmcnt(12) lgkmcnt(12)
	v_pk_add_f32 v[78:79], v[78:79], v[148:149]
	v_pk_add_f32 v[80:81], v[80:81], v[150:151]
	v_cvt_pk_bf16_f32 v148, v78, v79
	v_cvt_pk_bf16_f32 v149, v80, v81
	v_mul_f32_e32 v150, v78, v78
	v_fmac_f32_e32 v150, v79, v79
	v_fmac_f32_e32 v150, v80, v80
	v_fmac_f32_e32 v150, v81, v81
	s_waitcnt vmcnt(11) lgkmcnt(11)
	v_pk_add_f32 v[82:83], v[82:83], v[172:173]
	v_pk_add_f32 v[84:85], v[84:85], v[174:175]
	v_cvt_pk_bf16_f32 v172, v82, v83
	v_cvt_pk_bf16_f32 v173, v84, v85
	v_mul_f32_e32 v174, v82, v82
	v_fmac_f32_e32 v174, v83, v83
	v_fmac_f32_e32 v174, v84, v84
	v_fmac_f32_e32 v174, v85, v85
	s_waitcnt vmcnt(10) lgkmcnt(10)
	v_pk_add_f32 v[86:87], v[86:87], v[176:177]
	v_pk_add_f32 v[88:89], v[88:89], v[178:179]
	v_cvt_pk_bf16_f32 v176, v86, v87
	v_cvt_pk_bf16_f32 v177, v88, v89
	v_mul_f32_e32 v178, v86, v86
	v_fmac_f32_e32 v178, v87, v87
	v_fmac_f32_e32 v178, v88, v88
	v_fmac_f32_e32 v178, v89, v89
	s_waitcnt vmcnt(9) lgkmcnt(9)
	v_pk_add_f32 v[90:91], v[90:91], v[180:181]
	v_pk_add_f32 v[92:93], v[92:93], v[182:183]
	v_cvt_pk_bf16_f32 v180, v90, v91
	v_cvt_pk_bf16_f32 v181, v92, v93
	v_mul_f32_e32 v182, v90, v90
	v_fmac_f32_e32 v182, v91, v91
	v_fmac_f32_e32 v182, v92, v92
	v_fmac_f32_e32 v182, v93, v93
	s_waitcnt vmcnt(8) lgkmcnt(8)
	v_pk_add_f32 v[94:95], v[94:95], v[184:185]
	v_pk_add_f32 v[96:97], v[96:97], v[186:187]
	v_cvt_pk_bf16_f32 v184, v94, v95
	v_cvt_pk_bf16_f32 v185, v96, v97
	v_mul_f32_e32 v186, v94, v94
	v_fmac_f32_e32 v186, v95, v95
	v_fmac_f32_e32 v186, v96, v96
	v_fmac_f32_e32 v186, v97, v97
	s_waitcnt vmcnt(7) lgkmcnt(7)
	v_pk_add_f32 v[98:99], v[98:99], v[188:189]
	v_pk_add_f32 v[100:101], v[100:101], v[190:191]
	v_cvt_pk_bf16_f32 v188, v98, v99
	v_cvt_pk_bf16_f32 v189, v100, v101
	v_mul_f32_e32 v190, v98, v98
	v_fmac_f32_e32 v190, v99, v99
	v_fmac_f32_e32 v190, v100, v100
	v_fmac_f32_e32 v190, v101, v101
	s_waitcnt vmcnt(6) lgkmcnt(6)
	v_pk_add_f32 v[102:103], v[102:103], v[196:197]
	v_pk_add_f32 v[104:105], v[104:105], v[198:199]
	v_cvt_pk_bf16_f32 v196, v102, v103
	v_cvt_pk_bf16_f32 v197, v104, v105
	v_mul_f32_e32 v198, v102, v102
	v_fmac_f32_e32 v198, v103, v103
	v_fmac_f32_e32 v198, v104, v104
	v_fmac_f32_e32 v198, v105, v105
	s_waitcnt vmcnt(5) lgkmcnt(5)
	v_pk_add_f32 v[106:107], v[106:107], v[200:201]
	v_pk_add_f32 v[108:109], v[108:109], v[202:203]
	v_cvt_pk_bf16_f32 v200, v106, v107
	v_cvt_pk_bf16_f32 v201, v108, v109
	v_mul_f32_e32 v202, v106, v106
	v_fmac_f32_e32 v202, v107, v107
	v_fmac_f32_e32 v202, v108, v108
	v_fmac_f32_e32 v202, v109, v109
	s_waitcnt vmcnt(4) lgkmcnt(4)
	v_pk_add_f32 v[110:111], v[110:111], v[204:205]
	v_pk_add_f32 v[112:113], v[112:113], v[206:207]
	v_cvt_pk_bf16_f32 v204, v110, v111
	v_cvt_pk_bf16_f32 v205, v112, v113
	v_mul_f32_e32 v206, v110, v110
	v_fmac_f32_e32 v206, v111, v111
	v_fmac_f32_e32 v206, v112, v112
	v_fmac_f32_e32 v206, v113, v113
	s_waitcnt vmcnt(3) lgkmcnt(3)
	v_pk_add_f32 v[114:115], v[114:115], v[212:213]
	v_pk_add_f32 v[116:117], v[116:117], v[214:215]
	v_cvt_pk_bf16_f32 v212, v114, v115
	v_cvt_pk_bf16_f32 v213, v116, v117
	v_mul_f32_e32 v214, v114, v114
	v_fmac_f32_e32 v214, v115, v115
	v_fmac_f32_e32 v214, v116, v116
	v_fmac_f32_e32 v214, v117, v117
	s_waitcnt vmcnt(2) lgkmcnt(2)
	v_pk_add_f32 v[118:119], v[118:119], v[216:217]
	v_pk_add_f32 v[120:121], v[120:121], v[218:219]
	v_cvt_pk_bf16_f32 v216, v118, v119
	v_cvt_pk_bf16_f32 v217, v120, v121
	v_mul_f32_e32 v218, v118, v118
	v_fmac_f32_e32 v218, v119, v119
	v_fmac_f32_e32 v218, v120, v120
	v_fmac_f32_e32 v218, v121, v121
	s_waitcnt vmcnt(1) lgkmcnt(1)
	v_pk_add_f32 v[122:123], v[122:123], v[220:221]
	v_pk_add_f32 v[124:125], v[124:125], v[222:223]
	v_cvt_pk_bf16_f32 v220, v122, v123
	v_cvt_pk_bf16_f32 v221, v124, v125
	v_mul_f32_e32 v222, v122, v122
	v_fmac_f32_e32 v222, v123, v123
	v_fmac_f32_e32 v222, v124, v124
	v_fmac_f32_e32 v222, v125, v125
	s_waitcnt vmcnt(0) lgkmcnt(0)
	v_pk_add_f32 v[126:127], v[126:127], v[224:225]
	v_pk_add_f32 v[128:129], v[128:129], v[226:227]
	v_cvt_pk_bf16_f32 v224, v126, v127
	v_cvt_pk_bf16_f32 v225, v128, v129
	v_mul_f32_e32 v226, v126, v126
	v_fmac_f32_e32 v226, v127, v127
	v_fmac_f32_e32 v226, v128, v128
	v_fmac_f32_e32 v226, v129, v129
	s_mov_b32 s56, s58
	s_mov_b32 s57, s59
	s_mov_b32 s40, s46
	s_mov_b32 s41, s47
	global_store_dwordx4 v240, v[66:69], s[56:57]
	global_store_dwordx2 v244, v[136:137], s[40:41]
	s_add_u32 s56, s56, 0x10000
	s_addc_u32 s57, s57, 0
	s_add_u32 s40, s40, 0x8400
	s_addc_u32 s41, s41, 0
	global_store_dwordx4 v240, v[70:73], s[56:57]
	global_store_dwordx2 v244, v[140:141], s[40:41]
	s_add_u32 s56, s56, 0x10000
	s_addc_u32 s57, s57, 0
	s_add_u32 s40, s40, 0x8400
	s_addc_u32 s41, s41, 0
	global_store_dwordx4 v240, v[74:77], s[56:57]
	global_store_dwordx2 v244, v[144:145], s[40:41]
	s_add_u32 s56, s56, 0x10000
	s_addc_u32 s57, s57, 0
	s_add_u32 s40, s40, 0x8400
	s_addc_u32 s41, s41, 0
	global_store_dwordx4 v240, v[78:81], s[56:57]
	global_store_dwordx2 v244, v[148:149], s[40:41]
	s_add_u32 s56, s56, 0x10000
	s_addc_u32 s57, s57, 0
	s_add_u32 s40, s40, 0x8400
	s_addc_u32 s41, s41, 0
	global_store_dwordx4 v240, v[82:85], s[56:57]
	global_store_dwordx2 v244, v[172:173], s[40:41]
	s_add_u32 s56, s56, 0x10000
	s_addc_u32 s57, s57, 0
	s_add_u32 s40, s40, 0x8400
	s_addc_u32 s41, s41, 0
	global_store_dwordx4 v240, v[86:89], s[56:57]
	global_store_dwordx2 v244, v[176:177], s[40:41]
	s_add_u32 s56, s56, 0x10000
	s_addc_u32 s57, s57, 0
	s_add_u32 s40, s40, 0x8400
	s_addc_u32 s41, s41, 0
	global_store_dwordx4 v240, v[90:93], s[56:57]
	global_store_dwordx2 v244, v[180:181], s[40:41]
	s_add_u32 s56, s56, 0x10000
	s_addc_u32 s57, s57, 0
	s_add_u32 s40, s40, 0x8400
	s_addc_u32 s41, s41, 0
	global_store_dwordx4 v240, v[94:97], s[56:57]
	global_store_dwordx2 v244, v[184:185], s[40:41]
	s_add_u32 s56, s56, 0x10000
	s_addc_u32 s57, s57, 0
	s_add_u32 s40, s40, 0x8400
	s_addc_u32 s41, s41, 0
	global_store_dwordx4 v240, v[98:101], s[56:57]
	global_store_dwordx2 v244, v[188:189], s[40:41]
	s_add_u32 s56, s56, 0x10000
	s_addc_u32 s57, s57, 0
	s_add_u32 s40, s40, 0x8400
	s_addc_u32 s41, s41, 0
	global_store_dwordx4 v240, v[102:105], s[56:57]
	global_store_dwordx2 v244, v[196:197], s[40:41]
	s_add_u32 s56, s56, 0x10000
	s_addc_u32 s57, s57, 0
	s_add_u32 s40, s40, 0x8400
	s_addc_u32 s41, s41, 0
	global_store_dwordx4 v240, v[106:109], s[56:57]
	global_store_dwordx2 v244, v[200:201], s[40:41]
	s_add_u32 s56, s56, 0x10000
	s_addc_u32 s57, s57, 0
	s_add_u32 s40, s40, 0x8400
	s_addc_u32 s41, s41, 0
	global_store_dwordx4 v240, v[110:113], s[56:57]
	global_store_dwordx2 v244, v[204:205], s[40:41]
	s_add_u32 s56, s56, 0x10000
	s_addc_u32 s57, s57, 0
	s_add_u32 s40, s40, 0x8400
	s_addc_u32 s41, s41, 0
	global_store_dwordx4 v240, v[114:117], s[56:57]
	global_store_dwordx2 v244, v[212:213], s[40:41]
	s_add_u32 s56, s56, 0x10000
	s_addc_u32 s57, s57, 0
	s_add_u32 s40, s40, 0x8400
	s_addc_u32 s41, s41, 0
	global_store_dwordx4 v240, v[118:121], s[56:57]
	global_store_dwordx2 v244, v[216:217], s[40:41]
	s_add_u32 s56, s56, 0x10000
	s_addc_u32 s57, s57, 0
	s_add_u32 s40, s40, 0x8400
	s_addc_u32 s41, s41, 0
	global_store_dwordx4 v240, v[122:125], s[56:57]
	global_store_dwordx2 v244, v[220:221], s[40:41]
	s_add_u32 s56, s56, 0x10000
	s_addc_u32 s57, s57, 0
	s_add_u32 s40, s40, 0x8400
	s_addc_u32 s41, s41, 0
	global_store_dwordx4 v240, v[126:129], s[56:57]
	global_store_dwordx2 v244, v[224:225], s[40:41]
	v_add_f32_dpp v138, v138, v138 quad_perm:[1,0,3,2] row_mask:0xf bank_mask:0xf
	v_add_f32_dpp v142, v142, v142 quad_perm:[1,0,3,2] row_mask:0xf bank_mask:0xf
	v_add_f32_dpp v146, v146, v146 quad_perm:[1,0,3,2] row_mask:0xf bank_mask:0xf
	v_add_f32_dpp v150, v150, v150 quad_perm:[1,0,3,2] row_mask:0xf bank_mask:0xf
	v_add_f32_dpp v174, v174, v174 quad_perm:[1,0,3,2] row_mask:0xf bank_mask:0xf
	v_add_f32_dpp v178, v178, v178 quad_perm:[1,0,3,2] row_mask:0xf bank_mask:0xf
	v_add_f32_dpp v182, v182, v182 quad_perm:[1,0,3,2] row_mask:0xf bank_mask:0xf
	v_add_f32_dpp v186, v186, v186 quad_perm:[1,0,3,2] row_mask:0xf bank_mask:0xf
	v_add_f32_dpp v190, v190, v190 quad_perm:[1,0,3,2] row_mask:0xf bank_mask:0xf
	v_add_f32_dpp v198, v198, v198 quad_perm:[1,0,3,2] row_mask:0xf bank_mask:0xf
	v_add_f32_dpp v202, v202, v202 quad_perm:[1,0,3,2] row_mask:0xf bank_mask:0xf
	v_add_f32_dpp v206, v206, v206 quad_perm:[1,0,3,2] row_mask:0xf bank_mask:0xf
	v_add_f32_dpp v214, v214, v214 quad_perm:[1,0,3,2] row_mask:0xf bank_mask:0xf
	v_add_f32_dpp v218, v218, v218 quad_perm:[1,0,3,2] row_mask:0xf bank_mask:0xf
	v_add_f32_dpp v222, v222, v222 quad_perm:[1,0,3,2] row_mask:0xf bank_mask:0xf
	v_add_f32_dpp v226, v226, v226 quad_perm:[1,0,3,2] row_mask:0xf bank_mask:0xf
	v_add_f32_dpp v138, v138, v138 quad_perm:[2,3,0,1] row_mask:0xf bank_mask:0xf
	v_add_f32_dpp v142, v142, v142 quad_perm:[2,3,0,1] row_mask:0xf bank_mask:0xf
	v_add_f32_dpp v146, v146, v146 quad_perm:[2,3,0,1] row_mask:0xf bank_mask:0xf
	v_add_f32_dpp v150, v150, v150 quad_perm:[2,3,0,1] row_mask:0xf bank_mask:0xf
	v_add_f32_dpp v174, v174, v174 quad_perm:[2,3,0,1] row_mask:0xf bank_mask:0xf
	v_add_f32_dpp v178, v178, v178 quad_perm:[2,3,0,1] row_mask:0xf bank_mask:0xf
	v_add_f32_dpp v182, v182, v182 quad_perm:[2,3,0,1] row_mask:0xf bank_mask:0xf
	v_add_f32_dpp v186, v186, v186 quad_perm:[2,3,0,1] row_mask:0xf bank_mask:0xf
	v_add_f32_dpp v190, v190, v190 quad_perm:[2,3,0,1] row_mask:0xf bank_mask:0xf
	v_add_f32_dpp v198, v198, v198 quad_perm:[2,3,0,1] row_mask:0xf bank_mask:0xf
	v_add_f32_dpp v202, v202, v202 quad_perm:[2,3,0,1] row_mask:0xf bank_mask:0xf
	v_add_f32_dpp v206, v206, v206 quad_perm:[2,3,0,1] row_mask:0xf bank_mask:0xf
	v_add_f32_dpp v214, v214, v214 quad_perm:[2,3,0,1] row_mask:0xf bank_mask:0xf
	v_add_f32_dpp v218, v218, v218 quad_perm:[2,3,0,1] row_mask:0xf bank_mask:0xf
	v_add_f32_dpp v222, v222, v222 quad_perm:[2,3,0,1] row_mask:0xf bank_mask:0xf
	v_add_f32_dpp v226, v226, v226 quad_perm:[2,3,0,1] row_mask:0xf bank_mask:0xf
	v_add_f32_dpp v138, v138, v138 row_half_mirror row_mask:0xf bank_mask:0xf
	v_add_f32_dpp v142, v142, v142 row_half_mirror row_mask:0xf bank_mask:0xf
	v_add_f32_dpp v146, v146, v146 row_half_mirror row_mask:0xf bank_mask:0xf
	v_add_f32_dpp v150, v150, v150 row_half_mirror row_mask:0xf bank_mask:0xf
	v_add_f32_dpp v174, v174, v174 row_half_mirror row_mask:0xf bank_mask:0xf
	v_add_f32_dpp v178, v178, v178 row_half_mirror row_mask:0xf bank_mask:0xf
	v_add_f32_dpp v182, v182, v182 row_half_mirror row_mask:0xf bank_mask:0xf
	v_add_f32_dpp v186, v186, v186 row_half_mirror row_mask:0xf bank_mask:0xf
	v_add_f32_dpp v190, v190, v190 row_half_mirror row_mask:0xf bank_mask:0xf
	v_add_f32_dpp v198, v198, v198 row_half_mirror row_mask:0xf bank_mask:0xf
	v_add_f32_dpp v202, v202, v202 row_half_mirror row_mask:0xf bank_mask:0xf
	v_add_f32_dpp v206, v206, v206 row_half_mirror row_mask:0xf bank_mask:0xf
	v_add_f32_dpp v214, v214, v214 row_half_mirror row_mask:0xf bank_mask:0xf
	v_add_f32_dpp v218, v218, v218 row_half_mirror row_mask:0xf bank_mask:0xf
	v_add_f32_dpp v222, v222, v222 row_half_mirror row_mask:0xf bank_mask:0xf
	v_add_f32_dpp v226, v226, v226 row_half_mirror row_mask:0xf bank_mask:0xf
	v_add_f32_dpp v138, v138, v138 row_mirror row_mask:0xf bank_mask:0xf
	v_add_f32_dpp v142, v142, v142 row_mirror row_mask:0xf bank_mask:0xf
	v_add_f32_dpp v146, v146, v146 row_mirror row_mask:0xf bank_mask:0xf
	v_add_f32_dpp v150, v150, v150 row_mirror row_mask:0xf bank_mask:0xf
	v_add_f32_dpp v174, v174, v174 row_mirror row_mask:0xf bank_mask:0xf
	v_add_f32_dpp v178, v178, v178 row_mirror row_mask:0xf bank_mask:0xf
	v_add_f32_dpp v182, v182, v182 row_mirror row_mask:0xf bank_mask:0xf
	v_add_f32_dpp v186, v186, v186 row_mirror row_mask:0xf bank_mask:0xf
	v_add_f32_dpp v190, v190, v190 row_mirror row_mask:0xf bank_mask:0xf
	v_add_f32_dpp v198, v198, v198 row_mirror row_mask:0xf bank_mask:0xf
	v_add_f32_dpp v202, v202, v202 row_mirror row_mask:0xf bank_mask:0xf
	v_add_f32_dpp v206, v206, v206 row_mirror row_mask:0xf bank_mask:0xf
	v_add_f32_dpp v214, v214, v214 row_mirror row_mask:0xf bank_mask:0xf
	v_add_f32_dpp v218, v218, v218 row_mirror row_mask:0xf bank_mask:0xf
	v_add_f32_dpp v222, v222, v222 row_mirror row_mask:0xf bank_mask:0xf
	v_add_f32_dpp v226, v226, v226 row_mirror row_mask:0xf bank_mask:0xf
	v_add_f32_dpp v138, v138, v138 row_bcast:15 row_mask:0xa bank_mask:0xf
	v_add_f32_dpp v142, v142, v142 row_bcast:15 row_mask:0xa bank_mask:0xf
	v_add_f32_dpp v146, v146, v146 row_bcast:15 row_mask:0xa bank_mask:0xf
	v_add_f32_dpp v150, v150, v150 row_bcast:15 row_mask:0xa bank_mask:0xf
	v_add_f32_dpp v174, v174, v174 row_bcast:15 row_mask:0xa bank_mask:0xf
	v_add_f32_dpp v178, v178, v178 row_bcast:15 row_mask:0xa bank_mask:0xf
	v_add_f32_dpp v182, v182, v182 row_bcast:15 row_mask:0xa bank_mask:0xf
	v_add_f32_dpp v186, v186, v186 row_bcast:15 row_mask:0xa bank_mask:0xf
	v_add_f32_dpp v190, v190, v190 row_bcast:15 row_mask:0xa bank_mask:0xf
	v_add_f32_dpp v198, v198, v198 row_bcast:15 row_mask:0xa bank_mask:0xf
	v_add_f32_dpp v202, v202, v202 row_bcast:15 row_mask:0xa bank_mask:0xf
	v_add_f32_dpp v206, v206, v206 row_bcast:15 row_mask:0xa bank_mask:0xf
	v_add_f32_dpp v214, v214, v214 row_bcast:15 row_mask:0xa bank_mask:0xf
	v_add_f32_dpp v218, v218, v218 row_bcast:15 row_mask:0xa bank_mask:0xf
	v_add_f32_dpp v222, v222, v222 row_bcast:15 row_mask:0xa bank_mask:0xf
	v_add_f32_dpp v226, v226, v226 row_bcast:15 row_mask:0xa bank_mask:0xf
	s_mov_b32 exec_lo, 0x10000
	s_mov_b32 exec_hi, 0x10000
	global_atomic_add_f32 v245, v138, s[48:49]
	global_atomic_add_f32 v245, v142, s[48:49] offset:32
	global_atomic_add_f32 v245, v146, s[48:49] offset:64
	global_atomic_add_f32 v245, v150, s[48:49] offset:96
	global_atomic_add_f32 v245, v174, s[48:49] offset:128
	global_atomic_add_f32 v245, v178, s[48:49] offset:160
	global_atomic_add_f32 v245, v182, s[48:49] offset:192
	global_atomic_add_f32 v245, v186, s[48:49] offset:224
	global_atomic_add_f32 v245, v190, s[48:49] offset:256
	global_atomic_add_f32 v245, v198, s[48:49] offset:288
	global_atomic_add_f32 v245, v202, s[48:49] offset:320
	global_atomic_add_f32 v245, v206, s[48:49] offset:352
	global_atomic_add_f32 v245, v214, s[48:49] offset:384
	global_atomic_add_f32 v245, v218, s[48:49] offset:416
	global_atomic_add_f32 v245, v222, s[48:49] offset:448
	global_atomic_add_f32 v245, v226, s[48:49] offset:480
	s_mov_b64 exec, -1
	s_add_i32 s21, s21, s72
	s_cmpk_lt_i32 s21, 0x200
	s_waitcnt lgkmcnt(0)
	s_barrier
	s_cbranch_scc1 .Lres1_tile

.Lin2_loop:
	s_setprio 3
	v_add_u32_e32 v234, s22, v232
	v_add_u32_e32 v236, s28, v232
	v_add_u32_e32 v235, s22, v233
	v_add_u32_e32 v237, s28, v233
	ds_read_b128 v[136:139], v234
	ds_read_b128 v[188:191], v236
	ds_read_b128 v[196:199], v236 offset:2048
	ds_read_b128 v[200:203], v236 offset:4096
	ds_read_b128 v[204:207], v236 offset:6144
	ds_read_b128 v[140:143], v234 offset:2048
	ds_read_b128 v[144:147], v234 offset:4096
	ds_read_b128 v[148:151], v234 offset:6144
	ds_read_b128 v[172:175], v235
	ds_read_b128 v[212:215], v237
	ds_read_b128 v[216:219], v237 offset:2048
	ds_read_b128 v[220:223], v237 offset:4096
	ds_read_b128 v[224:227], v237 offset:6144
	ds_read_b128 v[176:179], v235 offset:2048
	ds_read_b128 v[180:183], v235 offset:4096
	ds_read_b128 v[184:187], v235 offset:6144
	s_add_i32 m0, s51, 0xc000
	s_nop 0
	global_load_lds_dwordx4 v228, s[44:45]
	s_add_i32 m0, s51, 0xc400
	s_nop 0
	global_load_lds_dwordx4 v230, s[44:45]
	s_add_i32 m0, s51, 0xe000
	s_nop 0
	global_load_lds_dwordx4 v229, s[44:45]
	s_add_i32 m0, s51, 0xe400
	s_nop 0
	global_load_lds_dwordx4 v231, s[44:45]
	s_add_i32 m0, s51, 0x10000
	s_nop 0
	global_load_lds_dwordx4 v228, s[46:47]
	s_add_i32 m0, s51, 0x10400
	s_nop 0
	global_load_lds_dwordx4 v230, s[46:47]
	s_waitcnt lgkmcnt(11)
	s_setprio 1
	v_mfma_f32_16x16x32_bf16 v[2:5], v[136:139], v[188:191], v[2:5]
	v_mfma_f32_16x16x32_bf16 v[6:9], v[136:139], v[196:199], v[6:9]
	v_mfma_f32_16x16x32_bf16 v[10:13], v[136:139], v[200:203], v[10:13]
	v_mfma_f32_16x16x32_bf16 v[14:17], v[136:139], v[204:207], v[14:17]
	s_waitcnt lgkmcnt(10)
	v_mfma_f32_16x16x32_bf16 v[18:21], v[140:143], v[188:191], v[18:21]
	v_mfma_f32_16x16x32_bf16 v[22:25], v[140:143], v[196:199], v[22:25]
	v_mfma_f32_16x16x32_bf16 v[26:29], v[140:143], v[200:203], v[26:29]
	v_mfma_f32_16x16x32_bf16 v[30:33], v[140:143], v[204:207], v[30:33]
	s_waitcnt lgkmcnt(9)
	v_mfma_f32_16x16x32_bf16 v[34:37], v[144:147], v[188:191], v[34:37]
	v_mfma_f32_16x16x32_bf16 v[38:41], v[144:147], v[196:199], v[38:41]
	v_mfma_f32_16x16x32_bf16 v[42:45], v[144:147], v[200:203], v[42:45]
	v_mfma_f32_16x16x32_bf16 v[46:49], v[144:147], v[204:207], v[46:49]
	s_waitcnt lgkmcnt(8)
	v_mfma_f32_16x16x32_bf16 v[50:53], v[148:151], v[188:191], v[50:53]
	v_mfma_f32_16x16x32_bf16 v[54:57], v[148:151], v[196:199], v[54:57]
	v_mfma_f32_16x16x32_bf16 v[58:61], v[148:151], v[200:203], v[58:61]
	v_mfma_f32_16x16x32_bf16 v[62:65], v[148:151], v[204:207], v[62:65]
	s_waitcnt lgkmcnt(3)
	v_mfma_f32_16x16x32_bf16 v[2:5], v[172:175], v[212:215], v[2:5]
	v_mfma_f32_16x16x32_bf16 v[6:9], v[172:175], v[216:219], v[6:9]
	v_mfma_f32_16x16x32_bf16 v[10:13], v[172:175], v[220:223], v[10:13]
	v_mfma_f32_16x16x32_bf16 v[14:17], v[172:175], v[224:227], v[14:17]
	s_waitcnt lgkmcnt(2)
	v_mfma_f32_16x16x32_bf16 v[18:21], v[176:179], v[212:215], v[18:21]
	v_mfma_f32_16x16x32_bf16 v[22:25], v[176:179], v[216:219], v[22:25]
	v_mfma_f32_16x16x32_bf16 v[26:29], v[176:179], v[220:223], v[26:29]
	v_mfma_f32_16x16x32_bf16 v[30:33], v[176:179], v[224:227], v[30:33]
	s_waitcnt lgkmcnt(1)
	v_mfma_f32_16x16x32_bf16 v[34:37], v[180:183], v[212:215], v[34:37]
	v_mfma_f32_16x16x32_bf16 v[38:41], v[180:183], v[216:219], v[38:41]
	v_mfma_f32_16x16x32_bf16 v[42:45], v[180:183], v[220:223], v[42:45]
	v_mfma_f32_16x16x32_bf16 v[46:49], v[180:183], v[224:227], v[46:49]
	s_waitcnt lgkmcnt(0)
	v_mfma_f32_16x16x32_bf16 v[50:53], v[184:187], v[212:215], v[50:53]
	v_mfma_f32_16x16x32_bf16 v[54:57], v[184:187], v[216:219], v[54:57]
	v_mfma_f32_16x16x32_bf16 v[58:61], v[184:187], v[220:223], v[58:61]
	v_mfma_f32_16x16x32_bf16 v[62:65], v[184:187], v[224:227], v[62:65]
	s_setprio 0
	s_waitcnt vmcnt(6)
	s_barrier
	s_setprio 3
	v_add_u32_e32 v236, s40, v232
	v_add_u32_e32 v237, s40, v233
	ds_read_b128 v[188:191], v236
	ds_read_b128 v[196:199], v236 offset:2048
	ds_read_b128 v[200:203], v236 offset:4096
	ds_read_b128 v[204:207], v236 offset:6144
	ds_read_b128 v[212:215], v237
	ds_read_b128 v[216:219], v237 offset:2048
	ds_read_b128 v[220:223], v237 offset:4096
	ds_read_b128 v[224:227], v237 offset:6144
	s_mov_b32 m0, s51
	s_nop 0
	global_load_lds_dwordx4 v229, s[46:47]
	s_add_i32 m0, s51, 0x400
	s_nop 0
	global_load_lds_dwordx4 v231, s[46:47]
	s_add_i32 m0, s51, 0x2000
	s_nop 0
	global_load_lds_dwordx4 v228, s[48:49]
	s_add_i32 m0, s51, 0x2400
	s_nop 0
	global_load_lds_dwordx4 v230, s[48:49]
	s_add_i32 m0, s51, 0x4000
	s_nop 0
	global_load_lds_dwordx4 v229, s[48:49]
	s_add_i32 m0, s51, 0x4400
	s_nop 0
	global_load_lds_dwordx4 v231, s[48:49]
	s_waitcnt lgkmcnt(7)
	s_setprio 1
	v_mfma_f32_16x16x32_bf16 v[66:69], v[136:139], v[188:191], v[66:69]
	v_mfma_f32_16x16x32_bf16 v[82:85], v[140:143], v[188:191], v[82:85]
	v_mfma_f32_16x16x32_bf16 v[98:101], v[144:147], v[188:191], v[98:101]
	v_mfma_f32_16x16x32_bf16 v[114:117], v[148:151], v[188:191], v[114:117]
	s_waitcnt lgkmcnt(6)
	v_mfma_f32_16x16x32_bf16 v[70:73], v[136:139], v[196:199], v[70:73]
	v_mfma_f32_16x16x32_bf16 v[86:89], v[140:143], v[196:199], v[86:89]
	v_mfma_f32_16x16x32_bf16 v[102:105], v[144:147], v[196:199], v[102:105]
	v_mfma_f32_16x16x32_bf16 v[118:121], v[148:151], v[196:199], v[118:121]
	s_waitcnt lgkmcnt(5)
	v_mfma_f32_16x16x32_bf16 v[74:77], v[136:139], v[200:203], v[74:77]
	v_mfma_f32_16x16x32_bf16 v[90:93], v[140:143], v[200:203], v[90:93]
	v_mfma_f32_16x16x32_bf16 v[106:109], v[144:147], v[200:203], v[106:109]
	v_mfma_f32_16x16x32_bf16 v[122:125], v[148:151], v[200:203], v[122:125]
	s_waitcnt lgkmcnt(4)
	v_mfma_f32_16x16x32_bf16 v[78:81], v[136:139], v[204:207], v[78:81]
	v_mfma_f32_16x16x32_bf16 v[94:97], v[140:143], v[204:207], v[94:97]
	v_mfma_f32_16x16x32_bf16 v[110:113], v[144:147], v[204:207], v[110:113]
	v_mfma_f32_16x16x32_bf16 v[126:129], v[148:151], v[204:207], v[126:129]
	s_waitcnt lgkmcnt(3)
	v_mfma_f32_16x16x32_bf16 v[66:69], v[172:175], v[212:215], v[66:69]
	v_mfma_f32_16x16x32_bf16 v[82:85], v[176:179], v[212:215], v[82:85]
	v_mfma_f32_16x16x32_bf16 v[98:101], v[180:183], v[212:215], v[98:101]
	v_mfma_f32_16x16x32_bf16 v[114:117], v[184:187], v[212:215], v[114:117]
	s_waitcnt lgkmcnt(2)
	v_mfma_f32_16x16x32_bf16 v[70:73], v[172:175], v[216:219], v[70:73]
	v_mfma_f32_16x16x32_bf16 v[86:89], v[176:179], v[216:219], v[86:89]
	v_mfma_f32_16x16x32_bf16 v[102:105], v[180:183], v[216:219], v[102:105]
	v_mfma_f32_16x16x32_bf16 v[118:121], v[184:187], v[216:219], v[118:121]
	s_waitcnt lgkmcnt(1)
	v_mfma_f32_16x16x32_bf16 v[74:77], v[172:175], v[220:223], v[74:77]
	v_mfma_f32_16x16x32_bf16 v[90:93], v[176:179], v[220:223], v[90:93]
	v_mfma_f32_16x16x32_bf16 v[106:109], v[180:183], v[220:223], v[106:109]
	v_mfma_f32_16x16x32_bf16 v[122:125], v[184:187], v[220:223], v[122:125]
	s_waitcnt lgkmcnt(0)
	v_mfma_f32_16x16x32_bf16 v[78:81], v[172:175], v[224:227], v[78:81]
	v_mfma_f32_16x16x32_bf16 v[94:97], v[176:179], v[224:227], v[94:97]
	v_mfma_f32_16x16x32_bf16 v[110:113], v[180:183], v[224:227], v[110:113]
	v_mfma_f32_16x16x32_bf16 v[126:129], v[184:187], v[224:227], v[126:129]
	s_setprio 0
	v_add_u32_e32 v228, 0x80, v228
	v_add_u32_e32 v229, 0x80, v229
	v_add_u32_e32 v230, 0x80, v230
	v_add_u32_e32 v231, 0x80, v231
	s_waitcnt vmcnt(4)
	s_barrier
	s_setprio 3
	v_add_u32_e32 v234, s23, v232
	v_add_u32_e32 v236, s29, v232
	v_add_u32_e32 v235, s23, v233
	v_add_u32_e32 v237, s29, v233
	ds_read_b128 v[136:139], v234
	ds_read_b128 v[188:191], v236
	ds_read_b128 v[196:199], v236 offset:2048
	ds_read_b128 v[200:203], v236 offset:4096
	ds_read_b128 v[204:207], v236 offset:6144
	ds_read_b128 v[140:143], v234 offset:2048
	ds_read_b128 v[144:147], v234 offset:4096
	ds_read_b128 v[148:151], v234 offset:6144
	ds_read_b128 v[172:175], v235
	ds_read_b128 v[212:215], v237
	ds_read_b128 v[216:219], v237 offset:2048
	ds_read_b128 v[220:223], v237 offset:4096
	ds_read_b128 v[224:227], v237 offset:6144
	ds_read_b128 v[176:179], v235 offset:2048
	ds_read_b128 v[180:183], v235 offset:4096
	ds_read_b128 v[184:187], v235 offset:6144
	s_add_i32 m0, s51, 0x6000
	s_nop 0
	global_load_lds_dwordx4 v228, s[44:45]
	s_add_i32 m0, s51, 0x6400
	s_nop 0
	global_load_lds_dwordx4 v230, s[44:45]
	s_add_i32 m0, s51, 0x8000
	s_nop 0
	global_load_lds_dwordx4 v229, s[44:45]
	s_add_i32 m0, s51, 0x8400
	s_nop 0
	global_load_lds_dwordx4 v231, s[44:45]
	s_add_i32 m0, s51, 0xa000
	s_nop 0
	global_load_lds_dwordx4 v228, s[46:47]
	s_add_i32 m0, s51, 0xa400
	s_nop 0
	global_load_lds_dwordx4 v230, s[46:47]
	s_waitcnt lgkmcnt(11)
	s_setprio 1
	v_mfma_f32_16x16x32_bf16 v[2:5], v[136:139], v[188:191], v[2:5]
	v_mfma_f32_16x16x32_bf16 v[6:9], v[136:139], v[196:199], v[6:9]
	v_mfma_f32_16x16x32_bf16 v[10:13], v[136:139], v[200:203], v[10:13]
	v_mfma_f32_16x16x32_bf16 v[14:17], v[136:139], v[204:207], v[14:17]
	s_waitcnt lgkmcnt(10)
	v_mfma_f32_16x16x32_bf16 v[18:21], v[140:143], v[188:191], v[18:21]
	v_mfma_f32_16x16x32_bf16 v[22:25], v[140:143], v[196:199], v[22:25]
	v_mfma_f32_16x16x32_bf16 v[26:29], v[140:143], v[200:203], v[26:29]
	v_mfma_f32_16x16x32_bf16 v[30:33], v[140:143], v[204:207], v[30:33]
	s_waitcnt lgkmcnt(9)
	v_mfma_f32_16x16x32_bf16 v[34:37], v[144:147], v[188:191], v[34:37]
	v_mfma_f32_16x16x32_bf16 v[38:41], v[144:147], v[196:199], v[38:41]
	v_mfma_f32_16x16x32_bf16 v[42:45], v[144:147], v[200:203], v[42:45]
	v_mfma_f32_16x16x32_bf16 v[46:49], v[144:147], v[204:207], v[46:49]
	s_waitcnt lgkmcnt(8)
	v_mfma_f32_16x16x32_bf16 v[50:53], v[148:151], v[188:191], v[50:53]
	v_mfma_f32_16x16x32_bf16 v[54:57], v[148:151], v[196:199], v[54:57]
	v_mfma_f32_16x16x32_bf16 v[58:61], v[148:151], v[200:203], v[58:61]
	v_mfma_f32_16x16x32_bf16 v[62:65], v[148:151], v[204:207], v[62:65]
	s_waitcnt lgkmcnt(3)
	v_mfma_f32_16x16x32_bf16 v[2:5], v[172:175], v[212:215], v[2:5]
	v_mfma_f32_16x16x32_bf16 v[6:9], v[172:175], v[216:219], v[6:9]
	v_mfma_f32_16x16x32_bf16 v[10:13], v[172:175], v[220:223], v[10:13]
	v_mfma_f32_16x16x32_bf16 v[14:17], v[172:175], v[224:227], v[14:17]
	s_waitcnt lgkmcnt(2)
	v_mfma_f32_16x16x32_bf16 v[18:21], v[176:179], v[212:215], v[18:21]
	v_mfma_f32_16x16x32_bf16 v[22:25], v[176:179], v[216:219], v[22:25]
	v_mfma_f32_16x16x32_bf16 v[26:29], v[176:179], v[220:223], v[26:29]
	v_mfma_f32_16x16x32_bf16 v[30:33], v[176:179], v[224:227], v[30:33]
	s_waitcnt lgkmcnt(1)
	v_mfma_f32_16x16x32_bf16 v[34:37], v[180:183], v[212:215], v[34:37]
	v_mfma_f32_16x16x32_bf16 v[38:41], v[180:183], v[216:219], v[38:41]
	v_mfma_f32_16x16x32_bf16 v[42:45], v[180:183], v[220:223], v[42:45]
	v_mfma_f32_16x16x32_bf16 v[46:49], v[180:183], v[224:227], v[46:49]
	s_waitcnt lgkmcnt(0)
	v_mfma_f32_16x16x32_bf16 v[50:53], v[184:187], v[212:215], v[50:53]
	v_mfma_f32_16x16x32_bf16 v[54:57], v[184:187], v[216:219], v[54:57]
	v_mfma_f32_16x16x32_bf16 v[58:61], v[184:187], v[220:223], v[58:61]
	v_mfma_f32_16x16x32_bf16 v[62:65], v[184:187], v[224:227], v[62:65]
	s_setprio 0
	s_waitcnt vmcnt(6)
	s_barrier
	s_setprio 3
	v_add_u32_e32 v236, s41, v232
	v_add_u32_e32 v237, s41, v233
	ds_read_b128 v[188:191], v236
	ds_read_b128 v[196:199], v236 offset:2048
	ds_read_b128 v[200:203], v236 offset:4096
	ds_read_b128 v[204:207], v236 offset:6144
	ds_read_b128 v[212:215], v237
	ds_read_b128 v[216:219], v237 offset:2048
	ds_read_b128 v[220:223], v237 offset:4096
	ds_read_b128 v[224:227], v237 offset:6144
	s_add_i32 m0, s51, 0xc000
	s_nop 0
	global_load_lds_dwordx4 v229, s[46:47]
	s_add_i32 m0, s51, 0xc400
	s_nop 0
	global_load_lds_dwordx4 v231, s[46:47]
	s_add_i32 m0, s51, 0xe000
	s_nop 0
	global_load_lds_dwordx4 v228, s[48:49]
	s_add_i32 m0, s51, 0xe400
	s_nop 0
	global_load_lds_dwordx4 v230, s[48:49]
	s_add_i32 m0, s51, 0x10000
	s_nop 0
	global_load_lds_dwordx4 v229, s[48:49]
	s_add_i32 m0, s51, 0x10400
	s_nop 0
	global_load_lds_dwordx4 v231, s[48:49]
	s_waitcnt lgkmcnt(7)
	s_setprio 1
	v_mfma_f32_16x16x32_bf16 v[66:69], v[136:139], v[188:191], v[66:69]
	v_mfma_f32_16x16x32_bf16 v[82:85], v[140:143], v[188:191], v[82:85]
	v_mfma_f32_16x16x32_bf16 v[98:101], v[144:147], v[188:191], v[98:101]
	v_mfma_f32_16x16x32_bf16 v[114:117], v[148:151], v[188:191], v[114:117]
	s_waitcnt lgkmcnt(6)
	v_mfma_f32_16x16x32_bf16 v[70:73], v[136:139], v[196:199], v[70:73]
	v_mfma_f32_16x16x32_bf16 v[86:89], v[140:143], v[196:199], v[86:89]
	v_mfma_f32_16x16x32_bf16 v[102:105], v[144:147], v[196:199], v[102:105]
	v_mfma_f32_16x16x32_bf16 v[118:121], v[148:151], v[196:199], v[118:121]
	s_waitcnt lgkmcnt(5)
	v_mfma_f32_16x16x32_bf16 v[74:77], v[136:139], v[200:203], v[74:77]
	v_mfma_f32_16x16x32_bf16 v[90:93], v[140:143], v[200:203], v[90:93]
	v_mfma_f32_16x16x32_bf16 v[106:109], v[144:147], v[200:203], v[106:109]
	v_mfma_f32_16x16x32_bf16 v[122:125], v[148:151], v[200:203], v[122:125]
	s_waitcnt lgkmcnt(4)
	v_mfma_f32_16x16x32_bf16 v[78:81], v[136:139], v[204:207], v[78:81]
	v_mfma_f32_16x16x32_bf16 v[94:97], v[140:143], v[204:207], v[94:97]
	v_mfma_f32_16x16x32_bf16 v[110:113], v[144:147], v[204:207], v[110:113]
	v_mfma_f32_16x16x32_bf16 v[126:129], v[148:151], v[204:207], v[126:129]
	s_waitcnt lgkmcnt(3)
	v_mfma_f32_16x16x32_bf16 v[66:69], v[172:175], v[212:215], v[66:69]
	v_mfma_f32_16x16x32_bf16 v[82:85], v[176:179], v[212:215], v[82:85]
	v_mfma_f32_16x16x32_bf16 v[98:101], v[180:183], v[212:215], v[98:101]
	v_mfma_f32_16x16x32_bf16 v[114:117], v[184:187], v[212:215], v[114:117]
	s_waitcnt lgkmcnt(2)
	v_mfma_f32_16x16x32_bf16 v[70:73], v[172:175], v[216:219], v[70:73]
	v_mfma_f32_16x16x32_bf16 v[86:89], v[176:179], v[216:219], v[86:89]
	v_mfma_f32_16x16x32_bf16 v[102:105], v[180:183], v[216:219], v[102:105]
	v_mfma_f32_16x16x32_bf16 v[118:121], v[184:187], v[216:219], v[118:121]
	s_waitcnt lgkmcnt(1)
	v_mfma_f32_16x16x32_bf16 v[74:77], v[172:175], v[220:223], v[74:77]
	v_mfma_f32_16x16x32_bf16 v[90:93], v[176:179], v[220:223], v[90:93]
	v_mfma_f32_16x16x32_bf16 v[106:109], v[180:183], v[220:223], v[106:109]
	v_mfma_f32_16x16x32_bf16 v[122:125], v[184:187], v[220:223], v[122:125]
	s_waitcnt lgkmcnt(0)
	v_mfma_f32_16x16x32_bf16 v[78:81], v[172:175], v[224:227], v[78:81]
	v_mfma_f32_16x16x32_bf16 v[94:97], v[176:179], v[224:227], v[94:97]
	v_mfma_f32_16x16x32_bf16 v[110:113], v[180:183], v[224:227], v[110:113]
	v_mfma_f32_16x16x32_bf16 v[126:129], v[184:187], v[224:227], v[126:129]
	s_setprio 0
	v_add_u32_e32 v228, 0x80, v228
	v_add_u32_e32 v229, 0x80, v229
	v_add_u32_e32 v230, 0x80, v230
	v_add_u32_e32 v231, 0x80, v231
	s_waitcnt vmcnt(4)
	s_barrier
	s_setprio 3
	v_add_u32_e32 v234, s24, v232
	v_add_u32_e32 v236, s30, v232
	v_add_u32_e32 v235, s24, v233
	v_add_u32_e32 v237, s30, v233
	ds_read_b128 v[136:139], v234
	ds_read_b128 v[188:191], v236
	ds_read_b128 v[196:199], v236 offset:2048
	ds_read_b128 v[200:203], v236 offset:4096
	ds_read_b128 v[204:207], v236 offset:6144
	ds_read_b128 v[140:143], v234 offset:2048
	ds_read_b128 v[144:147], v234 offset:4096
	ds_read_b128 v[148:151], v234 offset:6144
	ds_read_b128 v[172:175], v235
	ds_read_b128 v[212:215], v237
	ds_read_b128 v[216:219], v237 offset:2048
	ds_read_b128 v[220:223], v237 offset:4096
	ds_read_b128 v[224:227], v237 offset:6144
	ds_read_b128 v[176:179], v235 offset:2048
	ds_read_b128 v[180:183], v235 offset:4096
	ds_read_b128 v[184:187], v235 offset:6144
	s_mov_b32 m0, s51
	s_nop 0
	global_load_lds_dwordx4 v228, s[44:45]
	s_add_i32 m0, s51, 0x400
	s_nop 0
	global_load_lds_dwordx4 v230, s[44:45]
	s_add_i32 m0, s51, 0x2000
	s_nop 0
	global_load_lds_dwordx4 v229, s[44:45]
	s_add_i32 m0, s51, 0x2400
	s_nop 0
	global_load_lds_dwordx4 v231, s[44:45]
	s_add_i32 m0, s51, 0x4000
	s_nop 0
	global_load_lds_dwordx4 v228, s[46:47]
	s_add_i32 m0, s51, 0x4400
	s_nop 0
	global_load_lds_dwordx4 v230, s[46:47]
	s_waitcnt lgkmcnt(11)
	s_setprio 1
	v_mfma_f32_16x16x32_bf16 v[2:5], v[136:139], v[188:191], v[2:5]
	v_mfma_f32_16x16x32_bf16 v[6:9], v[136:139], v[196:199], v[6:9]
	v_mfma_f32_16x16x32_bf16 v[10:13], v[136:139], v[200:203], v[10:13]
	v_mfma_f32_16x16x32_bf16 v[14:17], v[136:139], v[204:207], v[14:17]
	s_waitcnt lgkmcnt(10)
	v_mfma_f32_16x16x32_bf16 v[18:21], v[140:143], v[188:191], v[18:21]
	v_mfma_f32_16x16x32_bf16 v[22:25], v[140:143], v[196:199], v[22:25]
	v_mfma_f32_16x16x32_bf16 v[26:29], v[140:143], v[200:203], v[26:29]
	v_mfma_f32_16x16x32_bf16 v[30:33], v[140:143], v[204:207], v[30:33]
	s_waitcnt lgkmcnt(9)
	v_mfma_f32_16x16x32_bf16 v[34:37], v[144:147], v[188:191], v[34:37]
	v_mfma_f32_16x16x32_bf16 v[38:41], v[144:147], v[196:199], v[38:41]
	v_mfma_f32_16x16x32_bf16 v[42:45], v[144:147], v[200:203], v[42:45]
	v_mfma_f32_16x16x32_bf16 v[46:49], v[144:147], v[204:207], v[46:49]
	s_waitcnt lgkmcnt(8)
	v_mfma_f32_16x16x32_bf16 v[50:53], v[148:151], v[188:191], v[50:53]
	v_mfma_f32_16x16x32_bf16 v[54:57], v[148:151], v[196:199], v[54:57]
	v_mfma_f32_16x16x32_bf16 v[58:61], v[148:151], v[200:203], v[58:61]
	v_mfma_f32_16x16x32_bf16 v[62:65], v[148:151], v[204:207], v[62:65]
	s_waitcnt lgkmcnt(3)
	v_mfma_f32_16x16x32_bf16 v[2:5], v[172:175], v[212:215], v[2:5]
	v_mfma_f32_16x16x32_bf16 v[6:9], v[172:175], v[216:219], v[6:9]
	v_mfma_f32_16x16x32_bf16 v[10:13], v[172:175], v[220:223], v[10:13]
	v_mfma_f32_16x16x32_bf16 v[14:17], v[172:175], v[224:227], v[14:17]
	s_waitcnt lgkmcnt(2)
	v_mfma_f32_16x16x32_bf16 v[18:21], v[176:179], v[212:215], v[18:21]
	v_mfma_f32_16x16x32_bf16 v[22:25], v[176:179], v[216:219], v[22:25]
	v_mfma_f32_16x16x32_bf16 v[26:29], v[176:179], v[220:223], v[26:29]
	v_mfma_f32_16x16x32_bf16 v[30:33], v[176:179], v[224:227], v[30:33]
	s_waitcnt lgkmcnt(1)
	v_mfma_f32_16x16x32_bf16 v[34:37], v[180:183], v[212:215], v[34:37]
	v_mfma_f32_16x16x32_bf16 v[38:41], v[180:183], v[216:219], v[38:41]
	v_mfma_f32_16x16x32_bf16 v[42:45], v[180:183], v[220:223], v[42:45]
	v_mfma_f32_16x16x32_bf16 v[46:49], v[180:183], v[224:227], v[46:49]
	s_waitcnt lgkmcnt(0)
	v_mfma_f32_16x16x32_bf16 v[50:53], v[184:187], v[212:215], v[50:53]
	v_mfma_f32_16x16x32_bf16 v[54:57], v[184:187], v[216:219], v[54:57]
	v_mfma_f32_16x16x32_bf16 v[58:61], v[184:187], v[220:223], v[58:61]
	v_mfma_f32_16x16x32_bf16 v[62:65], v[184:187], v[224:227], v[62:65]
	s_setprio 0
	s_waitcnt vmcnt(6)
	s_barrier
	s_setprio 3
	v_add_u32_e32 v236, s42, v232
	v_add_u32_e32 v237, s42, v233
	ds_read_b128 v[188:191], v236
	ds_read_b128 v[196:199], v236 offset:2048
	ds_read_b128 v[200:203], v236 offset:4096
	ds_read_b128 v[204:207], v236 offset:6144
	ds_read_b128 v[212:215], v237
	ds_read_b128 v[216:219], v237 offset:2048
	ds_read_b128 v[220:223], v237 offset:4096
	ds_read_b128 v[224:227], v237 offset:6144
	s_add_i32 m0, s51, 0x6000
	s_nop 0
	global_load_lds_dwordx4 v229, s[46:47]
	s_add_i32 m0, s51, 0x6400
	s_nop 0
	global_load_lds_dwordx4 v231, s[46:47]
	s_add_i32 m0, s51, 0x8000
	s_nop 0
	global_load_lds_dwordx4 v228, s[48:49]
	s_add_i32 m0, s51, 0x8400
	s_nop 0
	global_load_lds_dwordx4 v230, s[48:49]
	s_add_i32 m0, s51, 0xa000
	s_nop 0
	global_load_lds_dwordx4 v229, s[48:49]
	s_add_i32 m0, s51, 0xa400
	s_nop 0
	global_load_lds_dwordx4 v231, s[48:49]
	s_waitcnt lgkmcnt(7)
	s_setprio 1
	v_mfma_f32_16x16x32_bf16 v[66:69], v[136:139], v[188:191], v[66:69]
	v_mfma_f32_16x16x32_bf16 v[82:85], v[140:143], v[188:191], v[82:85]
	v_mfma_f32_16x16x32_bf16 v[98:101], v[144:147], v[188:191], v[98:101]
	v_mfma_f32_16x16x32_bf16 v[114:117], v[148:151], v[188:191], v[114:117]
	s_waitcnt lgkmcnt(6)
	v_mfma_f32_16x16x32_bf16 v[70:73], v[136:139], v[196:199], v[70:73]
	v_mfma_f32_16x16x32_bf16 v[86:89], v[140:143], v[196:199], v[86:89]
	v_mfma_f32_16x16x32_bf16 v[102:105], v[144:147], v[196:199], v[102:105]
	v_mfma_f32_16x16x32_bf16 v[118:121], v[148:151], v[196:199], v[118:121]
	s_waitcnt lgkmcnt(5)
	v_mfma_f32_16x16x32_bf16 v[74:77], v[136:139], v[200:203], v[74:77]
	v_mfma_f32_16x16x32_bf16 v[90:93], v[140:143], v[200:203], v[90:93]
	v_mfma_f32_16x16x32_bf16 v[106:109], v[144:147], v[200:203], v[106:109]
	v_mfma_f32_16x16x32_bf16 v[122:125], v[148:151], v[200:203], v[122:125]
	s_waitcnt lgkmcnt(4)
	v_mfma_f32_16x16x32_bf16 v[78:81], v[136:139], v[204:207], v[78:81]
	v_mfma_f32_16x16x32_bf16 v[94:97], v[140:143], v[204:207], v[94:97]
	v_mfma_f32_16x16x32_bf16 v[110:113], v[144:147], v[204:207], v[110:113]
	v_mfma_f32_16x16x32_bf16 v[126:129], v[148:151], v[204:207], v[126:129]
	s_waitcnt lgkmcnt(3)
	v_mfma_f32_16x16x32_bf16 v[66:69], v[172:175], v[212:215], v[66:69]
	v_mfma_f32_16x16x32_bf16 v[82:85], v[176:179], v[212:215], v[82:85]
	v_mfma_f32_16x16x32_bf16 v[98:101], v[180:183], v[212:215], v[98:101]
	v_mfma_f32_16x16x32_bf16 v[114:117], v[184:187], v[212:215], v[114:117]
	s_waitcnt lgkmcnt(2)
	v_mfma_f32_16x16x32_bf16 v[70:73], v[172:175], v[216:219], v[70:73]
	v_mfma_f32_16x16x32_bf16 v[86:89], v[176:179], v[216:219], v[86:89]
	v_mfma_f32_16x16x32_bf16 v[102:105], v[180:183], v[216:219], v[102:105]
	v_mfma_f32_16x16x32_bf16 v[118:121], v[184:187], v[216:219], v[118:121]
	s_waitcnt lgkmcnt(1)
	v_mfma_f32_16x16x32_bf16 v[74:77], v[172:175], v[220:223], v[74:77]
	v_mfma_f32_16x16x32_bf16 v[90:93], v[176:179], v[220:223], v[90:93]
	v_mfma_f32_16x16x32_bf16 v[106:109], v[180:183], v[220:223], v[106:109]
	v_mfma_f32_16x16x32_bf16 v[122:125], v[184:187], v[220:223], v[122:125]
	s_waitcnt lgkmcnt(0)
	v_mfma_f32_16x16x32_bf16 v[78:81], v[172:175], v[224:227], v[78:81]
	v_mfma_f32_16x16x32_bf16 v[94:97], v[176:179], v[224:227], v[94:97]
	v_mfma_f32_16x16x32_bf16 v[110:113], v[180:183], v[224:227], v[110:113]
	v_mfma_f32_16x16x32_bf16 v[126:129], v[184:187], v[224:227], v[126:129]
	s_setprio 0
	v_add_u32_e32 v228, 0x80, v228
	v_add_u32_e32 v229, 0x80, v229
	v_add_u32_e32 v230, 0x80, v230
	v_add_u32_e32 v231, 0x80, v231
	s_waitcnt vmcnt(4)
	s_barrier
	s_add_i32 s52, s52, 1
	s_cmp_lt_u32 s52, 10
	s_cbranch_scc1 .Lin2_loop
	s_setprio 3
	v_add_u32_e32 v234, s22, v232
	v_add_u32_e32 v236, s28, v232
	v_add_u32_e32 v235, s22, v233
	v_add_u32_e32 v237, s28, v233
	ds_read_b128 v[136:139], v234
	ds_read_b128 v[188:191], v236
	ds_read_b128 v[196:199], v236 offset:2048
	ds_read_b128 v[200:203], v236 offset:4096
	ds_read_b128 v[204:207], v236 offset:6144
	ds_read_b128 v[140:143], v234 offset:2048
	ds_read_b128 v[144:147], v234 offset:4096
	ds_read_b128 v[148:151], v234 offset:6144
	ds_read_b128 v[172:175], v235
	ds_read_b128 v[212:215], v237
	ds_read_b128 v[216:219], v237 offset:2048
	ds_read_b128 v[220:223], v237 offset:4096
	ds_read_b128 v[224:227], v237 offset:6144
	ds_read_b128 v[176:179], v235 offset:2048
	ds_read_b128 v[180:183], v235 offset:4096
	ds_read_b128 v[184:187], v235 offset:6144
	s_add_i32 m0, s51, 0xc000
	s_nop 0
	global_load_lds_dwordx4 v228, s[44:45]
	s_add_i32 m0, s51, 0xc400
	s_nop 0
	global_load_lds_dwordx4 v230, s[44:45]
	s_add_i32 m0, s51, 0xe000
	s_nop 0
	global_load_lds_dwordx4 v229, s[44:45]
	s_add_i32 m0, s51, 0xe400
	s_nop 0
	global_load_lds_dwordx4 v231, s[44:45]
	s_add_i32 m0, s51, 0x10000
	s_nop 0
	global_load_lds_dwordx4 v228, s[46:47]
	s_add_i32 m0, s51, 0x10400
	s_nop 0
	global_load_lds_dwordx4 v230, s[46:47]
	s_waitcnt lgkmcnt(11)
	s_setprio 1
	v_mfma_f32_16x16x32_bf16 v[2:5], v[136:139], v[188:191], v[2:5]
	v_mfma_f32_16x16x32_bf16 v[6:9], v[136:139], v[196:199], v[6:9]
	v_mfma_f32_16x16x32_bf16 v[10:13], v[136:139], v[200:203], v[10:13]
	v_mfma_f32_16x16x32_bf16 v[14:17], v[136:139], v[204:207], v[14:17]
	s_waitcnt lgkmcnt(10)
	v_mfma_f32_16x16x32_bf16 v[18:21], v[140:143], v[188:191], v[18:21]
	v_mfma_f32_16x16x32_bf16 v[22:25], v[140:143], v[196:199], v[22:25]
	v_mfma_f32_16x16x32_bf16 v[26:29], v[140:143], v[200:203], v[26:29]
	v_mfma_f32_16x16x32_bf16 v[30:33], v[140:143], v[204:207], v[30:33]
	s_waitcnt lgkmcnt(9)
	v_mfma_f32_16x16x32_bf16 v[34:37], v[144:147], v[188:191], v[34:37]
	v_mfma_f32_16x16x32_bf16 v[38:41], v[144:147], v[196:199], v[38:41]
	v_mfma_f32_16x16x32_bf16 v[42:45], v[144:147], v[200:203], v[42:45]
	v_mfma_f32_16x16x32_bf16 v[46:49], v[144:147], v[204:207], v[46:49]
	s_waitcnt lgkmcnt(8)
	v_mfma_f32_16x16x32_bf16 v[50:53], v[148:151], v[188:191], v[50:53]
	v_mfma_f32_16x16x32_bf16 v[54:57], v[148:151], v[196:199], v[54:57]
	v_mfma_f32_16x16x32_bf16 v[58:61], v[148:151], v[200:203], v[58:61]
	v_mfma_f32_16x16x32_bf16 v[62:65], v[148:151], v[204:207], v[62:65]
	s_waitcnt lgkmcnt(3)
	v_mfma_f32_16x16x32_bf16 v[2:5], v[172:175], v[212:215], v[2:5]
	v_mfma_f32_16x16x32_bf16 v[6:9], v[172:175], v[216:219], v[6:9]
	v_mfma_f32_16x16x32_bf16 v[10:13], v[172:175], v[220:223], v[10:13]
	v_mfma_f32_16x16x32_bf16 v[14:17], v[172:175], v[224:227], v[14:17]
	s_waitcnt lgkmcnt(2)
	v_mfma_f32_16x16x32_bf16 v[18:21], v[176:179], v[212:215], v[18:21]
	v_mfma_f32_16x16x32_bf16 v[22:25], v[176:179], v[216:219], v[22:25]
	v_mfma_f32_16x16x32_bf16 v[26:29], v[176:179], v[220:223], v[26:29]
	v_mfma_f32_16x16x32_bf16 v[30:33], v[176:179], v[224:227], v[30:33]
	s_waitcnt lgkmcnt(1)
	v_mfma_f32_16x16x32_bf16 v[34:37], v[180:183], v[212:215], v[34:37]
	v_mfma_f32_16x16x32_bf16 v[38:41], v[180:183], v[216:219], v[38:41]
	v_mfma_f32_16x16x32_bf16 v[42:45], v[180:183], v[220:223], v[42:45]
	v_mfma_f32_16x16x32_bf16 v[46:49], v[180:183], v[224:227], v[46:49]
	s_waitcnt lgkmcnt(0)
	v_mfma_f32_16x16x32_bf16 v[50:53], v[184:187], v[212:215], v[50:53]
	v_mfma_f32_16x16x32_bf16 v[54:57], v[184:187], v[216:219], v[54:57]
	v_mfma_f32_16x16x32_bf16 v[58:61], v[184:187], v[220:223], v[58:61]
	v_mfma_f32_16x16x32_bf16 v[62:65], v[184:187], v[224:227], v[62:65]
	s_setprio 0
	s_waitcnt vmcnt(6)
	s_barrier
	s_setprio 3
	v_add_u32_e32 v236, s40, v232
	v_add_u32_e32 v237, s40, v233
	ds_read_b128 v[188:191], v236
	ds_read_b128 v[196:199], v236 offset:2048
	ds_read_b128 v[200:203], v236 offset:4096
	ds_read_b128 v[204:207], v236 offset:6144
	ds_read_b128 v[212:215], v237
	ds_read_b128 v[216:219], v237 offset:2048
	ds_read_b128 v[220:223], v237 offset:4096
	ds_read_b128 v[224:227], v237 offset:6144
	s_mov_b32 m0, s51
	s_nop 0
	global_load_lds_dwordx4 v229, s[46:47]
	s_add_i32 m0, s51, 0x400
	s_nop 0
	global_load_lds_dwordx4 v231, s[46:47]
	s_add_i32 m0, s51, 0x2000
	s_nop 0
	global_load_lds_dwordx4 v228, s[48:49]
	s_add_i32 m0, s51, 0x2400
	s_nop 0
	global_load_lds_dwordx4 v230, s[48:49]
	s_add_i32 m0, s51, 0x4000
	s_nop 0
	global_load_lds_dwordx4 v229, s[48:49]
	s_add_i32 m0, s51, 0x4400
	s_nop 0
	global_load_lds_dwordx4 v231, s[48:49]
	s_waitcnt lgkmcnt(7)
	s_setprio 1
	v_mfma_f32_16x16x32_bf16 v[66:69], v[136:139], v[188:191], v[66:69]
	v_mfma_f32_16x16x32_bf16 v[82:85], v[140:143], v[188:191], v[82:85]
	v_mfma_f32_16x16x32_bf16 v[98:101], v[144:147], v[188:191], v[98:101]
	v_mfma_f32_16x16x32_bf16 v[114:117], v[148:151], v[188:191], v[114:117]
	s_waitcnt lgkmcnt(6)
	v_mfma_f32_16x16x32_bf16 v[70:73], v[136:139], v[196:199], v[70:73]
	v_mfma_f32_16x16x32_bf16 v[86:89], v[140:143], v[196:199], v[86:89]
	v_mfma_f32_16x16x32_bf16 v[102:105], v[144:147], v[196:199], v[102:105]
	v_mfma_f32_16x16x32_bf16 v[118:121], v[148:151], v[196:199], v[118:121]
	s_waitcnt lgkmcnt(5)
	v_mfma_f32_16x16x32_bf16 v[74:77], v[136:139], v[200:203], v[74:77]
	v_mfma_f32_16x16x32_bf16 v[90:93], v[140:143], v[200:203], v[90:93]
	v_mfma_f32_16x16x32_bf16 v[106:109], v[144:147], v[200:203], v[106:109]
	v_mfma_f32_16x16x32_bf16 v[122:125], v[148:151], v[200:203], v[122:125]
	s_waitcnt lgkmcnt(4)
	v_mfma_f32_16x16x32_bf16 v[78:81], v[136:139], v[204:207], v[78:81]
	v_mfma_f32_16x16x32_bf16 v[94:97], v[140:143], v[204:207], v[94:97]
	v_mfma_f32_16x16x32_bf16 v[110:113], v[144:147], v[204:207], v[110:113]
	v_mfma_f32_16x16x32_bf16 v[126:129], v[148:151], v[204:207], v[126:129]
	s_waitcnt lgkmcnt(3)
	v_mfma_f32_16x16x32_bf16 v[66:69], v[172:175], v[212:215], v[66:69]
	v_mfma_f32_16x16x32_bf16 v[82:85], v[176:179], v[212:215], v[82:85]
	v_mfma_f32_16x16x32_bf16 v[98:101], v[180:183], v[212:215], v[98:101]
	v_mfma_f32_16x16x32_bf16 v[114:117], v[184:187], v[212:215], v[114:117]
	s_waitcnt lgkmcnt(2)
	v_mfma_f32_16x16x32_bf16 v[70:73], v[172:175], v[216:219], v[70:73]
	v_mfma_f32_16x16x32_bf16 v[86:89], v[176:179], v[216:219], v[86:89]
	v_mfma_f32_16x16x32_bf16 v[102:105], v[180:183], v[216:219], v[102:105]
	v_mfma_f32_16x16x32_bf16 v[118:121], v[184:187], v[216:219], v[118:121]
	s_waitcnt lgkmcnt(1)
	v_mfma_f32_16x16x32_bf16 v[74:77], v[172:175], v[220:223], v[74:77]
	v_mfma_f32_16x16x32_bf16 v[90:93], v[176:179], v[220:223], v[90:93]
	v_mfma_f32_16x16x32_bf16 v[106:109], v[180:183], v[220:223], v[106:109]
	v_mfma_f32_16x16x32_bf16 v[122:125], v[184:187], v[220:223], v[122:125]
	s_waitcnt lgkmcnt(0)
	v_mfma_f32_16x16x32_bf16 v[78:81], v[172:175], v[224:227], v[78:81]
	v_mfma_f32_16x16x32_bf16 v[94:97], v[176:179], v[224:227], v[94:97]
	v_mfma_f32_16x16x32_bf16 v[110:113], v[180:183], v[224:227], v[110:113]
	v_mfma_f32_16x16x32_bf16 v[126:129], v[184:187], v[224:227], v[126:129]
	s_setprio 0
	v_add_u32_e32 v228, 0x80, v228
	v_add_u32_e32 v229, 0x80, v229
	v_add_u32_e32 v230, 0x80, v230
	v_add_u32_e32 v231, 0x80, v231
	s_waitcnt vmcnt(4)
	s_barrier
	s_setprio 3
	v_add_u32_e32 v234, s23, v232
	v_add_u32_e32 v236, s29, v232
	v_add_u32_e32 v235, s23, v233
	v_add_u32_e32 v237, s29, v233
	ds_read_b128 v[136:139], v234
	ds_read_b128 v[188:191], v236
	ds_read_b128 v[196:199], v236 offset:2048
	ds_read_b128 v[200:203], v236 offset:4096
	ds_read_b128 v[204:207], v236 offset:6144
	ds_read_b128 v[140:143], v234 offset:2048
	ds_read_b128 v[144:147], v234 offset:4096
	ds_read_b128 v[148:151], v234 offset:6144
	ds_read_b128 v[172:175], v235
	ds_read_b128 v[212:215], v237
	ds_read_b128 v[216:219], v237 offset:2048
	ds_read_b128 v[220:223], v237 offset:4096
	ds_read_b128 v[224:227], v237 offset:6144
	ds_read_b128 v[176:179], v235 offset:2048
	ds_read_b128 v[180:183], v235 offset:4096
	ds_read_b128 v[184:187], v235 offset:6144
	s_waitcnt lgkmcnt(11)
	s_setprio 1
	v_mfma_f32_16x16x32_bf16 v[2:5], v[136:139], v[188:191], v[2:5]
	v_mfma_f32_16x16x32_bf16 v[6:9], v[136:139], v[196:199], v[6:9]
	v_mfma_f32_16x16x32_bf16 v[10:13], v[136:139], v[200:203], v[10:13]
	v_mfma_f32_16x16x32_bf16 v[14:17], v[136:139], v[204:207], v[14:17]
	s_waitcnt lgkmcnt(10)
	v_mfma_f32_16x16x32_bf16 v[18:21], v[140:143], v[188:191], v[18:21]
	v_mfma_f32_16x16x32_bf16 v[22:25], v[140:143], v[196:199], v[22:25]
	v_mfma_f32_16x16x32_bf16 v[26:29], v[140:143], v[200:203], v[26:29]
	v_mfma_f32_16x16x32_bf16 v[30:33], v[140:143], v[204:207], v[30:33]
	s_waitcnt lgkmcnt(9)
	v_mfma_f32_16x16x32_bf16 v[34:37], v[144:147], v[188:191], v[34:37]
	v_mfma_f32_16x16x32_bf16 v[38:41], v[144:147], v[196:199], v[38:41]
	v_mfma_f32_16x16x32_bf16 v[42:45], v[144:147], v[200:203], v[42:45]
	v_mfma_f32_16x16x32_bf16 v[46:49], v[144:147], v[204:207], v[46:49]
	s_waitcnt lgkmcnt(8)
	v_mfma_f32_16x16x32_bf16 v[50:53], v[148:151], v[188:191], v[50:53]
	v_mfma_f32_16x16x32_bf16 v[54:57], v[148:151], v[196:199], v[54:57]
	v_mfma_f32_16x16x32_bf16 v[58:61], v[148:151], v[200:203], v[58:61]
	v_mfma_f32_16x16x32_bf16 v[62:65], v[148:151], v[204:207], v[62:65]
	s_waitcnt lgkmcnt(3)
	v_mfma_f32_16x16x32_bf16 v[2:5], v[172:175], v[212:215], v[2:5]
	v_mfma_f32_16x16x32_bf16 v[6:9], v[172:175], v[216:219], v[6:9]
	v_mfma_f32_16x16x32_bf16 v[10:13], v[172:175], v[220:223], v[10:13]
	v_mfma_f32_16x16x32_bf16 v[14:17], v[172:175], v[224:227], v[14:17]
	s_waitcnt lgkmcnt(2)
	v_mfma_f32_16x16x32_bf16 v[18:21], v[176:179], v[212:215], v[18:21]
	v_mfma_f32_16x16x32_bf16 v[22:25], v[176:179], v[216:219], v[22:25]
	v_mfma_f32_16x16x32_bf16 v[26:29], v[176:179], v[220:223], v[26:29]
	v_mfma_f32_16x16x32_bf16 v[30:33], v[176:179], v[224:227], v[30:33]
	s_waitcnt lgkmcnt(1)
	v_mfma_f32_16x16x32_bf16 v[34:37], v[180:183], v[212:215], v[34:37]
	v_mfma_f32_16x16x32_bf16 v[38:41], v[180:183], v[216:219], v[38:41]
	v_mfma_f32_16x16x32_bf16 v[42:45], v[180:183], v[220:223], v[42:45]
	v_mfma_f32_16x16x32_bf16 v[46:49], v[180:183], v[224:227], v[46:49]
	s_waitcnt lgkmcnt(0)
	v_mfma_f32_16x16x32_bf16 v[50:53], v[184:187], v[212:215], v[50:53]
	v_mfma_f32_16x16x32_bf16 v[54:57], v[184:187], v[216:219], v[54:57]
	v_mfma_f32_16x16x32_bf16 v[58:61], v[184:187], v[220:223], v[58:61]
	v_mfma_f32_16x16x32_bf16 v[62:65], v[184:187], v[224:227], v[62:65]
	s_setprio 0
	s_waitcnt vmcnt(0)
	s_barrier
	s_setprio 3
	v_add_u32_e32 v236, s41, v232
	v_add_u32_e32 v237, s41, v233
	ds_read_b128 v[188:191], v236
	ds_read_b128 v[196:199], v236 offset:2048
	ds_read_b128 v[200:203], v236 offset:4096
	ds_read_b128 v[204:207], v236 offset:6144
	ds_read_b128 v[212:215], v237
	ds_read_b128 v[216:219], v237 offset:2048
	ds_read_b128 v[220:223], v237 offset:4096
	ds_read_b128 v[224:227], v237 offset:6144
	s_waitcnt lgkmcnt(7)
	s_setprio 1
	v_mfma_f32_16x16x32_bf16 v[66:69], v[136:139], v[188:191], v[66:69]
	v_mfma_f32_16x16x32_bf16 v[82:85], v[140:143], v[188:191], v[82:85]
	v_mfma_f32_16x16x32_bf16 v[98:101], v[144:147], v[188:191], v[98:101]
	v_mfma_f32_16x16x32_bf16 v[114:117], v[148:151], v[188:191], v[114:117]
	s_waitcnt lgkmcnt(6)
	v_mfma_f32_16x16x32_bf16 v[70:73], v[136:139], v[196:199], v[70:73]
	v_mfma_f32_16x16x32_bf16 v[86:89], v[140:143], v[196:199], v[86:89]
	v_mfma_f32_16x16x32_bf16 v[102:105], v[144:147], v[196:199], v[102:105]
	v_mfma_f32_16x16x32_bf16 v[118:121], v[148:151], v[196:199], v[118:121]
	s_waitcnt lgkmcnt(5)
	v_mfma_f32_16x16x32_bf16 v[74:77], v[136:139], v[200:203], v[74:77]
	v_mfma_f32_16x16x32_bf16 v[90:93], v[140:143], v[200:203], v[90:93]
	v_mfma_f32_16x16x32_bf16 v[106:109], v[144:147], v[200:203], v[106:109]
	v_mfma_f32_16x16x32_bf16 v[122:125], v[148:151], v[200:203], v[122:125]
	s_waitcnt lgkmcnt(4)
	v_mfma_f32_16x16x32_bf16 v[78:81], v[136:139], v[204:207], v[78:81]
	v_mfma_f32_16x16x32_bf16 v[94:97], v[140:143], v[204:207], v[94:97]
	v_mfma_f32_16x16x32_bf16 v[110:113], v[144:147], v[204:207], v[110:113]
	v_mfma_f32_16x16x32_bf16 v[126:129], v[148:151], v[204:207], v[126:129]
	s_waitcnt lgkmcnt(3)
	v_mfma_f32_16x16x32_bf16 v[66:69], v[172:175], v[212:215], v[66:69]
	v_mfma_f32_16x16x32_bf16 v[82:85], v[176:179], v[212:215], v[82:85]
	v_mfma_f32_16x16x32_bf16 v[98:101], v[180:183], v[212:215], v[98:101]
	v_mfma_f32_16x16x32_bf16 v[114:117], v[184:187], v[212:215], v[114:117]
	s_waitcnt lgkmcnt(2)
	v_mfma_f32_16x16x32_bf16 v[70:73], v[172:175], v[216:219], v[70:73]
	v_mfma_f32_16x16x32_bf16 v[86:89], v[176:179], v[216:219], v[86:89]
	v_mfma_f32_16x16x32_bf16 v[102:105], v[180:183], v[216:219], v[102:105]
	v_mfma_f32_16x16x32_bf16 v[118:121], v[184:187], v[216:219], v[118:121]
	s_waitcnt lgkmcnt(1)
	v_mfma_f32_16x16x32_bf16 v[74:77], v[172:175], v[220:223], v[74:77]
	v_mfma_f32_16x16x32_bf16 v[90:93], v[176:179], v[220:223], v[90:93]
	v_mfma_f32_16x16x32_bf16 v[106:109], v[180:183], v[220:223], v[106:109]
	v_mfma_f32_16x16x32_bf16 v[122:125], v[184:187], v[220:223], v[122:125]
	s_waitcnt lgkmcnt(0)
	v_mfma_f32_16x16x32_bf16 v[78:81], v[172:175], v[224:227], v[78:81]
	v_mfma_f32_16x16x32_bf16 v[94:97], v[176:179], v[224:227], v[94:97]
	v_mfma_f32_16x16x32_bf16 v[110:113], v[180:183], v[224:227], v[110:113]
	v_mfma_f32_16x16x32_bf16 v[126:129], v[184:187], v[224:227], v[126:129]
	s_setprio 0
	s_nop 7
	s_barrier
	s_setprio 2
	v_and_b32_e32 v241, 63, v131
	v_and_b32_e32 v242, 15, v241
	v_lshrrev_b32_e32 v243, 4, v241
	s_lshr_b32 s56, s50, 1
	s_and_b32 s57, s50, 1
	s_mul_i32 s0, s56, 64*272
	s_lshl_b32 s52, s57, 7
	s_add_i32 s0, s0, s52
	s_add_i32 s0, s0, 16
	v_mul_u32_u24_e32 v244, 1088, v243
	v_lshl_add_u32 v244, v242, 1, v244
	v_add_u32_e32 v229, s0, v244
	s_mul_i32 s0, s57, 64*272
	s_lshl_b32 s52, s56, 7
	s_add_i32 s0, s0, s52
	s_add_i32 s0, s0, 16
	v_mul_u32_u24_e32 v244, 272, v242
	v_lshl_add_u32 v244, v243, 3, v244
	v_add_u32_e32 v230, s0, v244
	s_lshl_b32 s0, s57, 9
	s_lshl_b32 s52, s56, 8
	s_add_i32 s0, s0, s52
	s_add_i32 s0, s0, 16+34816
	v_lshl_add_u32 v228, v243, 4, s0
	s_lshl_b32 s0, s57, 8
	v_lshl_add_u32 v234, v242, 2, s0
	v_lshrrev_b32_e32 v241, 4, v131
	v_and_b32_e32 v242, 15, v131
	v_lshlrev_b32_e32 v242, 4, v242
	v_mul_u32_u24_e32 v243, 272, v241
	v_add3_u32 v231, v243, v242, 16
	s_movk_i32 s0, 0x2500
	v_mad_u32_u24 v232, v241, s0, v242
	v_lshl_add_u32 v233, v241, 12, v242
	s_lshr_b32 s52, s54, 7
	s_mov_b32 s57, 0
	s_movk_i32 s56, 0x170
	s_cmp_lt_u32 s52, 8
	s_cbranch_scc0 .Lin2_t1_v1
	s_mov_b32 s57, 1
	s_movk_i32 s56, 0x28
	s_branch .Lin2_t1_vd

.Lin2_done:
	s_setprio 0
	s_add_i32 s21, s60, 0x800
	s_mov_b32 s20, s21
	v_readlane_b32 s8, v209, 21
	s_addk_i32 s8, 0x800
	s_cmpk_gt_i32 s21, 0x9bf
	s_cbranch_scc1 .LBB0_361
	s_branch .LBB0_367
